# on top of v29: all s_setprio flips removed from the GEMM mainloops (the loader no longer issues VALU, so MFMA issue needs no priority help)
# speedup vs baseline: 1.0080x; 1.0017x over previous
; #define PG8_STAGE(bufoff, gbase) do { _Pragma("unroll") for (int _i = 0; _i < 2; ++_i) \
;         __builtin_amdgcn_global_load_lds((const unsigned*)((const char*)(gbase) + voff[_i]), (LAS unsigned*)(lds + (bufoff) + ldsw + _i * 8192), 16, 0, 0); } while (0)
; #define PG8_LDA(dst, b, h) do { _Pragma("unroll") for (int m = 0; m < 4; ++m) _Pragma("unroll") for (int k = 0; k < 2; ++k) dst[m][k] = *(const LAS bf16x8*)(lds + PG8_SA(b, h) + aoff + m * 2048 + k * 1024); } while (0)
; #define PG8_LDB(dst, b, h) do { _Pragma("unroll") for (int n = 0; n < 2; ++n) _Pragma("unroll") for (int k = 0; k < 2; ++k) dst[n][k] = *(const LAS bf16x8*)(lds + PG8_SB(b, h) + boff + n * 2048 + k * 1024); } while (0)
; #define PG8_MMA(ai, bj, At, Bt) do { __builtin_amdgcn_s_setprio(1); _Pragma("unroll") for (int m = 0; m < 4; ++m) _Pragma("unroll") for (int n = 0; n < 2; ++n) _Pragma("unroll") for (int k = 0; k < 2; ++k) \
;         acc[ai][bj][m][n] = __builtin_amdgcn_mfma_f32_16x16x32_bf16(Bt[n][k], At[m][k], acc[ai][bj][m][n], 0, 0, 0); __builtin_amdgcn_s_setprio(0); } while (0)
; #define PG8_WAIT_V(n) asm volatile("s_waitcnt vmcnt(" #n ")" ::: "memory")
; #define PG8_WAIT_L(n) asm volatile("s_waitcnt lgkmcnt(" #n ")" ::: "memory")
; #define PG8_BAR __builtin_amdgcn_s_barrier()
; #define PG8_SCHED __builtin_amdgcn_sched_barrier(0)
; template <class Epi>
; DI void gemm_phase(LAS unsigned char* lds, const Gemm g, const StaticOrder& S, const Epi& E) {
;     ...
;         for (int t = 0; t < nt; t += 2) {
;             const bool last = (t == nt - 2);
;             const char* a1 = cA + (size_t)(t + 1) * kstep;
;             const char* a2 = last ? nA : cA + (size_t)(t + 2) * kstep; const char* b2 = last ? nB : cB + (size_t)(t + 2) * kstep;
;             const char* a3 = a2 + kstep; const char* b3 = b2 + kstep;
;             PG8_LDB(B0, 0, 0); PG8_SCHED; PG8_LDA(At, 0, 0); PG8_STAGE(PG8_SA(1, 1), a1 + hstep);
;             PG8_WAIT_L(8); PG8_BAR; PG8_WAIT_L(0); PG8_MMA(0, 0, At, B0); PG8_BAR; PG8_SCHED;
;             PG8_LDB(B1, 0, 1); PG8_STAGE(PG8_SB(0, 0), b2);
;             PG8_BAR; PG8_WAIT_L(0); PG8_MMA(0, 1, At, B1); PG8_BAR;
;             PG8_LDA(At, 0, 1); PG8_STAGE(PG8_SA(0, 0), a2);
;             PG8_BAR; PG8_WAIT_L(0); PG8_MMA(1, 0, At, B0); PG8_BAR; PG8_SCHED;
;             PG8_STAGE(PG8_SB(0, 1), b2 + hstep);
;             PG8_WAIT_V(6); PG8_BAR; PG8_MMA(1, 1, At, B1); PG8_BAR;
.LBB0_37:
	ds_read_b128 v[138:141], v135
	ds_read_b128 v[142:145], v135 offset:1024
	ds_read_b128 v[146:149], v135 offset:2048
	ds_read_b128 v[150:153], v135 offset:3072
	ds_read_b128 v[186:189], v137
	ds_read_b128 v[190:193], v137 offset:1024
	ds_read_b128 v[194:197], v137 offset:2048
	ds_read_b128 v[198:201], v137 offset:3072
	ds_read_b128 v[202:205], v137 offset:4096
	ds_read_b128 v[206:209], v137 offset:5120
	ds_read_b128 v[210:213], v137 offset:6144
	ds_read_b128 v[214:217], v137 offset:7168
	s_add_u32 s20, s18, 0xfff80080
	s_addc_u32 s21, s19, -1
	s_add_i32 s39, 0, 0x10000
	s_cmp_eq_u32 s38, 28
	s_cselect_b32 s23, s4, s21
	s_cselect_b32 s22, s5, s20
	s_cselect_b32 s21, s9, s37
	s_cselect_b32 s20, s11, s33
	s_add_i32 m0, s28, 0xc000
	s_nop 0
	global_load_lds_dwordx4 v130, s[18:19]
	s_add_i32 m0, s28, 0xe000
	s_nop 0
	global_load_lds_dwordx4 v132, s[18:19]
	s_waitcnt lgkmcnt(8)
	s_barrier
	s_waitcnt lgkmcnt(0)
	v_mfma_f32_16x16x32_bf16 v[124:127], v[138:141], v[186:189], v[124:127]
	v_mfma_f32_16x16x32_bf16 v[120:123], v[146:149], v[186:189], v[120:123]
	v_mfma_f32_16x16x32_bf16 v[108:111], v[138:141], v[194:197], v[108:111]
	v_mfma_f32_16x16x32_bf16 v[104:107], v[146:149], v[194:197], v[104:107]
	v_mfma_f32_16x16x32_bf16 v[92:95], v[138:141], v[202:205], v[92:95]
	v_mfma_f32_16x16x32_bf16 v[88:91], v[146:149], v[202:205], v[88:91]
	v_mfma_f32_16x16x32_bf16 v[76:79], v[138:141], v[210:213], v[76:79]
	v_mfma_f32_16x16x32_bf16 v[72:75], v[146:149], v[210:213], v[72:75]
	v_mfma_f32_16x16x32_bf16 v[124:127], v[142:145], v[190:193], v[124:127]
	v_mfma_f32_16x16x32_bf16 v[120:123], v[150:153], v[190:193], v[120:123]
	v_mfma_f32_16x16x32_bf16 v[108:111], v[142:145], v[198:201], v[108:111]
	v_mfma_f32_16x16x32_bf16 v[104:107], v[150:153], v[198:201], v[104:107]
	v_mfma_f32_16x16x32_bf16 v[92:95], v[142:145], v[206:209], v[92:95]
	v_mfma_f32_16x16x32_bf16 v[88:91], v[150:153], v[206:209], v[88:91]
	v_mfma_f32_16x16x32_bf16 v[76:79], v[142:145], v[214:217], v[76:79]
	v_mfma_f32_16x16x32_bf16 v[72:75], v[150:153], v[214:217], v[72:75]
	s_barrier
	ds_read_b128 v[226:229], v135 offset:16384
	ds_read_b128 v[230:233], v135 offset:17408
	ds_read_b128 v[234:237], v135 offset:18432
	ds_read_b128 v[238:241], v135 offset:19456
	s_add_i32 s42, 0, 0x14000
	s_add_i32 s39, s39, s27
	s_mov_b32 m0, s39
	s_nop 0
	global_load_lds_dwordx4 v158, s[20:21]
	s_add_i32 m0, s39, 0x2000
	s_nop 0
	global_load_lds_dwordx4 v128, s[20:21]
	s_waitcnt lgkmcnt(0)
	s_barrier
	v_mfma_f32_16x16x32_bf16 v[116:119], v[226:229], v[186:189], v[116:119]
	v_mfma_f32_16x16x32_bf16 v[112:115], v[234:237], v[186:189], v[112:115]
	v_mfma_f32_16x16x32_bf16 v[100:103], v[226:229], v[194:197], v[100:103]
	v_mfma_f32_16x16x32_bf16 v[96:99], v[234:237], v[194:197], v[96:99]
	v_mfma_f32_16x16x32_bf16 v[84:87], v[226:229], v[202:205], v[84:87]
	v_mfma_f32_16x16x32_bf16 v[80:83], v[234:237], v[202:205], v[80:83]
	v_mfma_f32_16x16x32_bf16 v[68:71], v[226:229], v[210:213], v[68:71]
	v_mfma_f32_16x16x32_bf16 v[64:67], v[234:237], v[210:213], v[64:67]
	v_mfma_f32_16x16x32_bf16 v[116:119], v[230:233], v[190:193], v[116:119]
	s_mov_b32 m0, s28
	v_mfma_f32_16x16x32_bf16 v[112:115], v[238:241], v[190:193], v[112:115]
	s_mov_b64 s[100:101], s[22:23]
	v_mfma_f32_16x16x32_bf16 v[100:103], v[230:233], v[198:201], v[100:103]
	v_mfma_f32_16x16x32_bf16 v[96:99], v[238:241], v[198:201], v[96:99]
	v_mfma_f32_16x16x32_bf16 v[84:87], v[230:233], v[206:209], v[84:87]
	v_mfma_f32_16x16x32_bf16 v[80:83], v[238:241], v[206:209], v[80:83]
	v_mfma_f32_16x16x32_bf16 v[68:71], v[230:233], v[214:217], v[68:71]
	v_mfma_f32_16x16x32_bf16 v[64:67], v[238:241], v[214:217], v[64:67]
	s_barrier
	ds_read_b128 v[186:189], v137 offset:16384
	ds_read_b128 v[190:193], v137 offset:17408
	ds_read_b128 v[194:197], v137 offset:18432
	ds_read_b128 v[198:201], v137 offset:19456
	ds_read_b128 v[202:205], v137 offset:20480
	ds_read_b128 v[206:209], v137 offset:21504
	ds_read_b128 v[210:213], v137 offset:22528
	ds_read_b128 v[214:217], v137 offset:23552
	global_load_lds_dwordx4 v158, s[22:23]
	s_mov_b64 s[100:101], s[22:23]
	s_mov_b32 m0, s29
	s_nop 0
	global_load_lds_dwordx4 v128, s[22:23]
	s_waitcnt lgkmcnt(0)
	s_barrier
	v_mfma_f32_16x16x32_bf16 v[60:63], v[138:141], v[186:189], v[60:63]
	v_mfma_f32_16x16x32_bf16 v[56:59], v[146:149], v[186:189], v[56:59]
	v_mfma_f32_16x16x32_bf16 v[44:47], v[138:141], v[194:197], v[44:47]
	v_mfma_f32_16x16x32_bf16 v[40:43], v[146:149], v[194:197], v[40:43]
	v_mfma_f32_16x16x32_bf16 v[28:31], v[138:141], v[202:205], v[28:31]
	v_mfma_f32_16x16x32_bf16 v[24:27], v[146:149], v[202:205], v[24:27]
	v_mfma_f32_16x16x32_bf16 v[12:15], v[138:141], v[210:213], v[12:15]
	v_mfma_f32_16x16x32_bf16 v[8:11], v[146:149], v[210:213], v[8:11]
	v_mfma_f32_16x16x32_bf16 v[60:63], v[142:145], v[190:193], v[60:63]
	v_mfma_f32_16x16x32_bf16 v[56:59], v[150:153], v[190:193], v[56:59]
	v_mfma_f32_16x16x32_bf16 v[44:47], v[142:145], v[198:201], v[44:47]
	v_mfma_f32_16x16x32_bf16 v[40:43], v[150:153], v[198:201], v[40:43]
	v_mfma_f32_16x16x32_bf16 v[28:31], v[142:145], v[206:209], v[28:31]
	v_mfma_f32_16x16x32_bf16 v[24:27], v[150:153], v[206:209], v[24:27]
	v_mfma_f32_16x16x32_bf16 v[12:15], v[142:145], v[214:217], v[12:15]
	v_mfma_f32_16x16x32_bf16 v[8:11], v[150:153], v[214:217], v[8:11]
	s_barrier
	s_add_u32 s40, s20, 0x80000
	s_addc_u32 s41, s21, 0
	s_add_i32 s39, s42, s27
	s_mov_b32 m0, s39
	s_nop 0
	global_load_lds_dwordx4 v158, s[40:41]
	s_add_i32 m0, s39, 0x2000
	s_nop 0
	global_load_lds_dwordx4 v128, s[40:41]
	s_waitcnt vmcnt(6)
	s_barrier
; #define PG8_STAGE(bufoff, gbase) do { _Pragma("unroll") for (int _i = 0; _i < 2; ++_i) \
;         __builtin_amdgcn_global_load_lds((const unsigned*)((const char*)(gbase) + voff[_i]), (LAS unsigned*)(lds + (bufoff) + ldsw + _i * 8192), 16, 0, 0); } while (0)
; #define PG8_LDA(dst, b, h) do { _Pragma("unroll") for (int m = 0; m < 4; ++m) _Pragma("unroll") for (int k = 0; k < 2; ++k) dst[m][k] = *(const LAS bf16x8*)(lds + PG8_SA(b, h) + aoff + m * 2048 + k * 1024); } while (0)
; #define PG8_LDB(dst, b, h) do { _Pragma("unroll") for (int n = 0; n < 2; ++n) _Pragma("unroll") for (int k = 0; k < 2; ++k) dst[n][k] = *(const LAS bf16x8*)(lds + PG8_SB(b, h) + boff + n * 2048 + k * 1024); } while (0)
; #define PG8_MMA(ai, bj, At, Bt) do { __builtin_amdgcn_s_setprio(1); _Pragma("unroll") for (int m = 0; m < 4; ++m) _Pragma("unroll") for (int n = 0; n < 2; ++n) _Pragma("unroll") for (int k = 0; k < 2; ++k) \
;         acc[ai][bj][m][n] = __builtin_amdgcn_mfma_f32_16x16x32_bf16(Bt[n][k], At[m][k], acc[ai][bj][m][n], 0, 0, 0); __builtin_amdgcn_s_setprio(0); } while (0)
; #define PG8_WAIT_V(n) asm volatile("s_waitcnt vmcnt(" #n ")" ::: "memory")
; #define PG8_WAIT_L(n) asm volatile("s_waitcnt lgkmcnt(" #n ")" ::: "memory")
; #define PG8_BAR __builtin_amdgcn_s_barrier()
; #define PG8_SCHED __builtin_amdgcn_sched_barrier(0)
; template <class Epi>
; DI void gemm_phase(LAS unsigned char* lds, const Gemm g, const StaticOrder& S, const Epi& E) {
;     ...
;             PG8_WAIT_V(6); PG8_BAR; PG8_MMA(1, 1, At, B1); PG8_BAR;
;             PG8_LDB(B0, 1, 0); PG8_SCHED; PG8_LDA(At, 1, 0); PG8_STAGE(PG8_SA(0, 1), a2 + hstep);
;             PG8_WAIT_L(8); PG8_BAR; PG8_WAIT_L(0); PG8_MMA(0, 0, At, B0); PG8_BAR; PG8_SCHED;
;             PG8_LDB(B1, 1, 1); PG8_STAGE(PG8_SB(1, 0), b3);
;             PG8_BAR; PG8_WAIT_L(0); PG8_MMA(0, 1, At, B1); PG8_BAR;
;             PG8_LDA(At, 1, 1); PG8_STAGE(PG8_SA(1, 0), a3);
;             PG8_BAR; PG8_WAIT_L(0); PG8_MMA(1, 0, At, B0); PG8_BAR; PG8_SCHED;
;             PG8_STAGE(PG8_SB(1, 1), b3 + hstep);
	v_mfma_f32_16x16x32_bf16 v[52:55], v[226:229], v[186:189], v[52:55]
	v_mfma_f32_16x16x32_bf16 v[48:51], v[234:237], v[186:189], v[48:51]
	v_mfma_f32_16x16x32_bf16 v[36:39], v[226:229], v[194:197], v[36:39]
	v_mfma_f32_16x16x32_bf16 v[32:35], v[234:237], v[194:197], v[32:35]
	v_mfma_f32_16x16x32_bf16 v[20:23], v[226:229], v[202:205], v[20:23]
	v_mfma_f32_16x16x32_bf16 v[16:19], v[234:237], v[202:205], v[16:19]
	v_mfma_f32_16x16x32_bf16 v[4:7], v[226:229], v[210:213], v[4:7]
	v_mfma_f32_16x16x32_bf16 v[0:3], v[234:237], v[210:213], v[0:3]
	v_mfma_f32_16x16x32_bf16 v[52:55], v[230:233], v[190:193], v[52:55]
	s_add_i32 s39, 0, 0x18000
	v_mfma_f32_16x16x32_bf16 v[48:51], v[238:241], v[190:193], v[48:51]
	v_mfma_f32_16x16x32_bf16 v[36:39], v[230:233], v[198:201], v[36:39]
	v_mfma_f32_16x16x32_bf16 v[32:35], v[238:241], v[198:201], v[32:35]
	v_mfma_f32_16x16x32_bf16 v[20:23], v[230:233], v[206:209], v[20:23]
	v_mfma_f32_16x16x32_bf16 v[16:19], v[238:241], v[206:209], v[16:19]
	v_mfma_f32_16x16x32_bf16 v[4:7], v[230:233], v[214:217], v[4:7]
	v_mfma_f32_16x16x32_bf16 v[0:3], v[238:241], v[214:217], v[0:3]
	s_barrier
	ds_read_b128 v[138:141], v135 offset:32768
	ds_read_b128 v[142:145], v135 offset:33792
	ds_read_b128 v[146:149], v135 offset:34816
	ds_read_b128 v[150:153], v135 offset:35840
	ds_read_b128 v[186:189], v137 offset:32768
	ds_read_b128 v[190:193], v137 offset:33792
	ds_read_b128 v[194:197], v137 offset:34816
	ds_read_b128 v[198:201], v137 offset:35840
	ds_read_b128 v[202:205], v137 offset:36864
	ds_read_b128 v[206:209], v137 offset:37888
	ds_read_b128 v[210:213], v137 offset:38912
	ds_read_b128 v[214:217], v137 offset:39936
	s_add_u32 s22, s22, 0x80000
	s_addc_u32 s23, s23, 0
	s_mov_b32 m0, s30
	s_nop 0
	global_load_lds_dwordx4 v158, s[22:23]
	s_mov_b32 m0, s31
	s_nop 0
	global_load_lds_dwordx4 v128, s[22:23]
	s_waitcnt lgkmcnt(8)
	s_barrier
	s_waitcnt lgkmcnt(0)
	v_mfma_f32_16x16x32_bf16 v[124:127], v[138:141], v[186:189], v[124:127]
	v_mfma_f32_16x16x32_bf16 v[120:123], v[146:149], v[186:189], v[120:123]
	v_mfma_f32_16x16x32_bf16 v[108:111], v[138:141], v[194:197], v[108:111]
	v_mfma_f32_16x16x32_bf16 v[104:107], v[146:149], v[194:197], v[104:107]
	v_mfma_f32_16x16x32_bf16 v[92:95], v[138:141], v[202:205], v[92:95]
	v_mfma_f32_16x16x32_bf16 v[88:91], v[146:149], v[202:205], v[88:91]
	v_mfma_f32_16x16x32_bf16 v[76:79], v[138:141], v[210:213], v[76:79]
	v_mfma_f32_16x16x32_bf16 v[72:75], v[146:149], v[210:213], v[72:75]
	v_mfma_f32_16x16x32_bf16 v[124:127], v[142:145], v[190:193], v[124:127]
	v_mfma_f32_16x16x32_bf16 v[120:123], v[150:153], v[190:193], v[120:123]
	v_mfma_f32_16x16x32_bf16 v[108:111], v[142:145], v[198:201], v[108:111]
	v_mfma_f32_16x16x32_bf16 v[104:107], v[150:153], v[198:201], v[104:107]
	v_mfma_f32_16x16x32_bf16 v[92:95], v[142:145], v[206:209], v[92:95]
	v_mfma_f32_16x16x32_bf16 v[88:91], v[150:153], v[206:209], v[88:91]
	v_mfma_f32_16x16x32_bf16 v[76:79], v[142:145], v[214:217], v[76:79]
	v_mfma_f32_16x16x32_bf16 v[72:75], v[150:153], v[214:217], v[72:75]
	s_barrier
	ds_read_b128 v[226:229], v135 offset:49152
	ds_read_b128 v[230:233], v135 offset:50176
	ds_read_b128 v[234:237], v135 offset:51200
	ds_read_b128 v[238:241], v135 offset:52224
	s_add_i32 s22, 0, 0x1c000
	s_add_i32 s23, s39, s27
	s_add_i32 m0, s23, 0xffffff80
	s_nop 0
	global_load_lds_dwordx4 v158, s[20:21] offset:128
	s_add_i32 m0, s23, 0x1f80
	s_nop 0
	global_load_lds_dwordx4 v128, s[20:21] offset:128
	s_waitcnt lgkmcnt(0)
	s_barrier
	v_mfma_f32_16x16x32_bf16 v[116:119], v[226:229], v[186:189], v[116:119]
	v_mfma_f32_16x16x32_bf16 v[112:115], v[234:237], v[186:189], v[112:115]
	v_mfma_f32_16x16x32_bf16 v[100:103], v[226:229], v[194:197], v[100:103]
	v_mfma_f32_16x16x32_bf16 v[96:99], v[234:237], v[194:197], v[96:99]
	v_mfma_f32_16x16x32_bf16 v[84:87], v[226:229], v[202:205], v[84:87]
	v_mfma_f32_16x16x32_bf16 v[80:83], v[234:237], v[202:205], v[80:83]
	v_mfma_f32_16x16x32_bf16 v[68:71], v[226:229], v[210:213], v[68:71]
	v_mfma_f32_16x16x32_bf16 v[64:67], v[234:237], v[210:213], v[64:67]
	v_mfma_f32_16x16x32_bf16 v[116:119], v[230:233], v[190:193], v[116:119]
	s_add_i32 m0, s34, 0xffffff80
	v_mfma_f32_16x16x32_bf16 v[112:115], v[238:241], v[190:193], v[112:115]
	v_mfma_f32_16x16x32_bf16 v[100:103], v[230:233], v[198:201], v[100:103]
	v_mfma_f32_16x16x32_bf16 v[96:99], v[238:241], v[198:201], v[96:99]
	v_mfma_f32_16x16x32_bf16 v[84:87], v[230:233], v[206:209], v[84:87]
	v_mfma_f32_16x16x32_bf16 v[80:83], v[238:241], v[206:209], v[80:83]
	v_mfma_f32_16x16x32_bf16 v[68:71], v[230:233], v[214:217], v[68:71]
	v_mfma_f32_16x16x32_bf16 v[64:67], v[238:241], v[214:217], v[64:67]
	s_barrier
	ds_read_b128 v[186:189], v137 offset:49152
	ds_read_b128 v[190:193], v137 offset:50176
	ds_read_b128 v[194:197], v137 offset:51200
	ds_read_b128 v[198:201], v137 offset:52224
	ds_read_b128 v[202:205], v137 offset:53248
	ds_read_b128 v[206:209], v137 offset:54272
	ds_read_b128 v[210:213], v137 offset:55296
	ds_read_b128 v[214:217], v137 offset:56320
	global_load_lds_dwordx4 v158, s[100:101] offset:128
	s_add_i32 m0, s35, 0xffffff80
	s_nop 0
	global_load_lds_dwordx4 v128, s[100:101] offset:128
	s_waitcnt lgkmcnt(0)
	s_barrier
; #define PG8_STAGE(bufoff, gbase) do { _Pragma("unroll") for (int _i = 0; _i < 2; ++_i) \
;         __builtin_amdgcn_global_load_lds((const unsigned*)((const char*)(gbase) + voff[_i]), (LAS unsigned*)(lds + (bufoff) + ldsw + _i * 8192), 16, 0, 0); } while (0)
; #define PG8_MMA(ai, bj, At, Bt) do { __builtin_amdgcn_s_setprio(1); _Pragma("unroll") for (int m = 0; m < 4; ++m) _Pragma("unroll") for (int n = 0; n < 2; ++n) _Pragma("unroll") for (int k = 0; k < 2; ++k) \
;         acc[ai][bj][m][n] = __builtin_amdgcn_mfma_f32_16x16x32_bf16(Bt[n][k], At[m][k], acc[ai][bj][m][n], 0, 0, 0); __builtin_amdgcn_s_setprio(0); } while (0)
; #define PG8_WAIT_V(n) asm volatile("s_waitcnt vmcnt(" #n ")" ::: "memory")
; #define PG8_WAIT_L(n) asm volatile("s_waitcnt lgkmcnt(" #n ")" ::: "memory")
; #define PG8_BAR __builtin_amdgcn_s_barrier()
; #define PG8_SCHED __builtin_amdgcn_sched_barrier(0)
; template <class Epi>
; DI void gemm_phase(LAS unsigned char* lds, const Gemm g, const StaticOrder& S, const Epi& E) {
;     ...
;             PG8_BAR; PG8_WAIT_L(0); PG8_MMA(1, 0, At, B0); PG8_BAR; PG8_SCHED;
;             PG8_STAGE(PG8_SB(1, 1), b3 + hstep);
;             PG8_WAIT_V(6); PG8_BAR; PG8_MMA(1, 1, At, B1); PG8_BAR;
;     DI void operator()(const f32x4 (&acc)[2][2][4][2], const Unit& u, int wr, int wc, int fr, int fq) const {
;         const int row0 = u.pm * BM + wr * 64 + fr, col0 = u.pn * HALF + wc * 32 + 8 * fq;
; #pragma unroll
;         for (int ai = 0; ai < 2; ++ai)
; #pragma unroll
;             for (int m = 0; m < 4; ++m) { float hv[8];
; #pragma unroll
;                 for (int n = 0; n < 2; ++n)
; #pragma unroll
;                     for (int e = 0; e < 4; ++e) { const float gt = acc[ai][0][m][n][e], up = acc[ai][1][m][n][e];
;                         hv[n * 4 + e] = gt * __builtin_amdgcn_rcpf(1.f + __builtin_amdgcn_exp2f(-1.4426950408889634f * gt)) * up; }
;                 *(u32x4*)(H + (size_t)(row0 + ai * HALF + m * 16) * DFF + col0) = (u32x4){pk(hv[0], hv[1]), pk(hv[2], hv[3]), pk(hv[4], hv[5]), pk(hv[6], hv[7])}; }
	v_mfma_f32_16x16x32_bf16 v[60:63], v[138:141], v[186:189], v[60:63]
	v_mfma_f32_16x16x32_bf16 v[56:59], v[146:149], v[186:189], v[56:59]
	v_mfma_f32_16x16x32_bf16 v[44:47], v[138:141], v[194:197], v[44:47]
	v_mfma_f32_16x16x32_bf16 v[40:43], v[146:149], v[194:197], v[40:43]
	v_mfma_f32_16x16x32_bf16 v[28:31], v[138:141], v[202:205], v[28:31]
	v_mfma_f32_16x16x32_bf16 v[24:27], v[146:149], v[202:205], v[24:27]
	v_mfma_f32_16x16x32_bf16 v[12:15], v[138:141], v[210:213], v[12:15]
	v_mfma_f32_16x16x32_bf16 v[8:11], v[146:149], v[210:213], v[8:11]
	v_mfma_f32_16x16x32_bf16 v[60:63], v[142:145], v[190:193], v[60:63]
	v_mfma_f32_16x16x32_bf16 v[56:59], v[150:153], v[190:193], v[56:59]
	v_mfma_f32_16x16x32_bf16 v[44:47], v[142:145], v[198:201], v[44:47]
	v_mfma_f32_16x16x32_bf16 v[40:43], v[150:153], v[198:201], v[40:43]
	v_mfma_f32_16x16x32_bf16 v[28:31], v[142:145], v[206:209], v[28:31]
	v_mfma_f32_16x16x32_bf16 v[24:27], v[150:153], v[206:209], v[24:27]
	v_mfma_f32_16x16x32_bf16 v[12:15], v[142:145], v[214:217], v[12:15]
	v_mfma_f32_16x16x32_bf16 v[8:11], v[150:153], v[214:217], v[8:11]
	s_barrier
	s_add_u32 s20, s20, 0x80080
	s_addc_u32 s21, s21, 0
	s_add_i32 s22, s22, s27
	s_mov_b32 m0, s22
	s_nop 0
	global_load_lds_dwordx4 v158, s[20:21]
	s_add_i32 m0, s22, 0x2000
	s_nop 0
	global_load_lds_dwordx4 v128, s[20:21]
	s_waitcnt vmcnt(6)
	s_barrier
	v_mfma_f32_16x16x32_bf16 v[52:55], v[226:229], v[186:189], v[52:55]
	v_mfma_f32_16x16x32_bf16 v[48:51], v[234:237], v[186:189], v[48:51]
	v_mfma_f32_16x16x32_bf16 v[36:39], v[226:229], v[194:197], v[36:39]
	v_mfma_f32_16x16x32_bf16 v[32:35], v[234:237], v[194:197], v[32:35]
	v_mfma_f32_16x16x32_bf16 v[20:23], v[226:229], v[202:205], v[20:23]
	v_mfma_f32_16x16x32_bf16 v[16:19], v[234:237], v[202:205], v[16:19]
	v_mfma_f32_16x16x32_bf16 v[4:7], v[226:229], v[210:213], v[4:7]
	v_mfma_f32_16x16x32_bf16 v[0:3], v[234:237], v[210:213], v[0:3]
	v_mfma_f32_16x16x32_bf16 v[52:55], v[230:233], v[190:193], v[52:55]
	s_add_i32 s38, s38, 2
	v_mfma_f32_16x16x32_bf16 v[48:51], v[238:241], v[190:193], v[48:51]
	s_add_u32 s18, s18, 0x100
	v_mfma_f32_16x16x32_bf16 v[36:39], v[230:233], v[198:201], v[36:39]
	s_addc_u32 s19, s19, 0
	v_mfma_f32_16x16x32_bf16 v[32:35], v[238:241], v[198:201], v[32:35]
	s_add_u32 s33, s33, 0x100
	v_mfma_f32_16x16x32_bf16 v[20:23], v[230:233], v[206:209], v[20:23]
	s_addc_u32 s37, s37, 0
	v_mfma_f32_16x16x32_bf16 v[16:19], v[238:241], v[206:209], v[16:19]
	s_cmp_gt_u32 s38, 29
	v_mfma_f32_16x16x32_bf16 v[4:7], v[230:233], v[214:217], v[4:7]
	v_mfma_f32_16x16x32_bf16 v[0:3], v[238:241], v[214:217], v[0:3]
	s_barrier
	s_cbranch_scc0 .LBB0_37
	v_mul_f32_e32 v139, 0xbfb8aa3b, v124
	v_exp_f32_e32 v139, v139
	v_lshl_or_b32 v140, s2, 7, v136
	v_lshl_add_u32 v138, s3, 8, v134
	v_ashrrev_i32_e32 v141, 31, v140
	v_add_f32_e32 v139, 1.0, v139
	v_rcp_f32_e32 v142, v139
	v_mul_f32_e32 v139, 0xbfb8aa3b, v125
	v_exp_f32_e32 v139, v139
	s_movk_i32 s4, 0x2c00
	s_and_b64 vcc, exec, s[6:7]
	s_mov_b64 s[20:21], s[16:17]
	v_add_f32_e32 v139, 1.0, v139
	v_rcp_f32_e32 v143, v139
	v_mul_f32_e32 v139, 0xbfb8aa3b, v126
	v_exp_f32_e32 v139, v139
	s_mov_b64 s[18:19], s[14:15]
	v_pk_mul_f32 v[124:125], v[124:125], v[142:143]
	v_add_f32_e32 v139, 1.0, v139
	v_rcp_f32_e32 v144, v139
	v_mul_f32_e32 v139, 0xbfb8aa3b, v127
	v_exp_f32_e32 v139, v139
	v_pk_mul_f32 v[116:117], v[124:125], v[116:117]
	v_add_f32_e32 v139, 1.0, v139
	v_rcp_f32_e32 v145, v139
	v_mul_f32_e32 v139, 0xbfb8aa3b, v120
	v_exp_f32_e32 v139, v139
	v_cvt_pk_bf16_f32 v116, v116, v117
	v_pk_mul_f32 v[124:125], v[126:127], v[144:145]
	v_add_f32_e32 v139, 1.0, v139
	v_rcp_f32_e32 v146, v139
	v_mul_f32_e32 v139, 0xbfb8aa3b, v121
	v_exp_f32_e32 v139, v139
	v_pk_mul_f32 v[118:119], v[124:125], v[118:119]
	v_add_f32_e32 v139, 1.0, v139
	v_rcp_f32_e32 v147, v139
	v_mul_f32_e32 v139, 0xbfb8aa3b, v122
	v_exp_f32_e32 v139, v139
	v_cvt_pk_bf16_f32 v117, v118, v119
	v_pk_mul_f32 v[118:119], v[120:121], v[146:147]
	v_add_f32_e32 v139, 1.0, v139
	v_rcp_f32_e32 v148, v139
	v_mul_f32_e32 v139, 0xbfb8aa3b, v123
	v_exp_f32_e32 v139, v139
	v_pk_mul_f32 v[112:113], v[118:119], v[112:113]
	v_add_f32_e32 v139, 1.0, v139
	v_rcp_f32_e32 v149, v139
	v_cvt_pk_bf16_f32 v118, v112, v113
	v_pk_mul_f32 v[112:113], v[122:123], v[148:149]
	s_nop 0
	v_pk_mul_f32 v[112:113], v[112:113], v[114:115]
	v_lshlrev_b64 v[114:115], 1, v[140:141]
	v_cvt_pk_bf16_f32 v119, v112, v113
	v_mov_b64_e32 v[112:113], s[54:55]
	v_mad_i64_i32 v[120:121], s[2:3], v138, s4, v[112:113]
	v_lshl_add_u64 v[120:121], v[120:121], 0, v[114:115]
	global_store_dwordx4 v[120:121], v[116:119], off
	v_mul_f32_e32 v120, 0xbfb8aa3b, v104
	v_mul_f32_e32 v121, 0xbfb8aa3b, v105
	v_mul_f32_e32 v116, 0xbfb8aa3b, v108
	v_mul_f32_e32 v117, 0xbfb8aa3b, v109
	v_exp_f32_e32 v116, v116
	v_exp_f32_e32 v117, v117
	v_mul_f32_e32 v118, 0xbfb8aa3b, v110
	v_mul_f32_e32 v119, 0xbfb8aa3b, v111
	v_exp_f32_e32 v118, v118
	v_exp_f32_e32 v119, v119
	v_exp_f32_e32 v120, v120
	v_exp_f32_e32 v121, v121
	v_add_f32_e32 v116, 1.0, v116
	v_add_f32_e32 v117, 1.0, v117
	v_mul_f32_e32 v122, 0xbfb8aa3b, v106
	v_mul_f32_e32 v123, 0xbfb8aa3b, v107
	v_rcp_f32_e32 v116, v116
	v_rcp_f32_e32 v117, v117
	v_add_f32_e32 v118, 1.0, v118
	v_add_f32_e32 v119, 1.0, v119
	v_exp_f32_e32 v122, v122
	v_exp_f32_e32 v123, v123
	v_rcp_f32_e32 v118, v118
	v_rcp_f32_e32 v119, v119
	v_add_f32_e32 v120, 1.0, v120
	v_add_f32_e32 v121, 1.0, v121
	v_rcp_f32_e32 v120, v120
	v_rcp_f32_e32 v121, v121
	v_add_f32_e32 v122, 1.0, v122
	v_add_f32_e32 v123, 1.0, v123
	v_pk_mul_f32 v[108:109], v[108:109], v[116:117]
	v_rcp_f32_e32 v122, v122
	v_rcp_f32_e32 v123, v123
	v_pk_mul_f32 v[100:101], v[108:109], v[100:101]
;     DI void operator()(const f32x4 (&acc)[2][2][4][2], const Unit& u, int wr, int wc, int fr, int fq) const {
;         const int row0 = u.pm * BM + wr * 64 + fr, col0 = u.pn * HALF + wc * 32 + 8 * fq;
; #pragma unroll
;         for (int ai = 0; ai < 2; ++ai)
; #pragma unroll
;             for (int m = 0; m < 4; ++m) { float hv[8];
; #pragma unroll
;                 for (int n = 0; n < 2; ++n)
; #pragma unroll
;                     for (int e = 0; e < 4; ++e) { const float gt = acc[ai][0][m][n][e], up = acc[ai][1][m][n][e];
;                         hv[n * 4 + e] = gt * __builtin_amdgcn_rcpf(1.f + __builtin_amdgcn_exp2f(-1.4426950408889634f * gt)) * up; }
;                 *(u32x4*)(H + (size_t)(row0 + ai * HALF + m * 16) * DFF + col0) = (u32x4){pk(hv[0], hv[1]), pk(hv[2], hv[3]), pk(hv[4], hv[5]), pk(hv[6], hv[7])}; }
	v_pk_mul_f32 v[108:109], v[110:111], v[118:119]
	v_cvt_pk_bf16_f32 v100, v100, v101
	v_pk_mul_f32 v[102:103], v[108:109], v[102:103]
	s_nop 0
	v_cvt_pk_bf16_f32 v101, v102, v103
	v_pk_mul_f32 v[102:103], v[104:105], v[120:121]
	s_nop 0
	v_pk_mul_f32 v[96:97], v[102:103], v[96:97]
	s_nop 0
	v_cvt_pk_bf16_f32 v102, v96, v97
	v_pk_mul_f32 v[96:97], v[106:107], v[122:123]
	s_nop 0
	v_pk_mul_f32 v[96:97], v[96:97], v[98:99]
	v_mul_f32_e32 v98, 0xbfb8aa3b, v94
	v_cvt_pk_bf16_f32 v103, v96, v97
	v_or_b32_e32 v96, 16, v138
	v_mad_i64_i32 v[96:97], s[2:3], v96, s4, v[112:113]
	v_lshl_add_u64 v[96:97], v[96:97], 0, v[114:115]
	global_store_dwordx4 v[96:97], v[100:103], off
	v_mul_f32_e32 v96, 0xbfb8aa3b, v92
	v_mul_f32_e32 v97, 0xbfb8aa3b, v93
	v_exp_f32_e32 v96, v96
	v_exp_f32_e32 v97, v97
	v_mul_f32_e32 v99, 0xbfb8aa3b, v95
	v_exp_f32_e32 v98, v98
	v_exp_f32_e32 v99, v99
	v_mul_f32_e32 v100, 0xbfb8aa3b, v88
	v_mul_f32_e32 v101, 0xbfb8aa3b, v89
	v_exp_f32_e32 v100, v100
	v_exp_f32_e32 v101, v101
	v_add_f32_e32 v96, 1.0, v96
	v_add_f32_e32 v97, 1.0, v97
	v_mul_f32_e32 v102, 0xbfb8aa3b, v90
	v_mul_f32_e32 v103, 0xbfb8aa3b, v91
	v_rcp_f32_e32 v96, v96
	v_rcp_f32_e32 v97, v97
	v_add_f32_e32 v98, 1.0, v98
	v_add_f32_e32 v99, 1.0, v99
	v_exp_f32_e32 v102, v102
	v_exp_f32_e32 v103, v103
	v_rcp_f32_e32 v98, v98
	v_rcp_f32_e32 v99, v99
	v_add_f32_e32 v100, 1.0, v100
	v_add_f32_e32 v101, 1.0, v101
	v_rcp_f32_e32 v100, v100
	v_rcp_f32_e32 v101, v101
	v_add_f32_e32 v102, 1.0, v102
	v_add_f32_e32 v103, 1.0, v103
	v_pk_mul_f32 v[92:93], v[92:93], v[96:97]
	v_rcp_f32_e32 v102, v102
	v_rcp_f32_e32 v103, v103
	v_pk_mul_f32 v[84:85], v[92:93], v[84:85]
	v_pk_mul_f32 v[92:93], v[94:95], v[98:99]
	v_cvt_pk_bf16_f32 v84, v84, v85
	v_pk_mul_f32 v[86:87], v[92:93], v[86:87]
	s_nop 0
	v_cvt_pk_bf16_f32 v85, v86, v87
	v_pk_mul_f32 v[86:87], v[88:89], v[100:101]
	s_nop 0
	v_pk_mul_f32 v[80:81], v[86:87], v[80:81]
	s_nop 0
	v_cvt_pk_bf16_f32 v86, v80, v81
	v_pk_mul_f32 v[80:81], v[90:91], v[102:103]
	s_nop 0
	v_pk_mul_f32 v[80:81], v[80:81], v[82:83]
	v_mul_f32_e32 v82, 0xbfb8aa3b, v78
	v_cvt_pk_bf16_f32 v87, v80, v81
	v_or_b32_e32 v80, 32, v138
	v_mad_i64_i32 v[80:81], s[2:3], v80, s4, v[112:113]
	v_lshl_add_u64 v[80:81], v[80:81], 0, v[114:115]
	global_store_dwordx4 v[80:81], v[84:87], off
	v_mul_f32_e32 v80, 0xbfb8aa3b, v76
	v_mul_f32_e32 v81, 0xbfb8aa3b, v77
	v_exp_f32_e32 v80, v80
	v_exp_f32_e32 v81, v81
	v_mul_f32_e32 v83, 0xbfb8aa3b, v79
	v_exp_f32_e32 v82, v82
	v_exp_f32_e32 v83, v83
	v_mul_f32_e32 v84, 0xbfb8aa3b, v72
	v_mul_f32_e32 v85, 0xbfb8aa3b, v73
	v_exp_f32_e32 v84, v84
	v_exp_f32_e32 v85, v85
	v_add_f32_e32 v80, 1.0, v80
	v_add_f32_e32 v81, 1.0, v81
	v_mul_f32_e32 v86, 0xbfb8aa3b, v74
	v_mul_f32_e32 v87, 0xbfb8aa3b, v75
	v_rcp_f32_e32 v80, v80
	v_rcp_f32_e32 v81, v81
	v_add_f32_e32 v82, 1.0, v82
	v_add_f32_e32 v83, 1.0, v83
	v_exp_f32_e32 v86, v86
	v_exp_f32_e32 v87, v87
	v_rcp_f32_e32 v82, v82
	v_rcp_f32_e32 v83, v83
	v_add_f32_e32 v84, 1.0, v84
	v_add_f32_e32 v85, 1.0, v85
	v_rcp_f32_e32 v84, v84
	v_rcp_f32_e32 v85, v85
	v_add_f32_e32 v86, 1.0, v86
	v_add_f32_e32 v87, 1.0, v87
	v_pk_mul_f32 v[76:77], v[76:77], v[80:81]
	v_rcp_f32_e32 v86, v86
	v_rcp_f32_e32 v87, v87
	v_pk_mul_f32 v[68:69], v[76:77], v[68:69]
	v_pk_mul_f32 v[76:77], v[78:79], v[82:83]
	v_cvt_pk_bf16_f32 v68, v68, v69
	v_pk_mul_f32 v[70:71], v[76:77], v[70:71]
	s_nop 0
	v_cvt_pk_bf16_f32 v69, v70, v71
	v_pk_mul_f32 v[70:71], v[72:73], v[84:85]
	v_add_u32_e32 v72, 0x80, v138
	v_pk_mul_f32 v[64:65], v[70:71], v[64:65]
	s_nop 0
	v_cvt_pk_bf16_f32 v70, v64, v65
	v_pk_mul_f32 v[64:65], v[74:75], v[86:87]
	s_nop 0
	v_pk_mul_f32 v[64:65], v[64:65], v[66:67]
	v_mul_f32_e32 v66, 0xbfb8aa3b, v62
	v_cvt_pk_bf16_f32 v71, v64, v65
	v_or_b32_e32 v64, 48, v138
	v_mad_i64_i32 v[64:65], s[2:3], v64, s4, v[112:113]
	v_lshl_add_u64 v[64:65], v[64:65], 0, v[114:115]
	global_store_dwordx4 v[64:65], v[68:71], off
	v_mul_f32_e32 v64, 0xbfb8aa3b, v60
	v_mul_f32_e32 v65, 0xbfb8aa3b, v61
	v_exp_f32_e32 v64, v64
	v_exp_f32_e32 v65, v65
	v_mul_f32_e32 v67, 0xbfb8aa3b, v63
	v_exp_f32_e32 v66, v66
	v_exp_f32_e32 v67, v67
	v_mul_f32_e32 v68, 0xbfb8aa3b, v56
	v_mul_f32_e32 v69, 0xbfb8aa3b, v57
	v_exp_f32_e32 v68, v68
	v_exp_f32_e32 v69, v69
	v_add_f32_e32 v64, 1.0, v64
	v_add_f32_e32 v65, 1.0, v65
	v_mul_f32_e32 v70, 0xbfb8aa3b, v58
	v_mul_f32_e32 v71, 0xbfb8aa3b, v59
	v_rcp_f32_e32 v64, v64
	v_rcp_f32_e32 v65, v65
	v_add_f32_e32 v66, 1.0, v66
	v_add_f32_e32 v67, 1.0, v67
	v_exp_f32_e32 v70, v70
	v_exp_f32_e32 v71, v71
	v_rcp_f32_e32 v66, v66
	v_rcp_f32_e32 v67, v67
	v_add_f32_e32 v68, 1.0, v68
	v_add_f32_e32 v69, 1.0, v69
	v_rcp_f32_e32 v68, v68
	v_rcp_f32_e32 v69, v69
	v_add_f32_e32 v70, 1.0, v70
	v_add_f32_e32 v71, 1.0, v71
	v_pk_mul_f32 v[60:61], v[60:61], v[64:65]
	v_rcp_f32_e32 v70, v70
	v_rcp_f32_e32 v71, v71
	v_pk_mul_f32 v[52:53], v[60:61], v[52:53]
	v_pk_mul_f32 v[60:61], v[62:63], v[66:67]
	v_cvt_pk_bf16_f32 v52, v52, v53
	v_pk_mul_f32 v[54:55], v[60:61], v[54:55]
	s_nop 0
	v_cvt_pk_bf16_f32 v53, v54, v55
	v_pk_mul_f32 v[54:55], v[56:57], v[68:69]
	s_nop 0
	v_pk_mul_f32 v[48:49], v[54:55], v[48:49]
	s_nop 0
	v_cvt_pk_bf16_f32 v54, v48, v49
; #define PG8_WAIT_V(n) asm volatile("s_waitcnt vmcnt(" #n ")" ::: "memory")
; #define PG8_BAR __builtin_amdgcn_s_barrier()
; template <class Epi>
; DI void gemm_phase(LAS unsigned char* lds, const Gemm g, const StaticOrder& S, const Epi& E) {
;     ...
;         if (!has_next) break;
; #pragma unroll
;         for (int a = 0; a < 2; ++a)
; #pragma unroll
;             for (int b = 0; b < 2; ++b)
; #pragma unroll
;                 for (int m = 0; m < 4; ++m)
; #pragma unroll
;                     for (int n = 0; n < 2; ++n) acc[a][b][m][n] = (f32x4){0.f, 0.f, 0.f, 0.f};
;         cur = nxt; cA = nA; cB = nB; ++ui;
;     }
;     PG8_WAIT_V(0);
;     if (wr == 0) PG8_BAR;
;     DI void operator()(const f32x4 (&acc)[2][2][4][2], const Unit& u, int wr, int wc, int fr, int fq) const {
;         const int row0 = u.pm * BM + wr * 64 + fr, col0 = u.pn * HALF + wc * 32 + 8 * fq;
; #pragma unroll
;         for (int ai = 0; ai < 2; ++ai)
; #pragma unroll
;             for (int m = 0; m < 4; ++m) { float hv[8];
; #pragma unroll
;                 for (int n = 0; n < 2; ++n)
; #pragma unroll
;                     for (int e = 0; e < 4; ++e) { const float gt = acc[ai][0][m][n][e], up = acc[ai][1][m][n][e];
;                         hv[n * 4 + e] = gt * __builtin_amdgcn_rcpf(1.f + __builtin_amdgcn_exp2f(-1.4426950408889634f * gt)) * up; }
;                 *(u32x4*)(H + (size_t)(row0 + ai * HALF + m * 16) * DFF + col0) = (u32x4){pk(hv[0], hv[1]), pk(hv[2], hv[3]), pk(hv[4], hv[5]), pk(hv[6], hv[7])}; }
	v_pk_mul_f32 v[48:49], v[58:59], v[70:71]
	s_nop 0
	v_pk_mul_f32 v[48:49], v[48:49], v[50:51]
	v_mul_f32_e32 v50, 0xbfb8aa3b, v46
	v_cvt_pk_bf16_f32 v55, v48, v49
	v_mad_i64_i32 v[48:49], s[2:3], v72, s4, v[112:113]
	v_lshl_add_u64 v[48:49], v[48:49], 0, v[114:115]
	global_store_dwordx4 v[48:49], v[52:55], off
	v_mul_f32_e32 v48, 0xbfb8aa3b, v44
	v_mul_f32_e32 v49, 0xbfb8aa3b, v45
	v_exp_f32_e32 v48, v48
	v_exp_f32_e32 v49, v49
	v_mul_f32_e32 v51, 0xbfb8aa3b, v47
	v_exp_f32_e32 v50, v50
	v_exp_f32_e32 v51, v51
	v_mul_f32_e32 v52, 0xbfb8aa3b, v40
	v_mul_f32_e32 v53, 0xbfb8aa3b, v41
	v_exp_f32_e32 v52, v52
	v_exp_f32_e32 v53, v53
	v_add_f32_e32 v48, 1.0, v48
	v_add_f32_e32 v49, 1.0, v49
	v_mul_f32_e32 v54, 0xbfb8aa3b, v42
	v_mul_f32_e32 v55, 0xbfb8aa3b, v43
	v_rcp_f32_e32 v48, v48
	v_rcp_f32_e32 v49, v49
	v_add_f32_e32 v50, 1.0, v50
	v_add_f32_e32 v51, 1.0, v51
	v_exp_f32_e32 v54, v54
	v_exp_f32_e32 v55, v55
	v_rcp_f32_e32 v50, v50
	v_rcp_f32_e32 v51, v51
	v_add_f32_e32 v52, 1.0, v52
	v_add_f32_e32 v53, 1.0, v53
	v_rcp_f32_e32 v52, v52
	v_rcp_f32_e32 v53, v53
	v_add_f32_e32 v54, 1.0, v54
	v_add_f32_e32 v55, 1.0, v55
	v_pk_mul_f32 v[44:45], v[44:45], v[48:49]
	v_rcp_f32_e32 v54, v54
	v_rcp_f32_e32 v55, v55
	v_pk_mul_f32 v[36:37], v[44:45], v[36:37]
	v_pk_mul_f32 v[44:45], v[46:47], v[50:51]
	v_cvt_pk_bf16_f32 v36, v36, v37
	v_pk_mul_f32 v[38:39], v[44:45], v[38:39]
	s_nop 0
	v_cvt_pk_bf16_f32 v37, v38, v39
	v_pk_mul_f32 v[38:39], v[40:41], v[52:53]
	s_nop 0
	v_pk_mul_f32 v[32:33], v[38:39], v[32:33]
	s_nop 0
	v_cvt_pk_bf16_f32 v38, v32, v33
	v_pk_mul_f32 v[32:33], v[42:43], v[54:55]
	s_nop 0
	v_pk_mul_f32 v[32:33], v[32:33], v[34:35]
	v_mul_f32_e32 v34, 0xbfb8aa3b, v30
	v_cvt_pk_bf16_f32 v39, v32, v33
	v_add_u32_e32 v32, 0x90, v138
	v_mad_i64_i32 v[32:33], s[2:3], v32, s4, v[112:113]
	v_lshl_add_u64 v[32:33], v[32:33], 0, v[114:115]
	global_store_dwordx4 v[32:33], v[36:39], off
	v_mul_f32_e32 v32, 0xbfb8aa3b, v28
	v_mul_f32_e32 v33, 0xbfb8aa3b, v29
	v_exp_f32_e32 v32, v32
	v_exp_f32_e32 v33, v33
	v_mul_f32_e32 v35, 0xbfb8aa3b, v31
	v_exp_f32_e32 v34, v34
	v_exp_f32_e32 v35, v35
	v_mul_f32_e32 v36, 0xbfb8aa3b, v24
	v_mul_f32_e32 v37, 0xbfb8aa3b, v25
	v_exp_f32_e32 v36, v36
	v_exp_f32_e32 v37, v37
	v_add_f32_e32 v32, 1.0, v32
	v_add_f32_e32 v33, 1.0, v33
	v_mul_f32_e32 v38, 0xbfb8aa3b, v26
	v_mul_f32_e32 v39, 0xbfb8aa3b, v27
	v_rcp_f32_e32 v32, v32
	v_rcp_f32_e32 v33, v33
	v_add_f32_e32 v34, 1.0, v34
	v_add_f32_e32 v35, 1.0, v35
	v_exp_f32_e32 v38, v38
	v_exp_f32_e32 v39, v39
	v_rcp_f32_e32 v34, v34
	v_rcp_f32_e32 v35, v35
	v_add_f32_e32 v36, 1.0, v36
	v_add_f32_e32 v37, 1.0, v37
	v_rcp_f32_e32 v36, v36
	v_rcp_f32_e32 v37, v37
	v_add_f32_e32 v38, 1.0, v38
	v_add_f32_e32 v39, 1.0, v39
	v_pk_mul_f32 v[28:29], v[28:29], v[32:33]
	v_rcp_f32_e32 v38, v38
	v_rcp_f32_e32 v39, v39
	v_pk_mul_f32 v[20:21], v[28:29], v[20:21]
	v_pk_mul_f32 v[28:29], v[30:31], v[34:35]
	v_cvt_pk_bf16_f32 v20, v20, v21
	v_pk_mul_f32 v[22:23], v[28:29], v[22:23]
	s_nop 0
	v_cvt_pk_bf16_f32 v21, v22, v23
	v_pk_mul_f32 v[22:23], v[24:25], v[36:37]
	s_nop 0
	v_pk_mul_f32 v[16:17], v[22:23], v[16:17]
	s_nop 0
	v_cvt_pk_bf16_f32 v22, v16, v17
	v_pk_mul_f32 v[16:17], v[26:27], v[38:39]
	s_nop 0
	v_pk_mul_f32 v[16:17], v[16:17], v[18:19]
	v_mul_f32_e32 v18, 0xbfb8aa3b, v14
	v_cvt_pk_bf16_f32 v23, v16, v17
	v_add_u32_e32 v16, 0xa0, v138
	v_mad_i64_i32 v[16:17], s[2:3], v16, s4, v[112:113]
	v_lshl_add_u64 v[16:17], v[16:17], 0, v[114:115]
	global_store_dwordx4 v[16:17], v[20:23], off
	v_mul_f32_e32 v16, 0xbfb8aa3b, v12
	v_mul_f32_e32 v17, 0xbfb8aa3b, v13
	v_exp_f32_e32 v16, v16
	v_exp_f32_e32 v17, v17
	v_mul_f32_e32 v19, 0xbfb8aa3b, v15
	v_exp_f32_e32 v18, v18
	v_exp_f32_e32 v19, v19
	v_mul_f32_e32 v20, 0xbfb8aa3b, v8
	v_mul_f32_e32 v21, 0xbfb8aa3b, v9
	v_exp_f32_e32 v20, v20
	v_exp_f32_e32 v21, v21
	v_add_f32_e32 v16, 1.0, v16
	v_add_f32_e32 v17, 1.0, v17
	v_mul_f32_e32 v22, 0xbfb8aa3b, v10
	v_mul_f32_e32 v23, 0xbfb8aa3b, v11
	v_rcp_f32_e32 v16, v16
	v_rcp_f32_e32 v17, v17
	v_add_f32_e32 v18, 1.0, v18
	v_add_f32_e32 v19, 1.0, v19
	v_exp_f32_e32 v22, v22
	v_exp_f32_e32 v23, v23
	v_rcp_f32_e32 v18, v18
	v_rcp_f32_e32 v19, v19
	v_add_f32_e32 v20, 1.0, v20
	v_add_f32_e32 v21, 1.0, v21
	v_rcp_f32_e32 v20, v20
	v_rcp_f32_e32 v21, v21
	v_add_f32_e32 v22, 1.0, v22
	v_add_f32_e32 v23, 1.0, v23
	v_pk_mul_f32 v[12:13], v[12:13], v[16:17]
	v_rcp_f32_e32 v22, v22
	v_rcp_f32_e32 v23, v23
	v_pk_mul_f32 v[4:5], v[12:13], v[4:5]
	v_pk_mul_f32 v[12:13], v[14:15], v[18:19]
	v_cvt_pk_bf16_f32 v4, v4, v5
	v_pk_mul_f32 v[6:7], v[12:13], v[6:7]
	s_nop 0
	v_cvt_pk_bf16_f32 v5, v6, v7
	v_pk_mul_f32 v[6:7], v[8:9], v[20:21]
	s_nop 0
	v_pk_mul_f32 v[0:1], v[6:7], v[0:1]
	s_nop 0
	v_cvt_pk_bf16_f32 v6, v0, v1
	v_pk_mul_f32 v[0:1], v[10:11], v[22:23]
	s_nop 0
	v_pk_mul_f32 v[0:1], v[0:1], v[2:3]
	s_nop 0
	v_cvt_pk_bf16_f32 v7, v0, v1
	v_add_u32_e32 v0, 0xb0, v138
	v_mad_i64_i32 v[0:1], s[2:3], v0, s4, v[112:113]
	v_lshl_add_u64 v[0:1], v[0:1], 0, v[114:115]
	s_mov_b32 s2, s8
	s_mov_b32 s3, s10
	global_store_dwordx4 v[0:1], v[4:7], off
	s_cbranch_vccz .LBB0_34
	s_waitcnt vmcnt(0)
	s_cmpk_gt_u32 s24, 0xff
	s_cbranch_scc1 .LBB0_41
	s_barrier

; #define PG8_STAGE(bufoff, gbase) do { _Pragma("unroll") for (int _i = 0; _i < 2; ++_i) \
;         __builtin_amdgcn_global_load_lds((const unsigned*)((const char*)(gbase) + voff[_i]), (LAS unsigned*)(lds + (bufoff) + ldsw + _i * 8192), 16, 0, 0); } while (0)
; #define PG8_LDA(dst, b, h) do { _Pragma("unroll") for (int m = 0; m < 4; ++m) _Pragma("unroll") for (int k = 0; k < 2; ++k) dst[m][k] = *(const LAS bf16x8*)(lds + PG8_SA(b, h) + aoff + m * 2048 + k * 1024); } while (0)
; #define PG8_LDB(dst, b, h) do { _Pragma("unroll") for (int n = 0; n < 2; ++n) _Pragma("unroll") for (int k = 0; k < 2; ++k) dst[n][k] = *(const LAS bf16x8*)(lds + PG8_SB(b, h) + boff + n * 2048 + k * 1024); } while (0)
; #define PG8_MMA(ai, bj, At, Bt) do { __builtin_amdgcn_s_setprio(1); _Pragma("unroll") for (int m = 0; m < 4; ++m) _Pragma("unroll") for (int n = 0; n < 2; ++n) _Pragma("unroll") for (int k = 0; k < 2; ++k) \
;         acc[ai][bj][m][n] = __builtin_amdgcn_mfma_f32_16x16x32_bf16(Bt[n][k], At[m][k], acc[ai][bj][m][n], 0, 0, 0); __builtin_amdgcn_s_setprio(0); } while (0)
; #define PG8_WAIT_V(n) asm volatile("s_waitcnt vmcnt(" #n ")" ::: "memory")
; #define PG8_WAIT_L(n) asm volatile("s_waitcnt lgkmcnt(" #n ")" ::: "memory")
; #define PG8_BAR __builtin_amdgcn_s_barrier()
; #define PG8_SCHED __builtin_amdgcn_sched_barrier(0)
; template <class Epi>
; DI void gemm_phase(LAS unsigned char* lds, const Gemm g, const StaticOrder& S, const Epi& E) {
;     ...
;         for (int t = 0; t < nt; t += 2) {
;             const bool last = (t == nt - 2);
;             const char* a1 = cA + (size_t)(t + 1) * kstep;
;             const char* a2 = last ? nA : cA + (size_t)(t + 2) * kstep; const char* b2 = last ? nB : cB + (size_t)(t + 2) * kstep;
;             const char* a3 = a2 + kstep; const char* b3 = b2 + kstep;
;             PG8_LDB(B0, 0, 0); PG8_SCHED; PG8_LDA(At, 0, 0); PG8_STAGE(PG8_SA(1, 1), a1 + hstep);
;             PG8_WAIT_L(8); PG8_BAR; PG8_WAIT_L(0); PG8_MMA(0, 0, At, B0); PG8_BAR; PG8_SCHED;
;             PG8_LDB(B1, 0, 1); PG8_STAGE(PG8_SB(0, 0), b2);
;             PG8_BAR; PG8_WAIT_L(0); PG8_MMA(0, 1, At, B1); PG8_BAR;
;             PG8_LDA(At, 0, 1); PG8_STAGE(PG8_SA(0, 0), a2);
;             PG8_BAR; PG8_WAIT_L(0); PG8_MMA(1, 0, At, B0); PG8_BAR; PG8_SCHED;
;             PG8_STAGE(PG8_SB(0, 1), b2 + hstep);
;             PG8_WAIT_V(6); PG8_BAR; PG8_MMA(1, 1, At, B1); PG8_BAR;
.LBB0_77:
	ds_read_b128 v[128:131], v226
	ds_read_b128 v[132:135], v226 offset:1024
	ds_read_b128 v[136:139], v226 offset:2048
	ds_read_b128 v[140:143], v226 offset:3072
	ds_read_b128 v[144:147], v228
	ds_read_b128 v[148:151], v228 offset:1024
	ds_read_b128 v[152:155], v228 offset:2048
	ds_read_b128 v[194:197], v228 offset:3072
	ds_read_b128 v[198:201], v228 offset:4096
	ds_read_b128 v[202:205], v228 offset:5120
	ds_read_b128 v[206:209], v228 offset:6144
	ds_read_b128 v[210:213], v228 offset:7168
	s_add_u32 s22, s20, 0x100
	s_addc_u32 s23, s21, 0
	s_add_i32 s43, 0, 0x10000
	s_cmp_eq_u32 s33, 32
	s_cselect_b32 s27, s9, s23
	s_cselect_b32 s26, s8, s22
	s_cselect_b32 s25, s11, s5
	s_cselect_b32 s24, s10, s4
	s_add_i32 m0, s34, 0xc000
	s_nop 0
	global_load_lds_dwordx4 v190, s[20:21]
	s_add_i32 m0, s34, 0xe000
	s_nop 0
	global_load_lds_dwordx4 v192, s[20:21]
	s_waitcnt lgkmcnt(8)
	s_barrier
	s_waitcnt lgkmcnt(0)
	v_mfma_f32_16x16x32_bf16 v[124:127], v[128:131], v[144:147], v[124:127]
	v_mfma_f32_16x16x32_bf16 v[120:123], v[136:139], v[144:147], v[120:123]
	v_mfma_f32_16x16x32_bf16 v[116:119], v[128:131], v[152:155], v[116:119]
	v_mfma_f32_16x16x32_bf16 v[112:115], v[136:139], v[152:155], v[112:115]
	v_mfma_f32_16x16x32_bf16 v[108:111], v[128:131], v[198:201], v[108:111]
	v_mfma_f32_16x16x32_bf16 v[104:107], v[136:139], v[198:201], v[104:107]
	v_mfma_f32_16x16x32_bf16 v[100:103], v[128:131], v[206:209], v[100:103]
	v_mfma_f32_16x16x32_bf16 v[96:99], v[136:139], v[206:209], v[96:99]
	v_mfma_f32_16x16x32_bf16 v[124:127], v[132:135], v[148:151], v[124:127]
	v_mfma_f32_16x16x32_bf16 v[120:123], v[140:143], v[148:151], v[120:123]
	v_mfma_f32_16x16x32_bf16 v[116:119], v[132:135], v[194:197], v[116:119]
	v_mfma_f32_16x16x32_bf16 v[112:115], v[140:143], v[194:197], v[112:115]
	v_mfma_f32_16x16x32_bf16 v[108:111], v[132:135], v[202:205], v[108:111]
	v_mfma_f32_16x16x32_bf16 v[104:107], v[140:143], v[202:205], v[104:107]
	v_mfma_f32_16x16x32_bf16 v[100:103], v[132:135], v[210:213], v[100:103]
	v_mfma_f32_16x16x32_bf16 v[96:99], v[140:143], v[210:213], v[96:99]
	s_barrier
	ds_read_b128 v[214:217], v226 offset:16384
	ds_read_b128 v[230:233], v226 offset:17408
	ds_read_b128 v[234:237], v226 offset:18432
	ds_read_b128 v[238:241], v226 offset:19456
	s_add_i32 s44, 0, 0x14000
	s_add_i32 s20, s43, s31
	s_mov_b32 m0, s20
	s_nop 0
	global_load_lds_dwordx4 v188, s[24:25]
	s_add_i32 m0, s20, 0x2000
	s_nop 0
	global_load_lds_dwordx4 v186, s[24:25]
	s_waitcnt lgkmcnt(0)
	s_barrier
	v_mfma_f32_16x16x32_bf16 v[60:63], v[214:217], v[144:147], v[60:63]
	v_mfma_f32_16x16x32_bf16 v[56:59], v[234:237], v[144:147], v[56:59]
	v_mfma_f32_16x16x32_bf16 v[52:55], v[214:217], v[152:155], v[52:55]
	v_mfma_f32_16x16x32_bf16 v[48:51], v[234:237], v[152:155], v[48:51]
	v_mfma_f32_16x16x32_bf16 v[44:47], v[214:217], v[198:201], v[44:47]
	v_mfma_f32_16x16x32_bf16 v[40:43], v[234:237], v[198:201], v[40:43]
	v_mfma_f32_16x16x32_bf16 v[36:39], v[214:217], v[206:209], v[36:39]
	v_mfma_f32_16x16x32_bf16 v[32:35], v[234:237], v[206:209], v[32:35]
	v_mfma_f32_16x16x32_bf16 v[60:63], v[230:233], v[148:151], v[60:63]
	s_mov_b32 m0, s34
	v_mfma_f32_16x16x32_bf16 v[56:59], v[238:241], v[148:151], v[56:59]
	s_mov_b64 s[100:101], s[26:27]
	v_mfma_f32_16x16x32_bf16 v[52:55], v[230:233], v[194:197], v[52:55]
	v_mfma_f32_16x16x32_bf16 v[48:51], v[238:241], v[194:197], v[48:51]
	v_mfma_f32_16x16x32_bf16 v[44:47], v[230:233], v[202:205], v[44:47]
	v_mfma_f32_16x16x32_bf16 v[40:43], v[238:241], v[202:205], v[40:43]
	v_mfma_f32_16x16x32_bf16 v[36:39], v[230:233], v[210:213], v[36:39]
	v_mfma_f32_16x16x32_bf16 v[32:35], v[238:241], v[210:213], v[32:35]
	s_barrier
	ds_read_b128 v[144:147], v228 offset:16384
	ds_read_b128 v[148:151], v228 offset:17408
	ds_read_b128 v[152:155], v228 offset:18432
	ds_read_b128 v[194:197], v228 offset:19456
	ds_read_b128 v[198:201], v228 offset:20480
	ds_read_b128 v[202:205], v228 offset:21504
	ds_read_b128 v[206:209], v228 offset:22528
	ds_read_b128 v[210:213], v228 offset:23552
	global_load_lds_dwordx4 v188, s[26:27]
	s_mov_b64 s[100:101], s[26:27]
	s_mov_b32 m0, s35
	s_nop 0
	global_load_lds_dwordx4 v186, s[26:27]
	s_waitcnt lgkmcnt(0)
	s_barrier
	v_mfma_f32_16x16x32_bf16 v[92:95], v[128:131], v[144:147], v[92:95]
	v_mfma_f32_16x16x32_bf16 v[88:91], v[136:139], v[144:147], v[88:91]
	v_mfma_f32_16x16x32_bf16 v[84:87], v[128:131], v[152:155], v[84:87]
	v_mfma_f32_16x16x32_bf16 v[80:83], v[136:139], v[152:155], v[80:83]
	v_mfma_f32_16x16x32_bf16 v[76:79], v[128:131], v[198:201], v[76:79]
	v_mfma_f32_16x16x32_bf16 v[72:75], v[136:139], v[198:201], v[72:75]
	v_mfma_f32_16x16x32_bf16 v[68:71], v[128:131], v[206:209], v[68:71]
	v_mfma_f32_16x16x32_bf16 v[64:67], v[136:139], v[206:209], v[64:67]
	v_mfma_f32_16x16x32_bf16 v[92:95], v[132:135], v[148:151], v[92:95]
	v_mfma_f32_16x16x32_bf16 v[88:91], v[140:143], v[148:151], v[88:91]
	v_mfma_f32_16x16x32_bf16 v[84:87], v[132:135], v[194:197], v[84:87]
	v_mfma_f32_16x16x32_bf16 v[80:83], v[140:143], v[194:197], v[80:83]
	v_mfma_f32_16x16x32_bf16 v[76:79], v[132:135], v[202:205], v[76:79]
	v_mfma_f32_16x16x32_bf16 v[72:75], v[140:143], v[202:205], v[72:75]
	v_mfma_f32_16x16x32_bf16 v[68:71], v[132:135], v[210:213], v[68:71]
	v_mfma_f32_16x16x32_bf16 v[64:67], v[140:143], v[210:213], v[64:67]
	s_barrier
	s_add_u32 s20, s24, 0x90000
	s_addc_u32 s21, s25, 0
	s_add_i32 s43, s44, s31
	s_mov_b32 m0, s43
	s_nop 0
	global_load_lds_dwordx4 v188, s[20:21]
	s_add_i32 m0, s43, 0x2000
	s_nop 0
	global_load_lds_dwordx4 v186, s[20:21]
	s_waitcnt vmcnt(6)
	s_barrier
; #define PG8_STAGE(bufoff, gbase) do { _Pragma("unroll") for (int _i = 0; _i < 2; ++_i) \
;         __builtin_amdgcn_global_load_lds((const unsigned*)((const char*)(gbase) + voff[_i]), (LAS unsigned*)(lds + (bufoff) + ldsw + _i * 8192), 16, 0, 0); } while (0)
; #define PG8_LDA(dst, b, h) do { _Pragma("unroll") for (int m = 0; m < 4; ++m) _Pragma("unroll") for (int k = 0; k < 2; ++k) dst[m][k] = *(const LAS bf16x8*)(lds + PG8_SA(b, h) + aoff + m * 2048 + k * 1024); } while (0)
; #define PG8_LDB(dst, b, h) do { _Pragma("unroll") for (int n = 0; n < 2; ++n) _Pragma("unroll") for (int k = 0; k < 2; ++k) dst[n][k] = *(const LAS bf16x8*)(lds + PG8_SB(b, h) + boff + n * 2048 + k * 1024); } while (0)
; #define PG8_MMA(ai, bj, At, Bt) do { __builtin_amdgcn_s_setprio(1); _Pragma("unroll") for (int m = 0; m < 4; ++m) _Pragma("unroll") for (int n = 0; n < 2; ++n) _Pragma("unroll") for (int k = 0; k < 2; ++k) \
;         acc[ai][bj][m][n] = __builtin_amdgcn_mfma_f32_16x16x32_bf16(Bt[n][k], At[m][k], acc[ai][bj][m][n], 0, 0, 0); __builtin_amdgcn_s_setprio(0); } while (0)
; #define PG8_WAIT_V(n) asm volatile("s_waitcnt vmcnt(" #n ")" ::: "memory")
; #define PG8_WAIT_L(n) asm volatile("s_waitcnt lgkmcnt(" #n ")" ::: "memory")
; #define PG8_BAR __builtin_amdgcn_s_barrier()
; #define PG8_SCHED __builtin_amdgcn_sched_barrier(0)
; template <class Epi>
; DI void gemm_phase(LAS unsigned char* lds, const Gemm g, const StaticOrder& S, const Epi& E) {
;     ...
;             PG8_WAIT_V(6); PG8_BAR; PG8_MMA(1, 1, At, B1); PG8_BAR;
;             PG8_LDB(B0, 1, 0); PG8_SCHED; PG8_LDA(At, 1, 0); PG8_STAGE(PG8_SA(0, 1), a2 + hstep);
;             PG8_WAIT_L(8); PG8_BAR; PG8_WAIT_L(0); PG8_MMA(0, 0, At, B0); PG8_BAR; PG8_SCHED;
;             PG8_LDB(B1, 1, 1); PG8_STAGE(PG8_SB(1, 0), b3);
;             PG8_BAR; PG8_WAIT_L(0); PG8_MMA(0, 1, At, B1); PG8_BAR;
;             PG8_LDA(At, 1, 1); PG8_STAGE(PG8_SA(1, 0), a3);
;             PG8_BAR; PG8_WAIT_L(0); PG8_MMA(1, 0, At, B0); PG8_BAR; PG8_SCHED;
;             PG8_STAGE(PG8_SB(1, 1), b3 + hstep);
	v_mfma_f32_16x16x32_bf16 v[28:31], v[214:217], v[144:147], v[28:31]
	v_mfma_f32_16x16x32_bf16 v[24:27], v[234:237], v[144:147], v[24:27]
	v_mfma_f32_16x16x32_bf16 v[20:23], v[214:217], v[152:155], v[20:23]
	v_mfma_f32_16x16x32_bf16 v[16:19], v[234:237], v[152:155], v[16:19]
	v_mfma_f32_16x16x32_bf16 v[12:15], v[214:217], v[198:201], v[12:15]
	v_mfma_f32_16x16x32_bf16 v[8:11], v[234:237], v[198:201], v[8:11]
	v_mfma_f32_16x16x32_bf16 v[4:7], v[214:217], v[206:209], v[4:7]
	v_mfma_f32_16x16x32_bf16 v[0:3], v[234:237], v[206:209], v[0:3]
	v_mfma_f32_16x16x32_bf16 v[28:31], v[230:233], v[148:151], v[28:31]
	s_add_i32 s43, 0, 0x18000
	v_mfma_f32_16x16x32_bf16 v[24:27], v[238:241], v[148:151], v[24:27]
	v_mfma_f32_16x16x32_bf16 v[20:23], v[230:233], v[194:197], v[20:23]
	v_mfma_f32_16x16x32_bf16 v[16:19], v[238:241], v[194:197], v[16:19]
	v_mfma_f32_16x16x32_bf16 v[12:15], v[230:233], v[202:205], v[12:15]
	v_mfma_f32_16x16x32_bf16 v[8:11], v[238:241], v[202:205], v[8:11]
	v_mfma_f32_16x16x32_bf16 v[4:7], v[230:233], v[210:213], v[4:7]
	v_mfma_f32_16x16x32_bf16 v[0:3], v[238:241], v[210:213], v[0:3]
	s_barrier
	ds_read_b128 v[128:131], v226 offset:32768
	ds_read_b128 v[132:135], v226 offset:33792
	ds_read_b128 v[136:139], v226 offset:34816
	ds_read_b128 v[140:143], v226 offset:35840
	ds_read_b128 v[144:147], v228 offset:32768
	ds_read_b128 v[148:151], v228 offset:33792
	ds_read_b128 v[152:155], v228 offset:34816
	ds_read_b128 v[194:197], v228 offset:35840
	ds_read_b128 v[198:201], v228 offset:36864
	ds_read_b128 v[202:205], v228 offset:37888
	ds_read_b128 v[206:209], v228 offset:38912
	ds_read_b128 v[210:213], v228 offset:39936
	s_add_u32 s20, s26, 0x90000
	s_addc_u32 s21, s27, 0
	s_mov_b32 m0, s36
	s_nop 0
	global_load_lds_dwordx4 v188, s[20:21]
	s_mov_b32 m0, s37
	s_nop 0
	global_load_lds_dwordx4 v186, s[20:21]
	s_waitcnt lgkmcnt(8)
	s_barrier
	s_waitcnt lgkmcnt(0)
	v_mfma_f32_16x16x32_bf16 v[124:127], v[128:131], v[144:147], v[124:127]
	v_mfma_f32_16x16x32_bf16 v[120:123], v[136:139], v[144:147], v[120:123]
	v_mfma_f32_16x16x32_bf16 v[116:119], v[128:131], v[152:155], v[116:119]
	v_mfma_f32_16x16x32_bf16 v[112:115], v[136:139], v[152:155], v[112:115]
	v_mfma_f32_16x16x32_bf16 v[108:111], v[128:131], v[198:201], v[108:111]
	v_mfma_f32_16x16x32_bf16 v[104:107], v[136:139], v[198:201], v[104:107]
	v_mfma_f32_16x16x32_bf16 v[100:103], v[128:131], v[206:209], v[100:103]
	v_mfma_f32_16x16x32_bf16 v[96:99], v[136:139], v[206:209], v[96:99]
	v_mfma_f32_16x16x32_bf16 v[124:127], v[132:135], v[148:151], v[124:127]
	v_mfma_f32_16x16x32_bf16 v[120:123], v[140:143], v[148:151], v[120:123]
	v_mfma_f32_16x16x32_bf16 v[116:119], v[132:135], v[194:197], v[116:119]
	v_mfma_f32_16x16x32_bf16 v[112:115], v[140:143], v[194:197], v[112:115]
	v_mfma_f32_16x16x32_bf16 v[108:111], v[132:135], v[202:205], v[108:111]
	v_mfma_f32_16x16x32_bf16 v[104:107], v[140:143], v[202:205], v[104:107]
	v_mfma_f32_16x16x32_bf16 v[100:103], v[132:135], v[210:213], v[100:103]
	v_mfma_f32_16x16x32_bf16 v[96:99], v[140:143], v[210:213], v[96:99]
	s_barrier
	ds_read_b128 v[214:217], v226 offset:49152
	ds_read_b128 v[230:233], v226 offset:50176
	ds_read_b128 v[234:237], v226 offset:51200
	ds_read_b128 v[238:241], v226 offset:52224
	s_add_i32 s26, 0, 0x1c000
	s_add_i32 s20, s43, s31
	s_add_i32 m0, s20, 0xffffff80
	s_nop 0
	global_load_lds_dwordx4 v188, s[24:25] offset:128
	s_add_i32 m0, s20, 0x1f80
	s_nop 0
	global_load_lds_dwordx4 v186, s[24:25] offset:128
	s_waitcnt lgkmcnt(0)
	s_barrier
	v_mfma_f32_16x16x32_bf16 v[60:63], v[214:217], v[144:147], v[60:63]
	v_mfma_f32_16x16x32_bf16 v[56:59], v[234:237], v[144:147], v[56:59]
	v_mfma_f32_16x16x32_bf16 v[52:55], v[214:217], v[152:155], v[52:55]
	v_mfma_f32_16x16x32_bf16 v[48:51], v[234:237], v[152:155], v[48:51]
	v_mfma_f32_16x16x32_bf16 v[44:47], v[214:217], v[198:201], v[44:47]
	v_mfma_f32_16x16x32_bf16 v[40:43], v[234:237], v[198:201], v[40:43]
	v_mfma_f32_16x16x32_bf16 v[36:39], v[214:217], v[206:209], v[36:39]
	v_mfma_f32_16x16x32_bf16 v[32:35], v[234:237], v[206:209], v[32:35]
	v_mfma_f32_16x16x32_bf16 v[60:63], v[230:233], v[148:151], v[60:63]
	s_add_i32 m0, s38, 0xffffff80
	v_mfma_f32_16x16x32_bf16 v[56:59], v[238:241], v[148:151], v[56:59]
	v_mfma_f32_16x16x32_bf16 v[52:55], v[230:233], v[194:197], v[52:55]
	v_mfma_f32_16x16x32_bf16 v[48:51], v[238:241], v[194:197], v[48:51]
	v_mfma_f32_16x16x32_bf16 v[44:47], v[230:233], v[202:205], v[44:47]
	v_mfma_f32_16x16x32_bf16 v[40:43], v[238:241], v[202:205], v[40:43]
	v_mfma_f32_16x16x32_bf16 v[36:39], v[230:233], v[210:213], v[36:39]
	v_mfma_f32_16x16x32_bf16 v[32:35], v[238:241], v[210:213], v[32:35]
	s_barrier
	ds_read_b128 v[144:147], v228 offset:49152
	ds_read_b128 v[148:151], v228 offset:50176
	ds_read_b128 v[152:155], v228 offset:51200
	ds_read_b128 v[194:197], v228 offset:52224
	ds_read_b128 v[198:201], v228 offset:53248
	ds_read_b128 v[202:205], v228 offset:54272
	ds_read_b128 v[206:209], v228 offset:55296
	ds_read_b128 v[210:213], v228 offset:56320
	global_load_lds_dwordx4 v188, s[100:101] offset:128
	s_add_i32 m0, s39, 0xffffff80
	s_nop 0
	global_load_lds_dwordx4 v186, s[100:101] offset:128
	s_waitcnt lgkmcnt(0)
	s_barrier
; #define PG8_STAGE(bufoff, gbase) do { _Pragma("unroll") for (int _i = 0; _i < 2; ++_i) \
;         __builtin_amdgcn_global_load_lds((const unsigned*)((const char*)(gbase) + voff[_i]), (LAS unsigned*)(lds + (bufoff) + ldsw + _i * 8192), 16, 0, 0); } while (0)
; #define PG8_MMA(ai, bj, At, Bt) do { __builtin_amdgcn_s_setprio(1); _Pragma("unroll") for (int m = 0; m < 4; ++m) _Pragma("unroll") for (int n = 0; n < 2; ++n) _Pragma("unroll") for (int k = 0; k < 2; ++k) \
;         acc[ai][bj][m][n] = __builtin_amdgcn_mfma_f32_16x16x32_bf16(Bt[n][k], At[m][k], acc[ai][bj][m][n], 0, 0, 0); __builtin_amdgcn_s_setprio(0); } while (0)
; #define PG8_WAIT_V(n) asm volatile("s_waitcnt vmcnt(" #n ")" ::: "memory")
; #define PG8_WAIT_L(n) asm volatile("s_waitcnt lgkmcnt(" #n ")" ::: "memory")
; #define PG8_BAR __builtin_amdgcn_s_barrier()
; #define PG8_SCHED __builtin_amdgcn_sched_barrier(0)
; template <class Epi>
; DI void gemm_phase(LAS unsigned char* lds, const Gemm g, const StaticOrder& S, const Epi& E) {
;     ...
;             PG8_BAR; PG8_WAIT_L(0); PG8_MMA(1, 0, At, B0); PG8_BAR; PG8_SCHED;
;             PG8_STAGE(PG8_SB(1, 1), b3 + hstep);
;             PG8_WAIT_V(6); PG8_BAR; PG8_MMA(1, 1, At, B1); PG8_BAR;
;     template <bool LN, int BJ> DI void load_gb(unsigned col0, f32x4 (&gv)[2], f32x4 (&bv)[2]) const {
; #pragma unroll
;         for (int n = 0; n < 2; ++n) {
;             if (LN) { gv[n] = *(const f32x4*)(gam + col0 + BJ * HALF + n * 16) * ALPHA; bv[n] = *(const f32x4*)(bet + col0 + BJ * HALF + n * 16) * ALPHA; }
;             else { gv[n] = (f32x4){ALPHA, ALPHA, ALPHA, ALPHA}; bv[n] = (f32x4){0.f, 0.f, 0.f, 0.f}; }
;         }
;     }
;     template <bool LN> DI void run(const f32x4 (&acc)[2][2][4][2], const Unit& u, int wr, int wc, int fr, int fq) const {
;         const unsigned row0 = u.pm * BM + wr * 64 + fr, col0 = u.pn * BM + wc * 32 + 4 * fq;
;         f32x4 gv[2], bv[2];
;         load_gb<LN, 0>(col0, gv, bv);
;         batch<LN, 0, 0, 4>(acc, row0, col0, gv, bv);
	v_mfma_f32_16x16x32_bf16 v[92:95], v[128:131], v[144:147], v[92:95]
	v_mfma_f32_16x16x32_bf16 v[88:91], v[136:139], v[144:147], v[88:91]
	v_mfma_f32_16x16x32_bf16 v[84:87], v[128:131], v[152:155], v[84:87]
	v_mfma_f32_16x16x32_bf16 v[80:83], v[136:139], v[152:155], v[80:83]
	v_mfma_f32_16x16x32_bf16 v[76:79], v[128:131], v[198:201], v[76:79]
	v_mfma_f32_16x16x32_bf16 v[72:75], v[136:139], v[198:201], v[72:75]
	v_mfma_f32_16x16x32_bf16 v[68:71], v[128:131], v[206:209], v[68:71]
	v_mfma_f32_16x16x32_bf16 v[64:67], v[136:139], v[206:209], v[64:67]
	v_mfma_f32_16x16x32_bf16 v[92:95], v[132:135], v[148:151], v[92:95]
	v_mfma_f32_16x16x32_bf16 v[88:91], v[140:143], v[148:151], v[88:91]
	v_mfma_f32_16x16x32_bf16 v[84:87], v[132:135], v[194:197], v[84:87]
	v_mfma_f32_16x16x32_bf16 v[80:83], v[140:143], v[194:197], v[80:83]
	v_mfma_f32_16x16x32_bf16 v[76:79], v[132:135], v[202:205], v[76:79]
	v_mfma_f32_16x16x32_bf16 v[72:75], v[140:143], v[202:205], v[72:75]
	v_mfma_f32_16x16x32_bf16 v[68:71], v[132:135], v[210:213], v[68:71]
	v_mfma_f32_16x16x32_bf16 v[64:67], v[140:143], v[210:213], v[64:67]
	s_barrier
	s_add_u32 s20, s24, 0x90080
	s_addc_u32 s21, s25, 0
	s_add_i32 s24, s26, s31
	s_mov_b32 m0, s24
	s_nop 0
	global_load_lds_dwordx4 v188, s[20:21]
	s_add_i32 m0, s24, 0x2000
	s_nop 0
	global_load_lds_dwordx4 v186, s[20:21]
	s_waitcnt vmcnt(6)
	s_barrier
	v_mfma_f32_16x16x32_bf16 v[28:31], v[214:217], v[144:147], v[28:31]
	v_mfma_f32_16x16x32_bf16 v[24:27], v[234:237], v[144:147], v[24:27]
	v_mfma_f32_16x16x32_bf16 v[20:23], v[214:217], v[152:155], v[20:23]
	v_mfma_f32_16x16x32_bf16 v[16:19], v[234:237], v[152:155], v[16:19]
	v_mfma_f32_16x16x32_bf16 v[12:15], v[214:217], v[198:201], v[12:15]
	v_mfma_f32_16x16x32_bf16 v[8:11], v[234:237], v[198:201], v[8:11]
	v_mfma_f32_16x16x32_bf16 v[4:7], v[214:217], v[206:209], v[4:7]
	v_mfma_f32_16x16x32_bf16 v[0:3], v[234:237], v[206:209], v[0:3]
	v_mfma_f32_16x16x32_bf16 v[28:31], v[230:233], v[148:151], v[28:31]
	s_add_i32 s33, s33, 2
	v_mfma_f32_16x16x32_bf16 v[24:27], v[238:241], v[148:151], v[24:27]
	s_add_u32 s4, s4, 0x100
	v_mfma_f32_16x16x32_bf16 v[20:23], v[230:233], v[194:197], v[20:23]
	s_addc_u32 s5, s5, 0
	v_mfma_f32_16x16x32_bf16 v[16:19], v[238:241], v[194:197], v[16:19]
	s_cmp_gt_u32 s33, 33
	v_mfma_f32_16x16x32_bf16 v[12:15], v[230:233], v[202:205], v[12:15]
	s_mov_b64 s[20:21], s[22:23]
	v_mfma_f32_16x16x32_bf16 v[8:11], v[238:241], v[202:205], v[8:11]
	v_mfma_f32_16x16x32_bf16 v[4:7], v[230:233], v[210:213], v[4:7]
	v_mfma_f32_16x16x32_bf16 v[0:3], v[238:241], v[210:213], v[0:3]
	s_barrier
	s_cbranch_scc0 .LBB0_77
	v_lshl_add_u32 v206, s3, 8, v225
	v_lshl_or_b32 v158, s2, 8, v227
	v_lshlrev_b32_e32 v232, 11, v206
	s_andn2_b64 vcc, exec, s[14:15]
	v_or_b32_e32 v231, 16, v158
	v_add_u32_e32 v194, v232, v158
	v_or_b32_e32 v230, 0x80, v158
	v_or_b32_e32 v229, 0x90, v158
	s_cbranch_vccnz .LBB0_80
	v_lshlrev_b64 v[132:133], 2, v[158:159]
	v_lshl_add_u64 v[140:141], s[16:17], 0, v[132:133]
	global_load_dwordx4 v[128:131], v[140:141], off
	v_lshl_add_u64 v[142:143], s[18:19], 0, v[132:133]
	v_readlane_b32 s2, v253, 8
	v_mov_b32_e32 v195, v159
	v_lshlrev_b32_e32 v136, 1, v206
	v_mov_b32_e32 v137, v159
	v_readlane_b32 s3, v253, 9
	v_lshlrev_b64 v[212:213], 2, v[194:195]
	v_add_u32_e32 v146, v232, v231
	v_lshl_add_u64 v[144:145], v[136:137], 2, s[2:3]
	v_lshl_add_u64 v[136:137], s[88:89], 0, v[212:213]
	v_mov_b32_e32 v147, v159
	v_lshl_add_u64 v[146:147], v[146:147], 2, s[88:89]
	v_or_b32_e32 v195, 16, v206
	v_mov_b32_e32 v201, v159
	v_mov_b32_e32 v209, v159
	v_lshl_add_u64 v[212:213], s[90:91], 0, v[212:213]
	s_waitcnt vmcnt(0)
	v_pk_mul_f32 v[152:153], v[130:131], s[78:79] op_sel_hi:[1,0]
	v_pk_mul_f32 v[154:155], v[128:129], s[78:79] op_sel_hi:[1,0]
	global_load_dwordx4 v[132:135], v[142:143], off
	global_load_dwordx4 v[128:131], v[140:141], off offset:64
	global_load_dwordx2 v[204:205], v[144:145], off
	global_load_dwordx4 v[196:199], v[146:147], off
	v_lshlrev_b32_e32 v146, 1, v195
	global_load_dwordx4 v[136:139], v[136:137], off
	v_lshlrev_b32_e32 v195, 11, v195
	v_mov_b32_e32 v147, v159
	v_add_u32_e32 v200, v195, v158
	v_lshl_add_u64 v[146:147], v[146:147], 2, s[2:3]
	v_lshl_add_u64 v[200:201], v[200:201], 2, s[88:89]
	global_load_dwordx2 v[214:215], v[146:147], off
	v_add_u32_e32 v208, v195, v231
	global_load_dwordx4 v[200:203], v[200:201], off
	v_lshl_add_u64 v[208:209], v[208:209], 2, s[88:89]
	global_load_dwordx4 v[208:211], v[208:209], off
	s_waitcnt vmcnt(0)
	v_pk_mul_f32 v[148:149], v[130:131], s[78:79] op_sel_hi:[1,0]
	v_pk_mul_f32 v[150:151], v[128:129], s[78:79] op_sel_hi:[1,0]
	global_load_dwordx4 v[128:131], v[142:143], off offset:64
	v_sub_f32_e32 v137, v137, v204
	v_sub_f32_e32 v136, v136, v204
	v_sub_f32_e32 v139, v139, v204
	v_sub_f32_e32 v138, v138, v204
	v_pk_mul_f32 v[138:139], v[204:205], v[138:139] op_sel:[1,0]
	v_pk_mul_f32 v[136:137], v[204:205], v[136:137] op_sel:[1,0]
	v_pk_fma_f32 v[138:139], v[152:153], v[138:139], v[126:127]
	v_pk_fma_f32 v[136:137], v[154:155], v[136:137], v[124:125]
	v_pk_fma_f32 v[138:139], v[134:135], s[78:79], v[138:139] op_sel_hi:[1,0,1]
	v_pk_fma_f32 v[136:137], v[132:133], s[78:79], v[136:137] op_sel_hi:[1,0,1]
	global_store_dwordx4 v[212:213], v[136:139], off
	s_nop 1
	v_sub_f32_e32 v137, v197, v204
	v_sub_f32_e32 v136, v196, v204
	v_sub_f32_e32 v139, v199, v204
	v_sub_f32_e32 v138, v198, v204
	v_pk_mul_f32 v[138:139], v[204:205], v[138:139] op_sel:[1,0]
	v_pk_mul_f32 v[136:137], v[204:205], v[136:137] op_sel:[1,0]
	v_pk_fma_f32 v[138:139], v[148:149], v[138:139], v[122:123]
	v_pk_fma_f32 v[136:137], v[150:151], v[136:137], v[120:121]
	v_or_b32_e32 v196, 16, v194
	v_mov_b32_e32 v197, v159
	v_lshl_add_u64 v[196:197], v[196:197], 2, s[90:91]
	s_waitcnt vmcnt(0)
;     template <bool LN, int BJ, int LO, int HI> DI void batch(const f32x4 (&acc)[2][2][4][2], unsigned row0, unsigned col0, const f32x4 (&gv)[2], const f32x4 (&bv)[2]) const {
;         f32x4 r[HI - LO]; float mean[(HI - LO) / 2], rstd[(HI - LO) / 2];
; #pragma unroll
;         for (int i = LO; i < HI; ++i) { const int ai = i >> 3, m = (i >> 1) & 3, n = i & 1; const unsigned row = row0 + ai * HALF + m * 16;
;             if (n == 0) { mean[(i - LO) >> 1] = 0.f; rstd[(i - LO) >> 1] = 1.f;
;                 if (LN) { const float2 st = *(const float2*)(stats + row * 2u); mean[(i - LO) >> 1] = st.x; rstd[(i - LO) >> 1] = st.y; } }
;             r[i - LO] = *(const f32x4*)(src + (row * (unsigned)DM + col0 + BJ * HALF + n * 16)); }
; #pragma unroll
;         for (int i = LO; i < HI; ++i) { const int ai = i >> 3, m = (i >> 1) & 3, n = i & 1; const unsigned row = row0 + ai * HALF + m * 16;
;             *(f32x4*)(Y + (row * (unsigned)DM + col0 + BJ * HALF + n * 16)) = acc[ai][BJ][m][n] + ((r[i - LO] - mean[(i - LO) >> 1]) * rstd[(i - LO) >> 1]) * gv[n] + bv[n]; }
	v_pk_fma_f32 v[138:139], v[130:131], s[78:79], v[138:139] op_sel_hi:[1,0,1]
	v_pk_fma_f32 v[136:137], v[128:129], s[78:79], v[136:137] op_sel_hi:[1,0,1]
	global_store_dwordx4 v[196:197], v[136:139], off
	v_add_u32_e32 v196, 0x8000, v194
	v_mov_b32_e32 v197, v159
	v_sub_f32_e32 v137, v201, v214
	v_sub_f32_e32 v136, v200, v214
	v_sub_f32_e32 v139, v203, v214
	v_sub_f32_e32 v138, v202, v214
	v_pk_mul_f32 v[138:139], v[214:215], v[138:139] op_sel:[1,0]
	v_pk_mul_f32 v[136:137], v[214:215], v[136:137] op_sel:[1,0]
	v_pk_fma_f32 v[138:139], v[152:153], v[138:139], v[118:119]
	v_pk_fma_f32 v[136:137], v[154:155], v[136:137], v[116:117]
	v_pk_fma_f32 v[138:139], v[134:135], s[78:79], v[138:139] op_sel_hi:[1,0,1]
	v_pk_fma_f32 v[136:137], v[132:133], s[78:79], v[136:137] op_sel_hi:[1,0,1]
	v_lshl_add_u64 v[196:197], v[196:197], 2, s[90:91]
	global_store_dwordx4 v[196:197], v[136:139], off
	v_add_u32_e32 v196, 0x8010, v194
	v_mov_b32_e32 v197, v159
	v_sub_f32_e32 v137, v209, v214
	v_sub_f32_e32 v136, v208, v214
	v_sub_f32_e32 v139, v211, v214
	v_sub_f32_e32 v138, v210, v214
	v_pk_mul_f32 v[138:139], v[214:215], v[138:139] op_sel:[1,0]
	v_pk_mul_f32 v[136:137], v[214:215], v[136:137] op_sel:[1,0]
	v_pk_fma_f32 v[138:139], v[148:149], v[138:139], v[114:115]
	v_pk_fma_f32 v[136:137], v[150:151], v[136:137], v[112:113]
	v_pk_fma_f32 v[138:139], v[130:131], s[78:79], v[138:139] op_sel_hi:[1,0,1]
	v_pk_fma_f32 v[136:137], v[128:129], s[78:79], v[136:137] op_sel_hi:[1,0,1]
	v_lshl_add_u64 v[196:197], v[196:197], 2, s[90:91]
	global_store_dwordx4 v[196:197], v[136:139], off
	s_nop 1
	v_or_b32_e32 v138, 32, v206
	v_lshlrev_b32_e32 v136, 1, v138
	v_mov_b32_e32 v137, v159
	v_lshlrev_b32_e32 v236, 11, v138
	v_lshl_add_u64 v[200:201], v[136:137], 2, s[2:3]
	v_add_u32_e32 v136, v236, v158
	v_lshl_add_u64 v[136:137], v[136:137], 2, s[88:89]
	global_load_dwordx2 v[204:205], v[200:201], off
	v_add_u32_e32 v196, v236, v231
	global_load_dwordx4 v[136:139], v[136:137], off
	v_mov_b32_e32 v197, v159
	v_lshl_add_u64 v[196:197], v[196:197], 2, s[88:89]
	global_load_dwordx4 v[196:199], v[196:197], off
	v_or_b32_e32 v207, 48, v206
	v_lshlrev_b32_e32 v235, 11, v207
	v_lshlrev_b32_e32 v202, 1, v207
	v_mov_b32_e32 v203, v159
	v_add_u32_e32 v208, v235, v158
	v_mov_b32_e32 v209, v159
	v_lshl_add_u64 v[202:203], v[202:203], 2, s[2:3]
	v_lshl_add_u64 v[208:209], v[208:209], 2, s[88:89]
	global_load_dwordx2 v[216:217], v[202:203], off
	v_add_u32_e32 v212, v235, v231
	global_load_dwordx4 v[208:211], v[208:209], off
	v_mov_b32_e32 v213, v159
	v_lshl_add_u64 v[212:213], v[212:213], 2, s[88:89]
	global_load_dwordx4 v[212:215], v[212:213], off
	v_add_u32_e32 v218, 0x10000, v194
	v_mov_b32_e32 v219, v159
	v_lshl_add_u64 v[218:219], v[218:219], 2, s[90:91]
	s_waitcnt vmcnt(0)
	v_sub_f32_e32 v137, v137, v204
	v_sub_f32_e32 v136, v136, v204
	v_sub_f32_e32 v139, v139, v204
	v_sub_f32_e32 v138, v138, v204
	v_pk_mul_f32 v[138:139], v[204:205], v[138:139] op_sel:[1,0]
	v_pk_mul_f32 v[136:137], v[204:205], v[136:137] op_sel:[1,0]
	v_pk_fma_f32 v[138:139], v[152:153], v[138:139], v[110:111]
	v_pk_fma_f32 v[136:137], v[154:155], v[136:137], v[108:109]
	v_pk_fma_f32 v[138:139], v[134:135], s[78:79], v[138:139] op_sel_hi:[1,0,1]
	v_pk_fma_f32 v[136:137], v[132:133], s[78:79], v[136:137] op_sel_hi:[1,0,1]
	global_store_dwordx4 v[218:219], v[136:139], off
	s_nop 1
	v_sub_f32_e32 v137, v197, v204
	v_sub_f32_e32 v136, v196, v204
	v_sub_f32_e32 v139, v199, v204
	v_sub_f32_e32 v138, v198, v204
	v_pk_mul_f32 v[138:139], v[204:205], v[138:139] op_sel:[1,0]
	v_pk_mul_f32 v[136:137], v[204:205], v[136:137] op_sel:[1,0]
	v_pk_fma_f32 v[138:139], v[148:149], v[138:139], v[106:107]
	v_pk_fma_f32 v[136:137], v[150:151], v[136:137], v[104:105]
	v_add_u32_e32 v196, 0x10010, v194
	v_mov_b32_e32 v197, v159
	v_pk_fma_f32 v[138:139], v[130:131], s[78:79], v[138:139] op_sel_hi:[1,0,1]
	v_pk_fma_f32 v[136:137], v[128:129], s[78:79], v[136:137] op_sel_hi:[1,0,1]
	v_lshl_add_u64 v[196:197], v[196:197], 2, s[90:91]
	global_store_dwordx4 v[196:197], v[136:139], off
	v_add_u32_e32 v196, 0x18000, v194
	v_mov_b32_e32 v197, v159
	v_sub_f32_e32 v137, v209, v216
	v_sub_f32_e32 v136, v208, v216
	v_sub_f32_e32 v139, v211, v216
	v_sub_f32_e32 v138, v210, v216
	v_pk_mul_f32 v[138:139], v[216:217], v[138:139] op_sel:[1,0]
	v_pk_mul_f32 v[136:137], v[216:217], v[136:137] op_sel:[1,0]
	v_pk_fma_f32 v[138:139], v[152:153], v[138:139], v[102:103]
	v_pk_fma_f32 v[136:137], v[154:155], v[136:137], v[100:101]
	v_pk_fma_f32 v[138:139], v[134:135], s[78:79], v[138:139] op_sel_hi:[1,0,1]
	v_pk_fma_f32 v[136:137], v[132:133], s[78:79], v[136:137] op_sel_hi:[1,0,1]
	v_lshl_add_u64 v[196:197], v[196:197], 2, s[90:91]
	global_store_dwordx4 v[196:197], v[136:139], off
	v_add_u32_e32 v196, 0x18010, v194
	v_mov_b32_e32 v197, v159
	v_sub_f32_e32 v137, v213, v216
	v_sub_f32_e32 v136, v212, v216
	v_sub_f32_e32 v139, v215, v216
	v_sub_f32_e32 v138, v214, v216
	v_pk_mul_f32 v[138:139], v[216:217], v[138:139] op_sel:[1,0]
	v_pk_mul_f32 v[136:137], v[216:217], v[136:137] op_sel:[1,0]
	v_pk_fma_f32 v[138:139], v[148:149], v[138:139], v[98:99]
	v_pk_fma_f32 v[136:137], v[150:151], v[136:137], v[96:97]
	v_pk_fma_f32 v[138:139], v[130:131], s[78:79], v[138:139] op_sel_hi:[1,0,1]
	v_pk_fma_f32 v[136:137], v[128:129], s[78:79], v[136:137] op_sel_hi:[1,0,1]
	v_lshl_add_u64 v[196:197], v[196:197], 2, s[90:91]
	global_store_dwordx4 v[196:197], v[136:139], off
	s_nop 1
	v_add_u32_e32 v138, 0x80, v206
	v_lshlrev_b32_e32 v136, 1, v138
	v_mov_b32_e32 v137, v159
	v_lshlrev_b32_e32 v233, 11, v138
	v_lshl_add_u64 v[196:197], v[136:137], 2, s[2:3]
	v_add_u32_e32 v136, v233, v158
	v_lshl_add_u64 v[136:137], v[136:137], 2, s[88:89]
	global_load_dwordx2 v[204:205], v[196:197], off
	v_add_u32_e32 v198, v233, v231
	global_load_dwordx4 v[136:139], v[136:137], off
	v_mov_b32_e32 v199, v159
	v_add_u32_e32 v207, 0x90, v206
	v_lshl_add_u64 v[198:199], v[198:199], 2, s[88:89]
	v_lshlrev_b32_e32 v234, 11, v207
	global_load_dwordx4 v[208:211], v[198:199], off
	v_add_u32_e32 v212, v234, v158
	v_mov_b32_e32 v213, v159
	v_lshl_add_u64 v[212:213], v[212:213], 2, s[88:89]
	global_load_dwordx4 v[212:215], v[212:213], off
	v_lshlrev_b32_e32 v198, 1, v207
	v_mov_b32_e32 v199, v159
	v_lshl_add_u64 v[198:199], v[198:199], 2, s[2:3]
	global_load_dwordx2 v[220:221], v[198:199], off
	v_add_u32_e32 v216, v234, v231
	v_mov_b32_e32 v217, v159
	v_lshl_add_u64 v[216:217], v[216:217], 2, s[88:89]
	global_load_dwordx4 v[216:219], v[216:217], off
	v_add_u32_e32 v238, 0x40000, v194
	v_mov_b32_e32 v239, v159
	v_lshl_add_u64 v[238:239], v[238:239], 2, s[90:91]
	s_waitcnt vmcnt(0)
;     template <bool LN, int BJ, int LO, int HI> DI void batch(const f32x4 (&acc)[2][2][4][2], unsigned row0, unsigned col0, const f32x4 (&gv)[2], const f32x4 (&bv)[2]) const {
;         f32x4 r[HI - LO]; float mean[(HI - LO) / 2], rstd[(HI - LO) / 2];
; #pragma unroll
;         for (int i = LO; i < HI; ++i) { const int ai = i >> 3, m = (i >> 1) & 3, n = i & 1; const unsigned row = row0 + ai * HALF + m * 16;
;             if (n == 0) { mean[(i - LO) >> 1] = 0.f; rstd[(i - LO) >> 1] = 1.f;
;                 if (LN) { const float2 st = *(const float2*)(stats + row * 2u); mean[(i - LO) >> 1] = st.x; rstd[(i - LO) >> 1] = st.y; } }
;             r[i - LO] = *(const f32x4*)(src + (row * (unsigned)DM + col0 + BJ * HALF + n * 16)); }
; #pragma unroll
;         for (int i = LO; i < HI; ++i) { const int ai = i >> 3, m = (i >> 1) & 3, n = i & 1; const unsigned row = row0 + ai * HALF + m * 16;
;             *(f32x4*)(Y + (row * (unsigned)DM + col0 + BJ * HALF + n * 16)) = acc[ai][BJ][m][n] + ((r[i - LO] - mean[(i - LO) >> 1]) * rstd[(i - LO) >> 1]) * gv[n] + bv[n]; }
;         __builtin_amdgcn_sched_barrier(0);
	v_sub_f32_e32 v137, v137, v204
	v_sub_f32_e32 v136, v136, v204
	v_sub_f32_e32 v139, v139, v204
	v_sub_f32_e32 v138, v138, v204
	v_pk_mul_f32 v[138:139], v[204:205], v[138:139] op_sel:[1,0]
	v_pk_mul_f32 v[136:137], v[204:205], v[136:137] op_sel:[1,0]
	v_pk_fma_f32 v[138:139], v[152:153], v[138:139], v[94:95]
	v_pk_fma_f32 v[136:137], v[154:155], v[136:137], v[92:93]
	v_pk_fma_f32 v[138:139], v[134:135], s[78:79], v[138:139] op_sel_hi:[1,0,1]
	v_pk_fma_f32 v[136:137], v[132:133], s[78:79], v[136:137] op_sel_hi:[1,0,1]
	global_store_dwordx4 v[238:239], v[136:139], off
	s_nop 1
	v_sub_f32_e32 v137, v209, v204
	v_sub_f32_e32 v136, v208, v204
	v_sub_f32_e32 v139, v211, v204
	v_sub_f32_e32 v138, v210, v204
	v_pk_mul_f32 v[138:139], v[204:205], v[138:139] op_sel:[1,0]
	v_pk_mul_f32 v[136:137], v[204:205], v[136:137] op_sel:[1,0]
	v_pk_fma_f32 v[138:139], v[148:149], v[138:139], v[90:91]
	v_pk_fma_f32 v[136:137], v[150:151], v[136:137], v[88:89]
	v_add_u32_e32 v204, 0x40010, v194
	v_mov_b32_e32 v205, v159
	v_pk_fma_f32 v[138:139], v[130:131], s[78:79], v[138:139] op_sel_hi:[1,0,1]
	v_pk_fma_f32 v[136:137], v[128:129], s[78:79], v[136:137] op_sel_hi:[1,0,1]
	v_lshl_add_u64 v[204:205], v[204:205], 2, s[90:91]
	global_store_dwordx4 v[204:205], v[136:139], off
	v_add_u32_e32 v204, 0x48000, v194
	v_mov_b32_e32 v205, v159
	v_sub_f32_e32 v137, v213, v220
	v_sub_f32_e32 v136, v212, v220
	v_sub_f32_e32 v139, v215, v220
	v_sub_f32_e32 v138, v214, v220
	v_pk_mul_f32 v[138:139], v[220:221], v[138:139] op_sel:[1,0]
	v_pk_mul_f32 v[136:137], v[220:221], v[136:137] op_sel:[1,0]
	v_pk_fma_f32 v[138:139], v[152:153], v[138:139], v[86:87]
	v_pk_fma_f32 v[136:137], v[154:155], v[136:137], v[84:85]
	v_pk_fma_f32 v[138:139], v[134:135], s[78:79], v[138:139] op_sel_hi:[1,0,1]
	v_pk_fma_f32 v[136:137], v[132:133], s[78:79], v[136:137] op_sel_hi:[1,0,1]
	v_lshl_add_u64 v[204:205], v[204:205], 2, s[90:91]
	global_store_dwordx4 v[204:205], v[136:139], off
	v_add_u32_e32 v204, 0x48010, v194
	v_mov_b32_e32 v205, v159
	v_sub_f32_e32 v137, v217, v220
	v_sub_f32_e32 v136, v216, v220
	v_sub_f32_e32 v139, v219, v220
	v_sub_f32_e32 v138, v218, v220
	v_pk_mul_f32 v[138:139], v[220:221], v[138:139] op_sel:[1,0]
	v_pk_mul_f32 v[136:137], v[220:221], v[136:137] op_sel:[1,0]
	v_pk_fma_f32 v[138:139], v[148:149], v[138:139], v[82:83]
	v_pk_fma_f32 v[136:137], v[150:151], v[136:137], v[80:81]
	v_pk_fma_f32 v[138:139], v[130:131], s[78:79], v[138:139] op_sel_hi:[1,0,1]
	v_pk_fma_f32 v[136:137], v[128:129], s[78:79], v[136:137] op_sel_hi:[1,0,1]
	v_lshl_add_u64 v[204:205], v[204:205], 2, s[90:91]
	global_store_dwordx4 v[204:205], v[136:139], off
	s_nop 1
	v_add_u32_e32 v138, 0xa0, v206
	v_lshlrev_b32_e32 v136, 1, v138
	v_mov_b32_e32 v137, v159
	v_lshlrev_b32_e32 v237, 11, v138
	v_lshl_add_u64 v[204:205], v[136:137], 2, s[2:3]
	v_add_u32_e32 v136, v237, v158
	v_lshl_add_u64 v[136:137], v[136:137], 2, s[88:89]
	global_load_dwordx2 v[220:221], v[204:205], off
	v_add_u32_e32 v208, v237, v231
	global_load_dwordx4 v[136:139], v[136:137], off
	v_mov_b32_e32 v209, v159
	v_lshl_add_u64 v[208:209], v[208:209], 2, s[88:89]
	global_load_dwordx4 v[212:215], v[208:209], off
	v_add_u32_e32 v208, 0xb0, v206
	v_lshlrev_b32_e32 v206, 1, v208
	v_mov_b32_e32 v207, v159
	v_lshlrev_b32_e32 v238, 11, v208
	v_lshl_add_u64 v[210:211], v[206:207], 2, s[2:3]
	v_add_u32_e32 v206, v238, v158
	v_lshl_add_u64 v[206:207], v[206:207], 2, s[88:89]
	global_load_dwordx2 v[240:241], v[210:211], off
	v_add_u32_e32 v216, v238, v231
	global_load_dwordx4 v[206:209], v[206:207], off
	v_mov_b32_e32 v217, v159
	v_lshl_add_u64 v[216:217], v[216:217], 2, s[88:89]
	global_load_dwordx4 v[216:219], v[216:217], off
	v_add_u32_e32 v242, 0x50000, v194
	v_mov_b32_e32 v243, v159
	v_lshl_add_u64 v[242:243], v[242:243], 2, s[90:91]
	s_waitcnt vmcnt(0)
	v_sub_f32_e32 v137, v137, v220
	v_sub_f32_e32 v136, v136, v220
	v_sub_f32_e32 v139, v139, v220
	v_sub_f32_e32 v138, v138, v220
	v_pk_mul_f32 v[138:139], v[220:221], v[138:139] op_sel:[1,0]
	v_pk_mul_f32 v[136:137], v[220:221], v[136:137] op_sel:[1,0]
	v_pk_fma_f32 v[138:139], v[152:153], v[138:139], v[78:79]
	v_pk_fma_f32 v[136:137], v[154:155], v[136:137], v[76:77]
	v_pk_fma_f32 v[138:139], v[134:135], s[78:79], v[138:139] op_sel_hi:[1,0,1]
	v_pk_fma_f32 v[136:137], v[132:133], s[78:79], v[136:137] op_sel_hi:[1,0,1]
	global_store_dwordx4 v[242:243], v[136:139], off
	s_nop 1
	v_sub_f32_e32 v137, v213, v220
	v_sub_f32_e32 v136, v212, v220
	v_sub_f32_e32 v139, v215, v220
	v_sub_f32_e32 v138, v214, v220
	v_pk_mul_f32 v[138:139], v[220:221], v[138:139] op_sel:[1,0]
	v_pk_mul_f32 v[136:137], v[220:221], v[136:137] op_sel:[1,0]
	v_pk_fma_f32 v[138:139], v[148:149], v[138:139], v[74:75]
	v_pk_fma_f32 v[136:137], v[150:151], v[136:137], v[72:73]
	v_add_u32_e32 v212, 0x50010, v194
	v_mov_b32_e32 v213, v159
	v_pk_fma_f32 v[138:139], v[130:131], s[78:79], v[138:139] op_sel_hi:[1,0,1]
	v_pk_fma_f32 v[136:137], v[128:129], s[78:79], v[136:137] op_sel_hi:[1,0,1]
	v_lshl_add_u64 v[212:213], v[212:213], 2, s[90:91]
	global_store_dwordx4 v[212:213], v[136:139], off
	s_nop 1
	v_sub_f32_e32 v137, v207, v240
	v_sub_f32_e32 v136, v206, v240
	v_sub_f32_e32 v139, v209, v240
	v_sub_f32_e32 v138, v208, v240
	v_pk_mul_f32 v[136:137], v[240:241], v[136:137] op_sel:[1,0]
	v_pk_mul_f32 v[138:139], v[240:241], v[138:139] op_sel:[1,0]
	v_pk_fma_f32 v[136:137], v[154:155], v[136:137], v[68:69]
	v_pk_fma_f32 v[138:139], v[152:153], v[138:139], v[70:71]
	v_pk_fma_f32 v[132:133], v[132:133], s[78:79], v[136:137] op_sel_hi:[1,0,1]
	v_add_u32_e32 v136, 0x58000, v194
	v_mov_b32_e32 v137, v159
	v_pk_fma_f32 v[134:135], v[134:135], s[78:79], v[138:139] op_sel_hi:[1,0,1]
	v_lshl_add_u64 v[136:137], v[136:137], 2, s[90:91]
	global_store_dwordx4 v[136:137], v[132:135], off
	s_nop 1
	v_sub_f32_e32 v133, v217, v240
	v_sub_f32_e32 v132, v216, v240
	v_sub_f32_e32 v135, v219, v240
	v_sub_f32_e32 v134, v218, v240
	v_pk_mul_f32 v[132:133], v[240:241], v[132:133] op_sel:[1,0]
	v_pk_mul_f32 v[134:135], v[240:241], v[134:135] op_sel:[1,0]
	v_pk_fma_f32 v[132:133], v[150:151], v[132:133], v[64:65]
	v_pk_fma_f32 v[134:135], v[148:149], v[134:135], v[66:67]
	v_pk_fma_f32 v[128:129], v[128:129], s[78:79], v[132:133] op_sel_hi:[1,0,1]
	v_add_u32_e32 v132, 0x58010, v194
	v_mov_b32_e32 v133, v159
	v_pk_fma_f32 v[130:131], v[130:131], s[78:79], v[134:135] op_sel_hi:[1,0,1]
	v_lshl_add_u64 v[132:133], v[132:133], 2, s[90:91]
	global_store_dwordx4 v[132:133], v[128:131], off
	global_load_dwordx4 v[128:131], v[140:141], off offset:512
	v_add_u32_e32 v136, v232, v230
	v_mov_b32_e32 v137, v159
	v_lshl_add_u64 v[136:137], v[136:137], 2, s[88:89]
	s_waitcnt vmcnt(0)
;     template <bool LN, int BJ> DI void load_gb(unsigned col0, f32x4 (&gv)[2], f32x4 (&bv)[2]) const {
; #pragma unroll
;         for (int n = 0; n < 2; ++n) {
;             if (LN) { gv[n] = *(const f32x4*)(gam + col0 + BJ * HALF + n * 16) * ALPHA; bv[n] = *(const f32x4*)(bet + col0 + BJ * HALF + n * 16) * ALPHA; }
;             else { gv[n] = (f32x4){ALPHA, ALPHA, ALPHA, ALPHA}; bv[n] = (f32x4){0.f, 0.f, 0.f, 0.f}; }
;         }
;     }
;     template <bool LN> DI void run(const f32x4 (&acc)[2][2][4][2], const Unit& u, int wr, int wc, int fr, int fq) const {
;         const unsigned row0 = u.pm * BM + wr * 64 + fr, col0 = u.pn * BM + wc * 32 + 4 * fq;
;         f32x4 gv[2], bv[2];
;         load_gb<LN, 0>(col0, gv, bv);
;         batch<LN, 0, 0, 4>(acc, row0, col0, gv, bv);
;         batch<LN, 0, 4, 8>(acc, row0, col0, gv, bv);
;         batch<LN, 0, 8, 12>(acc, row0, col0, gv, bv);
;         batch<LN, 0, 12, 16>(acc, row0, col0, gv, bv);
;         load_gb<LN, 1>(col0, gv, bv);
;         batch<LN, 1, 0, 8>(acc, row0, col0, gv, bv);
;         batch<LN, 1, 8, 16>(acc, row0, col0, gv, bv);
	v_pk_mul_f32 v[212:213], v[130:131], s[78:79] op_sel_hi:[1,0]
	v_pk_mul_f32 v[214:215], v[128:129], s[78:79] op_sel_hi:[1,0]
	global_load_dwordx4 v[132:135], v[142:143], off offset:512
	global_load_dwordx4 v[128:131], v[140:141], off offset:576
	s_waitcnt vmcnt(0)
	v_pk_mul_f32 v[206:207], v[130:131], s[78:79] op_sel_hi:[1,0]
	v_pk_mul_f32 v[208:209], v[128:129], s[78:79] op_sel_hi:[1,0]
	global_load_dwordx4 v[128:131], v[142:143], off offset:576
	global_load_dwordx2 v[220:221], v[144:145], off
	global_load_dwordx4 v[240:243], v[136:137], off
	v_add_u32_e32 v136, v232, v229
	v_mov_b32_e32 v137, v159
	v_lshl_add_u64 v[136:137], v[136:137], 2, s[88:89]
	global_load_dwordx4 v[244:247], v[136:137], off
	global_load_dwordx2 v[218:219], v[146:147], off
	v_add_u32_e32 v136, v195, v230
	v_mov_b32_e32 v137, v159
	v_lshl_add_u64 v[136:137], v[136:137], 2, s[88:89]
	global_load_dwordx4 v[248:251], v[136:137], off
	v_add_u32_e32 v136, v195, v229
	v_mov_b32_e32 v137, v159
	v_lshl_add_u64 v[136:137], v[136:137], 2, s[88:89]
	global_load_dwordx4 v[152:155], v[136:137], off
	global_load_dwordx2 v[216:217], v[200:201], off
	v_add_u32_e32 v136, v236, v230
	v_mov_b32_e32 v137, v159
	v_lshl_add_u64 v[136:137], v[136:137], 2, s[88:89]
	global_load_dwordx4 v[148:151], v[136:137], off
	v_add_u32_e32 v136, v236, v229
	v_mov_b32_e32 v137, v159
	v_lshl_add_u64 v[136:137], v[136:137], 2, s[88:89]
	global_load_dwordx4 v[144:147], v[136:137], off
	global_load_dwordx2 v[200:201], v[202:203], off
	v_add_u32_e32 v136, v235, v230
	v_mov_b32_e32 v137, v159
	v_lshl_add_u64 v[136:137], v[136:137], 2, s[88:89]
	global_load_dwordx4 v[140:143], v[136:137], off
	v_add_u32_e32 v136, v235, v229
	v_mov_b32_e32 v137, v159
	v_lshl_add_u64 v[136:137], v[136:137], 2, s[88:89]
	global_load_dwordx4 v[136:139], v[136:137], off
	v_add_u32_e32 v202, 0x80, v194
	v_mov_b32_e32 v203, v159
	v_lshl_add_u64 v[202:203], v[202:203], 2, s[90:91]
	s_waitcnt vmcnt(0)
	v_sub_f32_e32 v241, v241, v220
	v_sub_f32_e32 v240, v240, v220
	v_sub_f32_e32 v243, v243, v220
	v_sub_f32_e32 v242, v242, v220
	v_pk_mul_f32 v[242:243], v[220:221], v[242:243] op_sel:[1,0]
	v_pk_mul_f32 v[240:241], v[220:221], v[240:241] op_sel:[1,0]
	v_pk_fma_f32 v[242:243], v[212:213], v[242:243], v[62:63]
	v_pk_fma_f32 v[240:241], v[214:215], v[240:241], v[60:61]
	v_pk_fma_f32 v[242:243], v[134:135], s[78:79], v[242:243] op_sel_hi:[1,0,1]
	v_pk_fma_f32 v[240:241], v[132:133], s[78:79], v[240:241] op_sel_hi:[1,0,1]
	global_store_dwordx4 v[202:203], v[240:243], off
	v_sub_f32_e32 v203, v245, v220
	v_sub_f32_e32 v202, v244, v220
	v_sub_f32_e32 v241, v247, v220
	v_sub_f32_e32 v240, v246, v220
	v_pk_mul_f32 v[202:203], v[220:221], v[202:203] op_sel:[1,0]
	v_pk_mul_f32 v[240:241], v[220:221], v[240:241] op_sel:[1,0]
	v_pk_fma_f32 v[202:203], v[208:209], v[202:203], v[56:57]
	v_pk_fma_f32 v[220:221], v[206:207], v[240:241], v[58:59]
	v_pk_fma_f32 v[240:241], v[128:129], s[78:79], v[202:203] op_sel_hi:[1,0,1]
	v_add_u32_e32 v202, 0x90, v194
	v_mov_b32_e32 v203, v159
	v_pk_fma_f32 v[242:243], v[130:131], s[78:79], v[220:221] op_sel_hi:[1,0,1]
	v_lshl_add_u64 v[202:203], v[202:203], 2, s[90:91]
	global_store_dwordx4 v[202:203], v[240:243], off
	v_sub_f32_e32 v203, v249, v218
	v_sub_f32_e32 v202, v248, v218
	v_sub_f32_e32 v221, v251, v218
	v_sub_f32_e32 v220, v250, v218
	v_pk_mul_f32 v[202:203], v[218:219], v[202:203] op_sel:[1,0]
	v_pk_mul_f32 v[220:221], v[218:219], v[220:221] op_sel:[1,0]
	v_pk_fma_f32 v[202:203], v[214:215], v[202:203], v[52:53]
	v_pk_fma_f32 v[220:221], v[212:213], v[220:221], v[54:55]
	v_pk_fma_f32 v[240:241], v[132:133], s[78:79], v[202:203] op_sel_hi:[1,0,1]
	v_add_u32_e32 v202, 0x8080, v194
	v_mov_b32_e32 v203, v159
	v_sub_f32_e32 v153, v153, v218
	v_sub_f32_e32 v152, v152, v218
	v_sub_f32_e32 v155, v155, v218
	v_sub_f32_e32 v154, v154, v218
	v_pk_fma_f32 v[242:243], v[134:135], s[78:79], v[220:221] op_sel_hi:[1,0,1]
	v_lshl_add_u64 v[202:203], v[202:203], 2, s[90:91]
	v_pk_mul_f32 v[154:155], v[218:219], v[154:155] op_sel:[1,0]
	v_pk_mul_f32 v[152:153], v[218:219], v[152:153] op_sel:[1,0]
	global_store_dwordx4 v[202:203], v[240:243], off
	v_pk_fma_f32 v[152:153], v[208:209], v[152:153], v[48:49]
	v_pk_fma_f32 v[154:155], v[206:207], v[154:155], v[50:51]
	v_add_u32_e32 v202, 0x8090, v194
	v_mov_b32_e32 v203, v159
	v_sub_f32_e32 v149, v149, v216
	v_sub_f32_e32 v148, v148, v216
	v_sub_f32_e32 v151, v151, v216
	v_sub_f32_e32 v150, v150, v216
	v_pk_fma_f32 v[154:155], v[130:131], s[78:79], v[154:155] op_sel_hi:[1,0,1]
	v_pk_fma_f32 v[152:153], v[128:129], s[78:79], v[152:153] op_sel_hi:[1,0,1]
	v_lshl_add_u64 v[202:203], v[202:203], 2, s[90:91]
	v_pk_mul_f32 v[150:151], v[216:217], v[150:151] op_sel:[1,0]
	v_pk_mul_f32 v[148:149], v[216:217], v[148:149] op_sel:[1,0]
	global_store_dwordx4 v[202:203], v[152:155], off
	v_pk_fma_f32 v[148:149], v[214:215], v[148:149], v[44:45]
	v_pk_fma_f32 v[150:151], v[212:213], v[150:151], v[46:47]
	v_add_u32_e32 v152, 0x10080, v194
	v_mov_b32_e32 v153, v159
	v_sub_f32_e32 v145, v145, v216
	v_sub_f32_e32 v144, v144, v216
	v_sub_f32_e32 v147, v147, v216
	v_sub_f32_e32 v146, v146, v216
	v_pk_fma_f32 v[150:151], v[134:135], s[78:79], v[150:151] op_sel_hi:[1,0,1]
	v_pk_fma_f32 v[148:149], v[132:133], s[78:79], v[148:149] op_sel_hi:[1,0,1]
	v_lshl_add_u64 v[152:153], v[152:153], 2, s[90:91]
	v_pk_mul_f32 v[146:147], v[216:217], v[146:147] op_sel:[1,0]
	v_pk_mul_f32 v[144:145], v[216:217], v[144:145] op_sel:[1,0]
	global_store_dwordx4 v[152:153], v[148:151], off
	v_pk_fma_f32 v[144:145], v[208:209], v[144:145], v[40:41]
	v_pk_fma_f32 v[146:147], v[206:207], v[146:147], v[42:43]
;     template <bool LN, int BJ, int LO, int HI> DI void batch(const f32x4 (&acc)[2][2][4][2], unsigned row0, unsigned col0, const f32x4 (&gv)[2], const f32x4 (&bv)[2]) const {
;         f32x4 r[HI - LO]; float mean[(HI - LO) / 2], rstd[(HI - LO) / 2];
; #pragma unroll
;         for (int i = LO; i < HI; ++i) { const int ai = i >> 3, m = (i >> 1) & 3, n = i & 1; const unsigned row = row0 + ai * HALF + m * 16;
;             if (n == 0) { mean[(i - LO) >> 1] = 0.f; rstd[(i - LO) >> 1] = 1.f;
;                 if (LN) { const float2 st = *(const float2*)(stats + row * 2u); mean[(i - LO) >> 1] = st.x; rstd[(i - LO) >> 1] = st.y; } }
;             r[i - LO] = *(const f32x4*)(src + (row * (unsigned)DM + col0 + BJ * HALF + n * 16)); }
; #pragma unroll
;         for (int i = LO; i < HI; ++i) { const int ai = i >> 3, m = (i >> 1) & 3, n = i & 1; const unsigned row = row0 + ai * HALF + m * 16;
;             *(f32x4*)(Y + (row * (unsigned)DM + col0 + BJ * HALF + n * 16)) = acc[ai][BJ][m][n] + ((r[i - LO] - mean[(i - LO) >> 1]) * rstd[(i - LO) >> 1]) * gv[n] + bv[n]; }
;         __builtin_amdgcn_sched_barrier(0);
;     template <bool LN> DI void run(const f32x4 (&acc)[2][2][4][2], const Unit& u, int wr, int wc, int fr, int fq) const {
;     ...
;         batch<LN, 1, 8, 16>(acc, row0, col0, gv, bv);
	v_add_u32_e32 v148, 0x10090, v194
	v_mov_b32_e32 v149, v159
	v_sub_f32_e32 v141, v141, v200
	v_sub_f32_e32 v140, v140, v200
	v_sub_f32_e32 v143, v143, v200
	v_sub_f32_e32 v142, v142, v200
	v_pk_fma_f32 v[146:147], v[130:131], s[78:79], v[146:147] op_sel_hi:[1,0,1]
	v_pk_fma_f32 v[144:145], v[128:129], s[78:79], v[144:145] op_sel_hi:[1,0,1]
	v_lshl_add_u64 v[148:149], v[148:149], 2, s[90:91]
	v_pk_mul_f32 v[142:143], v[200:201], v[142:143] op_sel:[1,0]
	v_pk_mul_f32 v[140:141], v[200:201], v[140:141] op_sel:[1,0]
	global_store_dwordx4 v[148:149], v[144:147], off
	v_pk_fma_f32 v[140:141], v[214:215], v[140:141], v[36:37]
	v_pk_fma_f32 v[142:143], v[212:213], v[142:143], v[38:39]
	v_add_u32_e32 v144, 0x18080, v194
	v_mov_b32_e32 v145, v159
	v_sub_f32_e32 v137, v137, v200
	v_sub_f32_e32 v136, v136, v200
	v_sub_f32_e32 v139, v139, v200
	v_sub_f32_e32 v138, v138, v200
	v_pk_fma_f32 v[142:143], v[134:135], s[78:79], v[142:143] op_sel_hi:[1,0,1]
	v_pk_fma_f32 v[140:141], v[132:133], s[78:79], v[140:141] op_sel_hi:[1,0,1]
	v_lshl_add_u64 v[144:145], v[144:145], 2, s[90:91]
	v_pk_mul_f32 v[138:139], v[200:201], v[138:139] op_sel:[1,0]
	v_pk_mul_f32 v[136:137], v[200:201], v[136:137] op_sel:[1,0]
	global_store_dwordx4 v[144:145], v[140:143], off
	v_pk_fma_f32 v[136:137], v[208:209], v[136:137], v[32:33]
	v_pk_fma_f32 v[138:139], v[206:207], v[138:139], v[34:35]
	v_add_u32_e32 v140, 0x18090, v194
	v_mov_b32_e32 v141, v159
	v_pk_fma_f32 v[138:139], v[130:131], s[78:79], v[138:139] op_sel_hi:[1,0,1]
	v_pk_fma_f32 v[136:137], v[128:129], s[78:79], v[136:137] op_sel_hi:[1,0,1]
	v_lshl_add_u64 v[140:141], v[140:141], 2, s[90:91]
	global_store_dwordx4 v[140:141], v[136:139], off
	s_nop 1
	v_add_u32_e32 v136, v233, v230
	v_mov_b32_e32 v137, v159
	v_lshl_add_u64 v[136:137], v[136:137], 2, s[88:89]
	global_load_dwordx2 v[220:221], v[196:197], off
	global_load_dwordx4 v[216:219], v[136:137], off
	v_add_u32_e32 v136, v233, v229
	v_mov_b32_e32 v137, v159
	v_lshl_add_u64 v[136:137], v[136:137], 2, s[88:89]
	global_load_dwordx4 v[240:243], v[136:137], off
	global_load_dwordx2 v[200:201], v[198:199], off
	v_add_u32_e32 v136, v234, v230
	v_mov_b32_e32 v137, v159
	v_lshl_add_u64 v[136:137], v[136:137], 2, s[88:89]
	global_load_dwordx4 v[244:247], v[136:137], off
	v_add_u32_e32 v136, v234, v229
	v_mov_b32_e32 v137, v159
	v_lshl_add_u64 v[136:137], v[136:137], 2, s[88:89]
	global_load_dwordx4 v[152:155], v[136:137], off
	global_load_dwordx2 v[198:199], v[204:205], off
	v_add_u32_e32 v136, v237, v230
	v_mov_b32_e32 v137, v159
	v_lshl_add_u64 v[136:137], v[136:137], 2, s[88:89]
	global_load_dwordx4 v[148:151], v[136:137], off
	v_add_u32_e32 v136, v237, v229
	v_mov_b32_e32 v137, v159
	v_lshl_add_u64 v[136:137], v[136:137], 2, s[88:89]
	global_load_dwordx4 v[144:147], v[136:137], off
	global_load_dwordx2 v[196:197], v[210:211], off
	v_add_u32_e32 v136, v238, v230
	v_mov_b32_e32 v137, v159
	v_lshl_add_u64 v[136:137], v[136:137], 2, s[88:89]
	global_load_dwordx4 v[140:143], v[136:137], off
	v_add_u32_e32 v136, v238, v229
	v_mov_b32_e32 v137, v159
	v_lshl_add_u64 v[136:137], v[136:137], 2, s[88:89]
	global_load_dwordx4 v[136:139], v[136:137], off
	v_add_u32_e32 v210, 0x40080, v194
	v_mov_b32_e32 v211, v159
	v_lshl_add_u64 v[210:211], v[210:211], 2, s[90:91]
	s_waitcnt vmcnt(0)
;     template <bool LN, int BJ, int LO, int HI> DI void batch(const f32x4 (&acc)[2][2][4][2], unsigned row0, unsigned col0, const f32x4 (&gv)[2], const f32x4 (&bv)[2]) const {
;         f32x4 r[HI - LO]; float mean[(HI - LO) / 2], rstd[(HI - LO) / 2];
; #pragma unroll
;         for (int i = LO; i < HI; ++i) { const int ai = i >> 3, m = (i >> 1) & 3, n = i & 1; const unsigned row = row0 + ai * HALF + m * 16;
;             if (n == 0) { mean[(i - LO) >> 1] = 0.f; rstd[(i - LO) >> 1] = 1.f;
;                 if (LN) { const float2 st = *(const float2*)(stats + row * 2u); mean[(i - LO) >> 1] = st.x; rstd[(i - LO) >> 1] = st.y; } }
;             r[i - LO] = *(const f32x4*)(src + (row * (unsigned)DM + col0 + BJ * HALF + n * 16)); }
; #pragma unroll
;         for (int i = LO; i < HI; ++i) { const int ai = i >> 3, m = (i >> 1) & 3, n = i & 1; const unsigned row = row0 + ai * HALF + m * 16;
;             *(f32x4*)(Y + (row * (unsigned)DM + col0 + BJ * HALF + n * 16)) = acc[ai][BJ][m][n] + ((r[i - LO] - mean[(i - LO) >> 1]) * rstd[(i - LO) >> 1]) * gv[n] + bv[n]; }
;         __builtin_amdgcn_sched_barrier(0);
;     template <bool LN> DI void run(const f32x4 (&acc)[2][2][4][2], const Unit& u, int wr, int wc, int fr, int fq) const {
;     ...
;         batch<LN, 1, 8, 16>(acc, row0, col0, gv, bv);
	v_sub_f32_e32 v203, v217, v220
	v_sub_f32_e32 v202, v216, v220
	v_sub_f32_e32 v205, v219, v220
	v_sub_f32_e32 v204, v218, v220
	v_pk_mul_f32 v[204:205], v[220:221], v[204:205] op_sel:[1,0]
	v_pk_mul_f32 v[202:203], v[220:221], v[202:203] op_sel:[1,0]
	v_pk_fma_f32 v[204:205], v[212:213], v[204:205], v[30:31]
	v_pk_fma_f32 v[202:203], v[214:215], v[202:203], v[28:29]
	v_pk_fma_f32 v[204:205], v[134:135], s[78:79], v[204:205] op_sel_hi:[1,0,1]
	v_pk_fma_f32 v[202:203], v[132:133], s[78:79], v[202:203] op_sel_hi:[1,0,1]
	global_store_dwordx4 v[210:211], v[202:205], off
	v_add_u32_e32 v210, 0x40090, v194
	v_mov_b32_e32 v211, v159
	v_sub_f32_e32 v203, v241, v220
	v_sub_f32_e32 v202, v240, v220
	v_sub_f32_e32 v205, v243, v220
	v_sub_f32_e32 v204, v242, v220
	v_pk_mul_f32 v[204:205], v[220:221], v[204:205] op_sel:[1,0]
	v_pk_mul_f32 v[202:203], v[220:221], v[202:203] op_sel:[1,0]
	v_pk_fma_f32 v[204:205], v[206:207], v[204:205], v[26:27]
	v_pk_fma_f32 v[202:203], v[208:209], v[202:203], v[24:25]
	v_pk_fma_f32 v[204:205], v[130:131], s[78:79], v[204:205] op_sel_hi:[1,0,1]
	v_pk_fma_f32 v[202:203], v[128:129], s[78:79], v[202:203] op_sel_hi:[1,0,1]
	v_lshl_add_u64 v[210:211], v[210:211], 2, s[90:91]
	global_store_dwordx4 v[210:211], v[202:205], off
	v_sub_f32_e32 v149, v149, v198
	v_sub_f32_e32 v148, v148, v198
	v_sub_f32_e32 v203, v245, v200
	v_sub_f32_e32 v202, v244, v200
	v_sub_f32_e32 v141, v141, v196
	v_sub_f32_e32 v140, v140, v196
	v_sub_f32_e32 v205, v247, v200
	v_sub_f32_e32 v204, v246, v200
	v_pk_mul_f32 v[202:203], v[200:201], v[202:203] op_sel:[1,0]
	v_sub_f32_e32 v151, v151, v198
	v_sub_f32_e32 v150, v150, v198
	v_pk_mul_f32 v[148:149], v[198:199], v[148:149] op_sel:[1,0]
	v_sub_f32_e32 v143, v143, v196
	v_sub_f32_e32 v142, v142, v196
	v_pk_mul_f32 v[140:141], v[196:197], v[140:141] op_sel:[1,0]
	v_pk_mul_f32 v[204:205], v[200:201], v[204:205] op_sel:[1,0]
	v_pk_fma_f32 v[202:203], v[214:215], v[202:203], v[20:21]
	v_sub_f32_e32 v153, v153, v200
	v_sub_f32_e32 v152, v152, v200
	v_sub_f32_e32 v155, v155, v200
	v_sub_f32_e32 v154, v154, v200
	v_pk_mul_f32 v[150:151], v[198:199], v[150:151] op_sel:[1,0]
	v_pk_fma_f32 v[148:149], v[214:215], v[148:149], v[12:13]
	v_pk_mul_f32 v[142:143], v[196:197], v[142:143] op_sel:[1,0]
	v_pk_fma_f32 v[140:141], v[214:215], v[140:141], v[4:5]
	v_pk_fma_f32 v[204:205], v[212:213], v[204:205], v[22:23]
	v_pk_fma_f32 v[202:203], v[132:133], s[78:79], v[202:203] op_sel_hi:[1,0,1]
	v_pk_mul_f32 v[154:155], v[200:201], v[154:155] op_sel:[1,0]
	v_pk_mul_f32 v[152:153], v[200:201], v[152:153] op_sel:[1,0]
	v_pk_fma_f32 v[150:151], v[212:213], v[150:151], v[14:15]
	v_pk_fma_f32 v[148:149], v[132:133], s[78:79], v[148:149] op_sel_hi:[1,0,1]
	v_pk_fma_f32 v[142:143], v[212:213], v[142:143], v[6:7]
	v_pk_fma_f32 v[132:133], v[132:133], s[78:79], v[140:141] op_sel_hi:[1,0,1]
	v_add_u32_e32 v140, 0x58080, v194
	v_mov_b32_e32 v141, v159
	v_pk_fma_f32 v[204:205], v[134:135], s[78:79], v[204:205] op_sel_hi:[1,0,1]
	v_pk_fma_f32 v[152:153], v[208:209], v[152:153], v[16:17]
	v_pk_fma_f32 v[154:155], v[206:207], v[154:155], v[18:19]
	v_add_u32_e32 v200, 0x48090, v194
	v_mov_b32_e32 v201, v159
	v_pk_fma_f32 v[150:151], v[134:135], s[78:79], v[150:151] op_sel_hi:[1,0,1]
	v_pk_fma_f32 v[134:135], v[134:135], s[78:79], v[142:143] op_sel_hi:[1,0,1]
	v_lshl_add_u64 v[140:141], v[140:141], 2, s[90:91]
	v_pk_fma_f32 v[154:155], v[130:131], s[78:79], v[154:155] op_sel_hi:[1,0,1]
	v_pk_fma_f32 v[152:153], v[128:129], s[78:79], v[152:153] op_sel_hi:[1,0,1]
	v_lshl_add_u64 v[200:201], v[200:201], 2, s[90:91]
	v_sub_f32_e32 v145, v145, v198
	v_sub_f32_e32 v144, v144, v198
	global_store_dwordx4 v[140:141], v[132:135], off
	global_store_dwordx4 v[200:201], v[152:155], off
	v_sub_f32_e32 v147, v147, v198
	v_sub_f32_e32 v133, v137, v196
	v_sub_f32_e32 v132, v136, v196
	v_add_u32_e32 v152, 0x50080, v194
	v_mov_b32_e32 v153, v159
	v_sub_f32_e32 v146, v146, v198
	v_pk_mul_f32 v[144:145], v[198:199], v[144:145] op_sel:[1,0]
	v_sub_f32_e32 v135, v139, v196
	v_sub_f32_e32 v134, v138, v196
	v_pk_mul_f32 v[132:133], v[196:197], v[132:133] op_sel:[1,0]
	v_lshl_add_u64 v[152:153], v[152:153], 2, s[90:91]
	v_pk_mul_f32 v[146:147], v[198:199], v[146:147] op_sel:[1,0]
	v_pk_fma_f32 v[144:145], v[208:209], v[144:145], v[8:9]
	v_pk_mul_f32 v[134:135], v[196:197], v[134:135] op_sel:[1,0]
	v_pk_fma_f32 v[132:133], v[208:209], v[132:133], v[0:1]
	v_add_u32_e32 v210, 0x48080, v194
	v_mov_b32_e32 v211, v159
	global_store_dwordx4 v[152:153], v[148:151], off
	v_pk_fma_f32 v[146:147], v[206:207], v[146:147], v[10:11]
	v_pk_fma_f32 v[144:145], v[128:129], s[78:79], v[144:145] op_sel_hi:[1,0,1]
	v_add_u32_e32 v148, 0x50090, v194
	v_mov_b32_e32 v149, v159
	v_pk_fma_f32 v[134:135], v[206:207], v[134:135], v[2:3]
	v_pk_fma_f32 v[128:129], v[128:129], s[78:79], v[132:133] op_sel_hi:[1,0,1]
	v_add_u32_e32 v132, 0x58090, v194
	v_mov_b32_e32 v133, v159
	v_lshl_add_u64 v[210:211], v[210:211], 2, s[90:91]
	v_pk_fma_f32 v[146:147], v[130:131], s[78:79], v[146:147] op_sel_hi:[1,0,1]
	v_lshl_add_u64 v[148:149], v[148:149], 2, s[90:91]
	v_pk_fma_f32 v[130:131], v[130:131], s[78:79], v[134:135] op_sel_hi:[1,0,1]
	v_lshl_add_u64 v[132:133], v[132:133], 2, s[90:91]
	global_store_dwordx4 v[210:211], v[202:205], off
	global_store_dwordx4 v[148:149], v[144:147], off
	global_store_dwordx4 v[132:133], v[128:131], off
	s_mov_b64 s[20:21], 0
	s_branch .LBB0_81

; #define PG8_STAGE(bufoff, gbase) do { _Pragma("unroll") for (int _i = 0; _i < 2; ++_i) \
;         __builtin_amdgcn_global_load_lds((const unsigned*)((const char*)(gbase) + voff[_i]), (LAS unsigned*)(lds + (bufoff) + ldsw + _i * 8192), 16, 0, 0); } while (0)
; #define PG8_LDA(dst, b, h) do { _Pragma("unroll") for (int m = 0; m < 4; ++m) _Pragma("unroll") for (int k = 0; k < 2; ++k) dst[m][k] = *(const LAS bf16x8*)(lds + PG8_SA(b, h) + aoff + m * 2048 + k * 1024); } while (0)
; #define PG8_LDB(dst, b, h) do { _Pragma("unroll") for (int n = 0; n < 2; ++n) _Pragma("unroll") for (int k = 0; k < 2; ++k) dst[n][k] = *(const LAS bf16x8*)(lds + PG8_SB(b, h) + boff + n * 2048 + k * 1024); } while (0)
; #define PG8_MMA(ai, bj, At, Bt) do { __builtin_amdgcn_s_setprio(1); _Pragma("unroll") for (int m = 0; m < 4; ++m) _Pragma("unroll") for (int n = 0; n < 2; ++n) _Pragma("unroll") for (int k = 0; k < 2; ++k) \
;         acc[ai][bj][m][n] = __builtin_amdgcn_mfma_f32_16x16x32_bf16(Bt[n][k], At[m][k], acc[ai][bj][m][n], 0, 0, 0); __builtin_amdgcn_s_setprio(0); } while (0)
; #define PG8_WAIT_V(n) asm volatile("s_waitcnt vmcnt(" #n ")" ::: "memory")
; #define PG8_WAIT_L(n) asm volatile("s_waitcnt lgkmcnt(" #n ")" ::: "memory")
; #define PG8_BAR __builtin_amdgcn_s_barrier()
; #define PG8_SCHED __builtin_amdgcn_sched_barrier(0)
; template <class Epi>
; DI void gemm_phase(LAS unsigned char* lds, const Gemm g, const StaticOrder& S, const Epi& E) {
;     ...
;         for (int t = 0; t < nt; t += 2) {
;             const bool last = (t == nt - 2);
;             const char* a1 = cA + (size_t)(t + 1) * kstep;
;             const char* a2 = last ? nA : cA + (size_t)(t + 2) * kstep; const char* b2 = last ? nB : cB + (size_t)(t + 2) * kstep;
;             const char* a3 = a2 + kstep; const char* b3 = b2 + kstep;
;             PG8_LDB(B0, 0, 0); PG8_SCHED; PG8_LDA(At, 0, 0); PG8_STAGE(PG8_SA(1, 1), a1 + hstep);
;             PG8_WAIT_L(8); PG8_BAR; PG8_WAIT_L(0); PG8_MMA(0, 0, At, B0); PG8_BAR; PG8_SCHED;
;             PG8_LDB(B1, 0, 1); PG8_STAGE(PG8_SB(0, 0), b2);
;             PG8_BAR; PG8_WAIT_L(0); PG8_MMA(0, 1, At, B1); PG8_BAR;
;             PG8_LDA(At, 0, 1); PG8_STAGE(PG8_SA(0, 0), a2);
;             PG8_BAR; PG8_WAIT_L(0); PG8_MMA(1, 0, At, B0); PG8_BAR; PG8_SCHED;
;             PG8_STAGE(PG8_SB(0, 1), b2 + hstep);
;             PG8_WAIT_V(6); PG8_BAR; PG8_MMA(1, 1, At, B1); PG8_BAR;
.LBB0_134:
	ds_read_b128 v[96:99], v199
	ds_read_b128 v[100:103], v199 offset:1024
	ds_read_b128 v[136:139], v199 offset:2048
	ds_read_b128 v[148:151], v199 offset:3072
	ds_read_b128 v[152:155], v201
	ds_read_b128 v[186:189], v201 offset:1024
	ds_read_b128 v[190:193], v201 offset:2048
	ds_read_b128 v[194:197], v201 offset:3072
	ds_read_b128 v[202:205], v201 offset:4096
	ds_read_b128 v[206:209], v201 offset:5120
	ds_read_b128 v[210:213], v201 offset:6144
	ds_read_b128 v[214:217], v201 offset:7168
	s_add_u32 s18, s16, 0x100
	s_addc_u32 s19, s17, 0
	s_add_i32 s39, 0, 0x10000
	s_cmpk_eq_i32 s33, 0x54
	s_cselect_b32 s23, s9, s19
	s_cselect_b32 s22, s8, s18
	s_cselect_b32 s21, s11, s5
	s_cselect_b32 s20, s10, s4
	s_add_i32 m0, s28, 0xc000
	s_nop 0
	global_load_lds_dwordx4 v144, s[16:17]
	s_add_i32 m0, s28, 0xe000
	s_nop 0
	global_load_lds_dwordx4 v146, s[16:17]
	s_waitcnt lgkmcnt(8)
	s_barrier
	s_waitcnt lgkmcnt(0)
	v_mfma_f32_16x16x32_bf16 v[132:135], v[96:99], v[152:155], v[132:135]
	v_mfma_f32_16x16x32_bf16 v[128:131], v[136:139], v[152:155], v[128:131]
	v_mfma_f32_16x16x32_bf16 v[124:127], v[96:99], v[190:193], v[124:127]
	v_mfma_f32_16x16x32_bf16 v[120:123], v[136:139], v[190:193], v[120:123]
	v_mfma_f32_16x16x32_bf16 v[116:119], v[96:99], v[202:205], v[116:119]
	v_mfma_f32_16x16x32_bf16 v[112:115], v[136:139], v[202:205], v[112:115]
	v_mfma_f32_16x16x32_bf16 v[108:111], v[96:99], v[210:213], v[108:111]
	v_mfma_f32_16x16x32_bf16 v[104:107], v[136:139], v[210:213], v[104:107]
	v_mfma_f32_16x16x32_bf16 v[132:135], v[100:103], v[186:189], v[132:135]
	v_mfma_f32_16x16x32_bf16 v[128:131], v[148:151], v[186:189], v[128:131]
	v_mfma_f32_16x16x32_bf16 v[124:127], v[100:103], v[194:197], v[124:127]
	v_mfma_f32_16x16x32_bf16 v[120:123], v[148:151], v[194:197], v[120:123]
	v_mfma_f32_16x16x32_bf16 v[116:119], v[100:103], v[206:209], v[116:119]
	v_mfma_f32_16x16x32_bf16 v[112:115], v[148:151], v[206:209], v[112:115]
	v_mfma_f32_16x16x32_bf16 v[108:111], v[100:103], v[214:217], v[108:111]
	v_mfma_f32_16x16x32_bf16 v[104:107], v[148:151], v[214:217], v[104:107]
	s_barrier
	ds_read_b128 v[226:229], v199 offset:16384
	ds_read_b128 v[230:233], v199 offset:17408
	ds_read_b128 v[234:237], v199 offset:18432
	ds_read_b128 v[238:241], v199 offset:19456
	s_add_i32 s40, 0, 0x14000
	s_add_i32 s16, s39, s27
	s_mov_b32 m0, s16
	s_nop 0
	global_load_lds_dwordx4 v142, s[20:21]
	s_add_i32 m0, s16, 0x2000
	s_nop 0
	global_load_lds_dwordx4 v140, s[20:21]
	s_waitcnt lgkmcnt(0)
	s_barrier
	v_mfma_f32_16x16x32_bf16 v[60:63], v[226:229], v[152:155], v[60:63]
	v_mfma_f32_16x16x32_bf16 v[56:59], v[234:237], v[152:155], v[56:59]
	v_mfma_f32_16x16x32_bf16 v[52:55], v[226:229], v[190:193], v[52:55]
	v_mfma_f32_16x16x32_bf16 v[48:51], v[234:237], v[190:193], v[48:51]
	v_mfma_f32_16x16x32_bf16 v[44:47], v[226:229], v[202:205], v[44:47]
	v_mfma_f32_16x16x32_bf16 v[40:43], v[234:237], v[202:205], v[40:43]
	v_mfma_f32_16x16x32_bf16 v[36:39], v[226:229], v[210:213], v[36:39]
	v_mfma_f32_16x16x32_bf16 v[32:35], v[234:237], v[210:213], v[32:35]
	v_mfma_f32_16x16x32_bf16 v[60:63], v[230:233], v[186:189], v[60:63]
	s_mov_b32 m0, s28
	v_mfma_f32_16x16x32_bf16 v[56:59], v[238:241], v[186:189], v[56:59]
	s_mov_b64 s[100:101], s[22:23]
	v_mfma_f32_16x16x32_bf16 v[52:55], v[230:233], v[194:197], v[52:55]
	v_mfma_f32_16x16x32_bf16 v[48:51], v[238:241], v[194:197], v[48:51]
	v_mfma_f32_16x16x32_bf16 v[44:47], v[230:233], v[206:209], v[44:47]
	v_mfma_f32_16x16x32_bf16 v[40:43], v[238:241], v[206:209], v[40:43]
	v_mfma_f32_16x16x32_bf16 v[36:39], v[230:233], v[214:217], v[36:39]
	v_mfma_f32_16x16x32_bf16 v[32:35], v[238:241], v[214:217], v[32:35]
	s_barrier
	ds_read_b128 v[152:155], v201 offset:16384
	ds_read_b128 v[186:189], v201 offset:17408
	ds_read_b128 v[190:193], v201 offset:18432
	ds_read_b128 v[194:197], v201 offset:19456
	ds_read_b128 v[202:205], v201 offset:20480
	ds_read_b128 v[206:209], v201 offset:21504
	ds_read_b128 v[210:213], v201 offset:22528
	ds_read_b128 v[214:217], v201 offset:23552
	global_load_lds_dwordx4 v142, s[22:23]
	s_mov_b64 s[100:101], s[22:23]
	s_mov_b32 m0, s29
	s_nop 0
	global_load_lds_dwordx4 v140, s[22:23]
	s_waitcnt lgkmcnt(0)
	s_barrier
	v_mfma_f32_16x16x32_bf16 v[92:95], v[96:99], v[152:155], v[92:95]
	v_mfma_f32_16x16x32_bf16 v[88:91], v[136:139], v[152:155], v[88:91]
	v_mfma_f32_16x16x32_bf16 v[84:87], v[96:99], v[190:193], v[84:87]
	v_mfma_f32_16x16x32_bf16 v[80:83], v[136:139], v[190:193], v[80:83]
	v_mfma_f32_16x16x32_bf16 v[76:79], v[96:99], v[202:205], v[76:79]
	v_mfma_f32_16x16x32_bf16 v[72:75], v[136:139], v[202:205], v[72:75]
	v_mfma_f32_16x16x32_bf16 v[68:71], v[96:99], v[210:213], v[68:71]
	v_mfma_f32_16x16x32_bf16 v[64:67], v[136:139], v[210:213], v[64:67]
	v_mfma_f32_16x16x32_bf16 v[92:95], v[100:103], v[186:189], v[92:95]
	v_mfma_f32_16x16x32_bf16 v[88:91], v[148:151], v[186:189], v[88:91]
	v_mfma_f32_16x16x32_bf16 v[84:87], v[100:103], v[194:197], v[84:87]
	v_mfma_f32_16x16x32_bf16 v[80:83], v[148:151], v[194:197], v[80:83]
	v_mfma_f32_16x16x32_bf16 v[76:79], v[100:103], v[206:209], v[76:79]
	v_mfma_f32_16x16x32_bf16 v[72:75], v[148:151], v[206:209], v[72:75]
	v_mfma_f32_16x16x32_bf16 v[68:71], v[100:103], v[214:217], v[68:71]
	v_mfma_f32_16x16x32_bf16 v[64:67], v[148:151], v[214:217], v[64:67]
	s_barrier
	s_add_u32 s16, s20, 0x160000
	s_addc_u32 s17, s21, 0
	s_add_i32 s39, s40, s27
	s_mov_b32 m0, s39
	s_nop 0
	global_load_lds_dwordx4 v142, s[16:17]
	s_add_i32 m0, s39, 0x2000
	s_nop 0
	global_load_lds_dwordx4 v140, s[16:17]
	s_waitcnt vmcnt(6)
	s_barrier
; #define PG8_STAGE(bufoff, gbase) do { _Pragma("unroll") for (int _i = 0; _i < 2; ++_i) \
;         __builtin_amdgcn_global_load_lds((const unsigned*)((const char*)(gbase) + voff[_i]), (LAS unsigned*)(lds + (bufoff) + ldsw + _i * 8192), 16, 0, 0); } while (0)
; #define PG8_LDA(dst, b, h) do { _Pragma("unroll") for (int m = 0; m < 4; ++m) _Pragma("unroll") for (int k = 0; k < 2; ++k) dst[m][k] = *(const LAS bf16x8*)(lds + PG8_SA(b, h) + aoff + m * 2048 + k * 1024); } while (0)
; #define PG8_LDB(dst, b, h) do { _Pragma("unroll") for (int n = 0; n < 2; ++n) _Pragma("unroll") for (int k = 0; k < 2; ++k) dst[n][k] = *(const LAS bf16x8*)(lds + PG8_SB(b, h) + boff + n * 2048 + k * 1024); } while (0)
; #define PG8_MMA(ai, bj, At, Bt) do { __builtin_amdgcn_s_setprio(1); _Pragma("unroll") for (int m = 0; m < 4; ++m) _Pragma("unroll") for (int n = 0; n < 2; ++n) _Pragma("unroll") for (int k = 0; k < 2; ++k) \
;         acc[ai][bj][m][n] = __builtin_amdgcn_mfma_f32_16x16x32_bf16(Bt[n][k], At[m][k], acc[ai][bj][m][n], 0, 0, 0); __builtin_amdgcn_s_setprio(0); } while (0)
; #define PG8_WAIT_V(n) asm volatile("s_waitcnt vmcnt(" #n ")" ::: "memory")
; #define PG8_WAIT_L(n) asm volatile("s_waitcnt lgkmcnt(" #n ")" ::: "memory")
; #define PG8_BAR __builtin_amdgcn_s_barrier()
; #define PG8_SCHED __builtin_amdgcn_sched_barrier(0)
; template <class Epi>
; DI void gemm_phase(LAS unsigned char* lds, const Gemm g, const StaticOrder& S, const Epi& E) {
;     ...
;             PG8_WAIT_V(6); PG8_BAR; PG8_MMA(1, 1, At, B1); PG8_BAR;
;             PG8_LDB(B0, 1, 0); PG8_SCHED; PG8_LDA(At, 1, 0); PG8_STAGE(PG8_SA(0, 1), a2 + hstep);
;             PG8_WAIT_L(8); PG8_BAR; PG8_WAIT_L(0); PG8_MMA(0, 0, At, B0); PG8_BAR; PG8_SCHED;
;             PG8_LDB(B1, 1, 1); PG8_STAGE(PG8_SB(1, 0), b3);
;             PG8_BAR; PG8_WAIT_L(0); PG8_MMA(0, 1, At, B1); PG8_BAR;
;             PG8_LDA(At, 1, 1); PG8_STAGE(PG8_SA(1, 0), a3);
;             PG8_BAR; PG8_WAIT_L(0); PG8_MMA(1, 0, At, B0); PG8_BAR; PG8_SCHED;
	v_mfma_f32_16x16x32_bf16 v[28:31], v[226:229], v[152:155], v[28:31]
	v_mfma_f32_16x16x32_bf16 v[24:27], v[234:237], v[152:155], v[24:27]
	v_mfma_f32_16x16x32_bf16 v[20:23], v[226:229], v[190:193], v[20:23]
	v_mfma_f32_16x16x32_bf16 v[16:19], v[234:237], v[190:193], v[16:19]
	v_mfma_f32_16x16x32_bf16 v[12:15], v[226:229], v[202:205], v[12:15]
	v_mfma_f32_16x16x32_bf16 v[8:11], v[234:237], v[202:205], v[8:11]
	v_mfma_f32_16x16x32_bf16 v[4:7], v[226:229], v[210:213], v[4:7]
	v_mfma_f32_16x16x32_bf16 v[0:3], v[234:237], v[210:213], v[0:3]
	v_mfma_f32_16x16x32_bf16 v[28:31], v[230:233], v[186:189], v[28:31]
	s_add_i32 s39, 0, 0x18000
	v_mfma_f32_16x16x32_bf16 v[24:27], v[238:241], v[186:189], v[24:27]
	v_mfma_f32_16x16x32_bf16 v[20:23], v[230:233], v[194:197], v[20:23]
	v_mfma_f32_16x16x32_bf16 v[16:19], v[238:241], v[194:197], v[16:19]
	v_mfma_f32_16x16x32_bf16 v[12:15], v[230:233], v[206:209], v[12:15]
	v_mfma_f32_16x16x32_bf16 v[8:11], v[238:241], v[206:209], v[8:11]
	v_mfma_f32_16x16x32_bf16 v[4:7], v[230:233], v[214:217], v[4:7]
	v_mfma_f32_16x16x32_bf16 v[0:3], v[238:241], v[214:217], v[0:3]
	s_barrier
	ds_read_b128 v[96:99], v199 offset:32768
	ds_read_b128 v[100:103], v199 offset:33792
	ds_read_b128 v[136:139], v199 offset:34816
	ds_read_b128 v[148:151], v199 offset:35840
	ds_read_b128 v[152:155], v201 offset:32768
	ds_read_b128 v[186:189], v201 offset:33792
	ds_read_b128 v[190:193], v201 offset:34816
	ds_read_b128 v[194:197], v201 offset:35840
	ds_read_b128 v[202:205], v201 offset:36864
	ds_read_b128 v[206:209], v201 offset:37888
	ds_read_b128 v[210:213], v201 offset:38912
	ds_read_b128 v[214:217], v201 offset:39936
	s_add_u32 s16, s22, 0x160000
	s_addc_u32 s17, s23, 0
	s_mov_b32 m0, s30
	s_nop 0
	global_load_lds_dwordx4 v142, s[16:17]
	s_mov_b32 m0, s31
	s_nop 0
	global_load_lds_dwordx4 v140, s[16:17]
	s_waitcnt lgkmcnt(8)
	s_barrier
	s_waitcnt lgkmcnt(0)
	v_mfma_f32_16x16x32_bf16 v[132:135], v[96:99], v[152:155], v[132:135]
	v_mfma_f32_16x16x32_bf16 v[128:131], v[136:139], v[152:155], v[128:131]
	v_mfma_f32_16x16x32_bf16 v[124:127], v[96:99], v[190:193], v[124:127]
	v_mfma_f32_16x16x32_bf16 v[120:123], v[136:139], v[190:193], v[120:123]
	v_mfma_f32_16x16x32_bf16 v[116:119], v[96:99], v[202:205], v[116:119]
	v_mfma_f32_16x16x32_bf16 v[112:115], v[136:139], v[202:205], v[112:115]
	v_mfma_f32_16x16x32_bf16 v[108:111], v[96:99], v[210:213], v[108:111]
	v_mfma_f32_16x16x32_bf16 v[104:107], v[136:139], v[210:213], v[104:107]
	v_mfma_f32_16x16x32_bf16 v[132:135], v[100:103], v[186:189], v[132:135]
	v_mfma_f32_16x16x32_bf16 v[128:131], v[148:151], v[186:189], v[128:131]
	v_mfma_f32_16x16x32_bf16 v[124:127], v[100:103], v[194:197], v[124:127]
	v_mfma_f32_16x16x32_bf16 v[120:123], v[148:151], v[194:197], v[120:123]
	v_mfma_f32_16x16x32_bf16 v[116:119], v[100:103], v[206:209], v[116:119]
	v_mfma_f32_16x16x32_bf16 v[112:115], v[148:151], v[206:209], v[112:115]
	v_mfma_f32_16x16x32_bf16 v[108:111], v[100:103], v[214:217], v[108:111]
	v_mfma_f32_16x16x32_bf16 v[104:107], v[148:151], v[214:217], v[104:107]
	s_barrier
	ds_read_b128 v[226:229], v199 offset:49152
	ds_read_b128 v[230:233], v199 offset:50176
	ds_read_b128 v[234:237], v199 offset:51200
	ds_read_b128 v[238:241], v199 offset:52224
	s_add_i32 s22, 0, 0x1c000
	s_add_i32 s16, s39, s27
	s_add_i32 m0, s16, 0xffffff80
	s_nop 0
	global_load_lds_dwordx4 v142, s[20:21] offset:128
	s_add_i32 m0, s16, 0x1f80
	s_nop 0
	global_load_lds_dwordx4 v140, s[20:21] offset:128
	s_waitcnt lgkmcnt(0)
	s_barrier
	v_mfma_f32_16x16x32_bf16 v[60:63], v[226:229], v[152:155], v[60:63]
	v_mfma_f32_16x16x32_bf16 v[56:59], v[234:237], v[152:155], v[56:59]
	v_mfma_f32_16x16x32_bf16 v[52:55], v[226:229], v[190:193], v[52:55]
	v_mfma_f32_16x16x32_bf16 v[48:51], v[234:237], v[190:193], v[48:51]
	v_mfma_f32_16x16x32_bf16 v[44:47], v[226:229], v[202:205], v[44:47]
	v_mfma_f32_16x16x32_bf16 v[40:43], v[234:237], v[202:205], v[40:43]
	v_mfma_f32_16x16x32_bf16 v[36:39], v[226:229], v[210:213], v[36:39]
	v_mfma_f32_16x16x32_bf16 v[32:35], v[234:237], v[210:213], v[32:35]
	v_mfma_f32_16x16x32_bf16 v[60:63], v[230:233], v[186:189], v[60:63]
	s_add_i32 m0, s34, 0xffffff80
	v_mfma_f32_16x16x32_bf16 v[56:59], v[238:241], v[186:189], v[56:59]
	v_mfma_f32_16x16x32_bf16 v[52:55], v[230:233], v[194:197], v[52:55]
	v_mfma_f32_16x16x32_bf16 v[48:51], v[238:241], v[194:197], v[48:51]
	v_mfma_f32_16x16x32_bf16 v[44:47], v[230:233], v[206:209], v[44:47]
	v_mfma_f32_16x16x32_bf16 v[40:43], v[238:241], v[206:209], v[40:43]
	v_mfma_f32_16x16x32_bf16 v[36:39], v[230:233], v[214:217], v[36:39]
	v_mfma_f32_16x16x32_bf16 v[32:35], v[238:241], v[214:217], v[32:35]
	s_barrier
	ds_read_b128 v[152:155], v201 offset:49152
	ds_read_b128 v[186:189], v201 offset:50176
	ds_read_b128 v[190:193], v201 offset:51200
	ds_read_b128 v[194:197], v201 offset:52224
	ds_read_b128 v[202:205], v201 offset:53248
	ds_read_b128 v[206:209], v201 offset:54272
	ds_read_b128 v[210:213], v201 offset:55296
	ds_read_b128 v[214:217], v201 offset:56320
	global_load_lds_dwordx4 v142, s[100:101] offset:128
	s_add_i32 m0, s35, 0xffffff80
	s_nop 0
	global_load_lds_dwordx4 v140, s[100:101] offset:128
	s_waitcnt lgkmcnt(0)
	s_barrier
; #define PG8_STAGE(bufoff, gbase) do { _Pragma("unroll") for (int _i = 0; _i < 2; ++_i) \
;         __builtin_amdgcn_global_load_lds((const unsigned*)((const char*)(gbase) + voff[_i]), (LAS unsigned*)(lds + (bufoff) + ldsw + _i * 8192), 16, 0, 0); } while (0)
; #define PG8_MMA(ai, bj, At, Bt) do { __builtin_amdgcn_s_setprio(1); _Pragma("unroll") for (int m = 0; m < 4; ++m) _Pragma("unroll") for (int n = 0; n < 2; ++n) _Pragma("unroll") for (int k = 0; k < 2; ++k) \
;         acc[ai][bj][m][n] = __builtin_amdgcn_mfma_f32_16x16x32_bf16(Bt[n][k], At[m][k], acc[ai][bj][m][n], 0, 0, 0); __builtin_amdgcn_s_setprio(0); } while (0)
; #define PG8_WAIT_V(n) asm volatile("s_waitcnt vmcnt(" #n ")" ::: "memory")
; #define PG8_WAIT_L(n) asm volatile("s_waitcnt lgkmcnt(" #n ")" ::: "memory")
; #define PG8_BAR __builtin_amdgcn_s_barrier()
; #define PG8_SCHED __builtin_amdgcn_sched_barrier(0)
; template <class Epi>
; DI void gemm_phase(LAS unsigned char* lds, const Gemm g, const StaticOrder& S, const Epi& E) {
;     ...
;             PG8_BAR; PG8_WAIT_L(0); PG8_MMA(1, 0, At, B0); PG8_BAR; PG8_SCHED;
;             PG8_STAGE(PG8_SB(1, 1), b3 + hstep);
;             PG8_WAIT_V(6); PG8_BAR; PG8_MMA(1, 1, At, B1); PG8_BAR;
;     template <bool LN, int BJ> DI void load_gb(unsigned col0, f32x4 (&gv)[2], f32x4 (&bv)[2]) const {
; #pragma unroll
;         for (int n = 0; n < 2; ++n) {
;             if (LN) { gv[n] = *(const f32x4*)(gam + col0 + BJ * HALF + n * 16) * ALPHA; bv[n] = *(const f32x4*)(bet + col0 + BJ * HALF + n * 16) * ALPHA; }
;             else { gv[n] = (f32x4){ALPHA, ALPHA, ALPHA, ALPHA}; bv[n] = (f32x4){0.f, 0.f, 0.f, 0.f}; }
;         }
;     }
;     template <bool LN> DI void run(const f32x4 (&acc)[2][2][4][2], const Unit& u, int wr, int wc, int fr, int fq) const {
;         const unsigned row0 = u.pm * BM + wr * 64 + fr, col0 = u.pn * BM + wc * 32 + 4 * fq;
;         f32x4 gv[2], bv[2];
;         load_gb<LN, 0>(col0, gv, bv);
;         batch<LN, 0, 0, 4>(acc, row0, col0, gv, bv);
;         batch<LN, 0, 4, 8>(acc, row0, col0, gv, bv);
;         batch<LN, 0, 8, 12>(acc, row0, col0, gv, bv);
	v_mfma_f32_16x16x32_bf16 v[92:95], v[96:99], v[152:155], v[92:95]
	v_mfma_f32_16x16x32_bf16 v[88:91], v[136:139], v[152:155], v[88:91]
	v_mfma_f32_16x16x32_bf16 v[84:87], v[96:99], v[190:193], v[84:87]
	v_mfma_f32_16x16x32_bf16 v[80:83], v[136:139], v[190:193], v[80:83]
	v_mfma_f32_16x16x32_bf16 v[76:79], v[96:99], v[202:205], v[76:79]
	v_mfma_f32_16x16x32_bf16 v[72:75], v[136:139], v[202:205], v[72:75]
	v_mfma_f32_16x16x32_bf16 v[68:71], v[96:99], v[210:213], v[68:71]
	v_mfma_f32_16x16x32_bf16 v[64:67], v[136:139], v[210:213], v[64:67]
	v_mfma_f32_16x16x32_bf16 v[92:95], v[100:103], v[186:189], v[92:95]
	v_mfma_f32_16x16x32_bf16 v[88:91], v[148:151], v[186:189], v[88:91]
	v_mfma_f32_16x16x32_bf16 v[84:87], v[100:103], v[194:197], v[84:87]
	v_mfma_f32_16x16x32_bf16 v[80:83], v[148:151], v[194:197], v[80:83]
	v_mfma_f32_16x16x32_bf16 v[76:79], v[100:103], v[206:209], v[76:79]
	v_mfma_f32_16x16x32_bf16 v[72:75], v[148:151], v[206:209], v[72:75]
	v_mfma_f32_16x16x32_bf16 v[68:71], v[100:103], v[214:217], v[68:71]
	v_mfma_f32_16x16x32_bf16 v[64:67], v[148:151], v[214:217], v[64:67]
	s_barrier
	s_add_u32 s16, s20, 0x160080
	s_addc_u32 s17, s21, 0
	s_add_i32 s20, s22, s27
	s_mov_b32 m0, s20
	s_nop 0
	global_load_lds_dwordx4 v142, s[16:17]
	s_add_i32 m0, s20, 0x2000
	s_nop 0
	global_load_lds_dwordx4 v140, s[16:17]
	s_waitcnt vmcnt(6)
	s_barrier
	v_mfma_f32_16x16x32_bf16 v[28:31], v[226:229], v[152:155], v[28:31]
	v_mfma_f32_16x16x32_bf16 v[24:27], v[234:237], v[152:155], v[24:27]
	v_mfma_f32_16x16x32_bf16 v[20:23], v[226:229], v[190:193], v[20:23]
	v_mfma_f32_16x16x32_bf16 v[16:19], v[234:237], v[190:193], v[16:19]
	v_mfma_f32_16x16x32_bf16 v[12:15], v[226:229], v[202:205], v[12:15]
	v_mfma_f32_16x16x32_bf16 v[8:11], v[234:237], v[202:205], v[8:11]
	v_mfma_f32_16x16x32_bf16 v[4:7], v[226:229], v[210:213], v[4:7]
	v_mfma_f32_16x16x32_bf16 v[0:3], v[234:237], v[210:213], v[0:3]
	v_mfma_f32_16x16x32_bf16 v[28:31], v[230:233], v[186:189], v[28:31]
	s_add_i32 s33, s33, 2
	v_mfma_f32_16x16x32_bf16 v[24:27], v[238:241], v[186:189], v[24:27]
	s_add_u32 s4, s4, 0x100
	v_mfma_f32_16x16x32_bf16 v[20:23], v[230:233], v[194:197], v[20:23]
	s_addc_u32 s5, s5, 0
	v_mfma_f32_16x16x32_bf16 v[16:19], v[238:241], v[194:197], v[16:19]
	s_cmpk_gt_u32 s33, 0x55
	v_mfma_f32_16x16x32_bf16 v[12:15], v[230:233], v[206:209], v[12:15]
	s_mov_b64 s[16:17], s[18:19]
	v_mfma_f32_16x16x32_bf16 v[8:11], v[238:241], v[206:209], v[8:11]
	v_mfma_f32_16x16x32_bf16 v[4:7], v[230:233], v[214:217], v[4:7]
	v_mfma_f32_16x16x32_bf16 v[0:3], v[238:241], v[214:217], v[0:3]
	s_barrier
	s_cbranch_scc0 .LBB0_134
	v_lshl_or_b32 v158, s2, 8, v200
	v_lshlrev_b64 v[100:101], 2, v[158:159]
	v_lshl_add_u64 v[150:151], s[12:13], 0, v[100:101]
	global_load_dwordx4 v[96:99], v[150:151], off
	v_lshl_add_u64 v[152:153], s[14:15], 0, v[100:101]
	v_lshl_add_u32 v203, s3, 8, v198
	v_lshlrev_b32_e32 v202, 11, v203
	v_add_u32_e32 v148, v202, v158
	v_mov_b32_e32 v149, v159
	v_lshlrev_b32_e32 v136, 1, v203
	v_mov_b32_e32 v137, v159
	v_lshlrev_b64 v[220:221], 2, v[148:149]
	v_lshl_add_u64 v[154:155], v[136:137], 2, s[96:97]
	v_lshl_add_u64 v[136:137], s[90:91], 0, v[220:221]
	v_or_b32_e32 v204, 16, v158
	v_or_b32_e32 v138, 16, v203
	v_lshlrev_b32_e32 v149, 11, v138
	s_waitcnt vmcnt(0)
	v_pk_mul_f32 v[192:193], v[98:99], s[78:79] op_sel_hi:[1,0]
	v_pk_mul_f32 v[194:195], v[96:97], s[78:79] op_sel_hi:[1,0]
	global_load_dwordx4 v[100:103], v[152:153], off
	global_load_dwordx4 v[96:99], v[150:151], off offset:64
	global_load_dwordx2 v[218:219], v[154:155], off
	global_load_dwordx4 v[206:209], v[136:137], off
	v_add_u32_e32 v136, v202, v204
	v_mov_b32_e32 v137, v159
	v_lshl_add_u64 v[136:137], v[136:137], 2, s[90:91]
	global_load_dwordx4 v[210:213], v[136:137], off
	v_lshlrev_b32_e32 v136, 1, v138
	v_mov_b32_e32 v137, v159
	v_lshl_add_u64 v[186:187], v[136:137], 2, s[96:97]
	v_add_u32_e32 v136, v149, v158
	v_lshl_add_u64 v[136:137], v[136:137], 2, s[90:91]
	global_load_dwordx2 v[196:197], v[186:187], off
	global_load_dwordx4 v[214:217], v[136:137], off
	v_add_u32_e32 v136, v149, v204
	v_mov_b32_e32 v137, v159
	v_lshl_add_u64 v[136:137], v[136:137], 2, s[90:91]
	global_load_dwordx4 v[136:139], v[136:137], off
	s_waitcnt vmcnt(0)
	v_pk_mul_f32 v[188:189], v[98:99], s[78:79] op_sel_hi:[1,0]
	v_pk_mul_f32 v[190:191], v[96:97], s[78:79] op_sel_hi:[1,0]
	global_load_dwordx4 v[96:99], v[152:153], off offset:64
	v_sub_f32_e32 v207, v207, v218
	v_sub_f32_e32 v206, v206, v218
	v_sub_f32_e32 v209, v209, v218
	v_sub_f32_e32 v208, v208, v218
	v_pk_mul_f32 v[208:209], v[218:219], v[208:209] op_sel:[1,0]
	v_pk_mul_f32 v[206:207], v[218:219], v[206:207] op_sel:[1,0]
	v_pk_fma_f32 v[134:135], v[192:193], v[208:209], v[134:135]
	v_pk_fma_f32 v[132:133], v[194:195], v[206:207], v[132:133]
	v_pk_fma_f32 v[134:135], v[102:103], s[78:79], v[134:135] op_sel_hi:[1,0,1]
	v_pk_fma_f32 v[132:133], v[100:101], s[78:79], v[132:133] op_sel_hi:[1,0,1]
	v_lshl_add_u64 v[206:207], s[88:89], 0, v[220:221]
	global_store_dwordx4 v[206:207], v[132:135], off
	s_nop 1
	v_sub_f32_e32 v133, v211, v218
	v_sub_f32_e32 v132, v210, v218
	v_sub_f32_e32 v135, v213, v218
	v_sub_f32_e32 v134, v212, v218
	v_pk_mul_f32 v[134:135], v[218:219], v[134:135] op_sel:[1,0]
	v_pk_mul_f32 v[132:133], v[218:219], v[132:133] op_sel:[1,0]
	v_pk_fma_f32 v[130:131], v[188:189], v[134:135], v[130:131]
	v_pk_fma_f32 v[128:129], v[190:191], v[132:133], v[128:129]
	v_or_b32_e32 v132, 16, v148
	v_mov_b32_e32 v133, v159
	v_lshl_add_u64 v[132:133], v[132:133], 2, s[88:89]
	s_waitcnt vmcnt(0)
;     template <bool LN, int BJ, int LO, int HI> DI void batch(const f32x4 (&acc)[2][2][4][2], unsigned row0, unsigned col0, const f32x4 (&gv)[2], const f32x4 (&bv)[2]) const {
;         f32x4 r[HI - LO]; float mean[(HI - LO) / 2], rstd[(HI - LO) / 2];
; #pragma unroll
;         for (int i = LO; i < HI; ++i) { const int ai = i >> 3, m = (i >> 1) & 3, n = i & 1; const unsigned row = row0 + ai * HALF + m * 16;
;             if (n == 0) { mean[(i - LO) >> 1] = 0.f; rstd[(i - LO) >> 1] = 1.f;
;                 if (LN) { const float2 st = *(const float2*)(stats + row * 2u); mean[(i - LO) >> 1] = st.x; rstd[(i - LO) >> 1] = st.y; } }
;             r[i - LO] = *(const f32x4*)(src + (row * (unsigned)DM + col0 + BJ * HALF + n * 16)); }
; #pragma unroll
;         for (int i = LO; i < HI; ++i) { const int ai = i >> 3, m = (i >> 1) & 3, n = i & 1; const unsigned row = row0 + ai * HALF + m * 16;
;             *(f32x4*)(Y + (row * (unsigned)DM + col0 + BJ * HALF + n * 16)) = acc[ai][BJ][m][n] + ((r[i - LO] - mean[(i - LO) >> 1]) * rstd[(i - LO) >> 1]) * gv[n] + bv[n]; }
;         __builtin_amdgcn_sched_barrier(0);
;     }
;     template <bool LN, int BJ> DI void load_gb(unsigned col0, f32x4 (&gv)[2], f32x4 (&bv)[2]) const {
; #pragma unroll
;         for (int n = 0; n < 2; ++n) {
;             if (LN) { gv[n] = *(const f32x4*)(gam + col0 + BJ * HALF + n * 16) * ALPHA; bv[n] = *(const f32x4*)(bet + col0 + BJ * HALF + n * 16) * ALPHA; }
;             else { gv[n] = (f32x4){ALPHA, ALPHA, ALPHA, ALPHA}; bv[n] = (f32x4){0.f, 0.f, 0.f, 0.f}; }
;         }
;     }
;     template <bool LN> DI void run(const f32x4 (&acc)[2][2][4][2], const Unit& u, int wr, int wc, int fr, int fq) const {
;         const unsigned row0 = u.pm * BM + wr * 64 + fr, col0 = u.pn * BM + wc * 32 + 4 * fq;
;         f32x4 gv[2], bv[2];
;         load_gb<LN, 0>(col0, gv, bv);
;         batch<LN, 0, 0, 4>(acc, row0, col0, gv, bv);
;         batch<LN, 0, 4, 8>(acc, row0, col0, gv, bv);
;         batch<LN, 0, 8, 12>(acc, row0, col0, gv, bv);
;         batch<LN, 0, 12, 16>(acc, row0, col0, gv, bv);
	v_pk_fma_f32 v[130:131], v[98:99], s[78:79], v[130:131] op_sel_hi:[1,0,1]
	v_pk_fma_f32 v[128:129], v[96:97], s[78:79], v[128:129] op_sel_hi:[1,0,1]
	global_store_dwordx4 v[132:133], v[128:131], off
	s_nop 1
	v_sub_f32_e32 v129, v215, v196
	v_sub_f32_e32 v128, v214, v196
	v_sub_f32_e32 v131, v217, v196
	v_sub_f32_e32 v130, v216, v196
	v_pk_mul_f32 v[130:131], v[196:197], v[130:131] op_sel:[1,0]
	v_pk_mul_f32 v[128:129], v[196:197], v[128:129] op_sel:[1,0]
	v_pk_fma_f32 v[126:127], v[192:193], v[130:131], v[126:127]
	v_pk_fma_f32 v[124:125], v[194:195], v[128:129], v[124:125]
	v_add_u32_e32 v128, 0x8000, v148
	v_mov_b32_e32 v129, v159
	v_pk_fma_f32 v[126:127], v[102:103], s[78:79], v[126:127] op_sel_hi:[1,0,1]
	v_pk_fma_f32 v[124:125], v[100:101], s[78:79], v[124:125] op_sel_hi:[1,0,1]
	v_lshl_add_u64 v[128:129], v[128:129], 2, s[88:89]
	global_store_dwordx4 v[128:129], v[124:127], off
	s_nop 1
	v_sub_f32_e32 v125, v137, v196
	v_sub_f32_e32 v124, v136, v196
	v_sub_f32_e32 v127, v139, v196
	v_sub_f32_e32 v126, v138, v196
	v_pk_mul_f32 v[126:127], v[196:197], v[126:127] op_sel:[1,0]
	v_pk_mul_f32 v[124:125], v[196:197], v[124:125] op_sel:[1,0]
	v_pk_fma_f32 v[122:123], v[188:189], v[126:127], v[122:123]
	v_pk_fma_f32 v[120:121], v[190:191], v[124:125], v[120:121]
	v_add_u32_e32 v124, 0x8010, v148
	v_mov_b32_e32 v125, v159
	v_pk_fma_f32 v[122:123], v[98:99], s[78:79], v[122:123] op_sel_hi:[1,0,1]
	v_pk_fma_f32 v[120:121], v[96:97], s[78:79], v[120:121] op_sel_hi:[1,0,1]
	v_lshl_add_u64 v[124:125], v[124:125], 2, s[88:89]
	global_store_dwordx4 v[124:125], v[120:123], off
	s_nop 1
	v_or_b32_e32 v122, 32, v203
	v_lshlrev_b32_e32 v124, 11, v122
	v_lshlrev_b32_e32 v120, 1, v122
	v_mov_b32_e32 v121, v159
	v_add_u32_e32 v122, v124, v158
	v_mov_b32_e32 v123, v159
	v_lshl_add_u64 v[120:121], v[120:121], 2, s[96:97]
	v_lshl_add_u64 v[122:123], v[122:123], 2, s[90:91]
	global_load_dwordx2 v[138:139], v[120:121], off
	global_load_dwordx4 v[126:129], v[122:123], off
	v_add_u32_e32 v122, v124, v204
	v_mov_b32_e32 v123, v159
	v_lshl_add_u64 v[122:123], v[122:123], 2, s[90:91]
	global_load_dwordx4 v[130:133], v[122:123], off
	v_or_b32_e32 v125, 48, v203
	v_lshlrev_b32_e32 v122, 1, v125
	v_lshlrev_b32_e32 v125, 11, v125
	v_mov_b32_e32 v123, v159
	v_add_u32_e32 v134, v125, v158
	v_mov_b32_e32 v135, v159
	v_lshl_add_u64 v[122:123], v[122:123], 2, s[96:97]
	v_lshl_add_u64 v[134:135], v[134:135], 2, s[90:91]
	global_load_dwordx2 v[196:197], v[122:123], off
	v_add_u32_e32 v206, v125, v204
	global_load_dwordx4 v[134:137], v[134:135], off
	v_mov_b32_e32 v207, v159
	v_lshl_add_u64 v[206:207], v[206:207], 2, s[90:91]
	global_load_dwordx4 v[206:209], v[206:207], off
	s_waitcnt vmcnt(0)
	v_sub_f32_e32 v127, v127, v138
	v_sub_f32_e32 v126, v126, v138
	v_sub_f32_e32 v129, v129, v138
	v_sub_f32_e32 v128, v128, v138
	v_pk_mul_f32 v[128:129], v[138:139], v[128:129] op_sel:[1,0]
	v_pk_mul_f32 v[126:127], v[138:139], v[126:127] op_sel:[1,0]
	v_pk_fma_f32 v[118:119], v[192:193], v[128:129], v[118:119]
	v_pk_fma_f32 v[116:117], v[194:195], v[126:127], v[116:117]
	v_add_u32_e32 v126, 0x10000, v148
	v_mov_b32_e32 v127, v159
	v_pk_fma_f32 v[118:119], v[102:103], s[78:79], v[118:119] op_sel_hi:[1,0,1]
	v_pk_fma_f32 v[116:117], v[100:101], s[78:79], v[116:117] op_sel_hi:[1,0,1]
	v_lshl_add_u64 v[126:127], v[126:127], 2, s[88:89]
	global_store_dwordx4 v[126:127], v[116:119], off
	s_nop 1
	v_sub_f32_e32 v117, v131, v138
	v_sub_f32_e32 v116, v130, v138
	v_sub_f32_e32 v119, v133, v138
	v_sub_f32_e32 v118, v132, v138
	v_pk_mul_f32 v[118:119], v[138:139], v[118:119] op_sel:[1,0]
	v_pk_mul_f32 v[116:117], v[138:139], v[116:117] op_sel:[1,0]
	v_pk_fma_f32 v[114:115], v[188:189], v[118:119], v[114:115]
	v_pk_fma_f32 v[112:113], v[190:191], v[116:117], v[112:113]
	v_add_u32_e32 v116, 0x10010, v148
	v_mov_b32_e32 v117, v159
	v_pk_fma_f32 v[114:115], v[98:99], s[78:79], v[114:115] op_sel_hi:[1,0,1]
	v_pk_fma_f32 v[112:113], v[96:97], s[78:79], v[112:113] op_sel_hi:[1,0,1]
	v_lshl_add_u64 v[116:117], v[116:117], 2, s[88:89]
	global_store_dwordx4 v[116:117], v[112:115], off
	s_nop 1
	v_sub_f32_e32 v113, v135, v196
	v_sub_f32_e32 v112, v134, v196
	v_sub_f32_e32 v115, v137, v196
	v_sub_f32_e32 v114, v136, v196
	v_pk_mul_f32 v[114:115], v[196:197], v[114:115] op_sel:[1,0]
	v_pk_mul_f32 v[112:113], v[196:197], v[112:113] op_sel:[1,0]
	v_pk_fma_f32 v[110:111], v[192:193], v[114:115], v[110:111]
	v_pk_fma_f32 v[108:109], v[194:195], v[112:113], v[108:109]
	v_add_u32_e32 v112, 0x18000, v148
	v_mov_b32_e32 v113, v159
	v_pk_fma_f32 v[110:111], v[102:103], s[78:79], v[110:111] op_sel_hi:[1,0,1]
	v_pk_fma_f32 v[108:109], v[100:101], s[78:79], v[108:109] op_sel_hi:[1,0,1]
	v_lshl_add_u64 v[112:113], v[112:113], 2, s[88:89]
	global_store_dwordx4 v[112:113], v[108:111], off
	s_nop 1
	v_sub_f32_e32 v109, v207, v196
	v_sub_f32_e32 v108, v206, v196
	v_sub_f32_e32 v111, v209, v196
	v_sub_f32_e32 v110, v208, v196
	v_pk_mul_f32 v[110:111], v[196:197], v[110:111] op_sel:[1,0]
	v_pk_mul_f32 v[108:109], v[196:197], v[108:109] op_sel:[1,0]
	v_pk_fma_f32 v[106:107], v[188:189], v[110:111], v[106:107]
	v_pk_fma_f32 v[104:105], v[190:191], v[108:109], v[104:105]
	v_add_u32_e32 v108, 0x18010, v148
	v_mov_b32_e32 v109, v159
	v_pk_fma_f32 v[106:107], v[98:99], s[78:79], v[106:107] op_sel_hi:[1,0,1]
	v_pk_fma_f32 v[104:105], v[96:97], s[78:79], v[104:105] op_sel_hi:[1,0,1]
	v_lshl_add_u64 v[108:109], v[108:109], 2, s[88:89]
	global_store_dwordx4 v[108:109], v[104:107], off
	s_nop 1
	v_add_u32_e32 v106, 0x80, v203
	v_lshlrev_b32_e32 v114, 11, v106
	v_lshlrev_b32_e32 v104, 1, v106
	v_mov_b32_e32 v105, v159
	v_add_u32_e32 v106, v114, v158
	v_mov_b32_e32 v107, v159
	v_lshl_add_u64 v[104:105], v[104:105], 2, s[96:97]
	v_lshl_add_u64 v[106:107], v[106:107], 2, s[90:91]
	global_load_dwordx2 v[112:113], v[104:105], off
	global_load_dwordx4 v[108:111], v[106:107], off
	v_add_u32_e32 v106, v114, v204
	v_mov_b32_e32 v107, v159
	v_lshl_add_u64 v[106:107], v[106:107], 2, s[90:91]
	global_load_dwordx4 v[116:119], v[106:107], off
	v_add_u32_e32 v115, 0x90, v203
	v_lshlrev_b32_e32 v106, 1, v115
	v_lshlrev_b32_e32 v115, 11, v115
	v_mov_b32_e32 v107, v159
	v_add_u32_e32 v126, v115, v158
	v_mov_b32_e32 v127, v159
	v_lshl_add_u64 v[106:107], v[106:107], 2, s[96:97]
	v_lshl_add_u64 v[126:127], v[126:127], 2, s[90:91]
	global_load_dwordx2 v[134:135], v[106:107], off
	v_add_u32_e32 v130, v115, v204
	global_load_dwordx4 v[126:129], v[126:127], off
	v_mov_b32_e32 v131, v159
	v_lshl_add_u64 v[130:131], v[130:131], 2, s[90:91]
	global_load_dwordx4 v[130:133], v[130:131], off
	s_waitcnt vmcnt(0)
;     template <bool LN, int BJ, int LO, int HI> DI void batch(const f32x4 (&acc)[2][2][4][2], unsigned row0, unsigned col0, const f32x4 (&gv)[2], const f32x4 (&bv)[2]) const {
;         f32x4 r[HI - LO]; float mean[(HI - LO) / 2], rstd[(HI - LO) / 2];
; #pragma unroll
;         for (int i = LO; i < HI; ++i) { const int ai = i >> 3, m = (i >> 1) & 3, n = i & 1; const unsigned row = row0 + ai * HALF + m * 16;
;             if (n == 0) { mean[(i - LO) >> 1] = 0.f; rstd[(i - LO) >> 1] = 1.f;
;                 if (LN) { const float2 st = *(const float2*)(stats + row * 2u); mean[(i - LO) >> 1] = st.x; rstd[(i - LO) >> 1] = st.y; } }
;             r[i - LO] = *(const f32x4*)(src + (row * (unsigned)DM + col0 + BJ * HALF + n * 16)); }
; #pragma unroll
;         for (int i = LO; i < HI; ++i) { const int ai = i >> 3, m = (i >> 1) & 3, n = i & 1; const unsigned row = row0 + ai * HALF + m * 16;
;             *(f32x4*)(Y + (row * (unsigned)DM + col0 + BJ * HALF + n * 16)) = acc[ai][BJ][m][n] + ((r[i - LO] - mean[(i - LO) >> 1]) * rstd[(i - LO) >> 1]) * gv[n] + bv[n]; }
;         __builtin_amdgcn_sched_barrier(0);
;     }
;     template <bool LN, int BJ> DI void load_gb(unsigned col0, f32x4 (&gv)[2], f32x4 (&bv)[2]) const {
; #pragma unroll
;         for (int n = 0; n < 2; ++n) {
;             if (LN) { gv[n] = *(const f32x4*)(gam + col0 + BJ * HALF + n * 16) * ALPHA; bv[n] = *(const f32x4*)(bet + col0 + BJ * HALF + n * 16) * ALPHA; }
;             else { gv[n] = (f32x4){ALPHA, ALPHA, ALPHA, ALPHA}; bv[n] = (f32x4){0.f, 0.f, 0.f, 0.f}; }
;         }
;     }
;     template <bool LN> DI void run(const f32x4 (&acc)[2][2][4][2], const Unit& u, int wr, int wc, int fr, int fq) const {
;         const unsigned row0 = u.pm * BM + wr * 64 + fr, col0 = u.pn * BM + wc * 32 + 4 * fq;
;         f32x4 gv[2], bv[2];
;         load_gb<LN, 0>(col0, gv, bv);
;         batch<LN, 0, 0, 4>(acc, row0, col0, gv, bv);
;         batch<LN, 0, 4, 8>(acc, row0, col0, gv, bv);
;         batch<LN, 0, 8, 12>(acc, row0, col0, gv, bv);
;         batch<LN, 0, 12, 16>(acc, row0, col0, gv, bv);
	v_sub_f32_e32 v109, v109, v112
	v_sub_f32_e32 v108, v108, v112
	v_sub_f32_e32 v111, v111, v112
	v_sub_f32_e32 v110, v110, v112
	v_pk_mul_f32 v[110:111], v[112:113], v[110:111] op_sel:[1,0]
	v_pk_mul_f32 v[108:109], v[112:113], v[108:109] op_sel:[1,0]
	v_pk_fma_f32 v[94:95], v[192:193], v[110:111], v[94:95]
	v_pk_fma_f32 v[92:93], v[194:195], v[108:109], v[92:93]
	v_add_u32_e32 v108, 0x40000, v148
	v_mov_b32_e32 v109, v159
	v_pk_fma_f32 v[94:95], v[102:103], s[78:79], v[94:95] op_sel_hi:[1,0,1]
	v_pk_fma_f32 v[92:93], v[100:101], s[78:79], v[92:93] op_sel_hi:[1,0,1]
	v_lshl_add_u64 v[108:109], v[108:109], 2, s[88:89]
	global_store_dwordx4 v[108:109], v[92:95], off
	s_nop 1
	v_sub_f32_e32 v93, v117, v112
	v_sub_f32_e32 v92, v116, v112
	v_sub_f32_e32 v95, v119, v112
	v_sub_f32_e32 v94, v118, v112
	v_pk_mul_f32 v[94:95], v[112:113], v[94:95] op_sel:[1,0]
	v_pk_mul_f32 v[92:93], v[112:113], v[92:93] op_sel:[1,0]
	v_pk_fma_f32 v[90:91], v[188:189], v[94:95], v[90:91]
	v_pk_fma_f32 v[88:89], v[190:191], v[92:93], v[88:89]
	v_add_u32_e32 v92, 0x40010, v148
	v_mov_b32_e32 v93, v159
	v_pk_fma_f32 v[90:91], v[98:99], s[78:79], v[90:91] op_sel_hi:[1,0,1]
	v_pk_fma_f32 v[88:89], v[96:97], s[78:79], v[88:89] op_sel_hi:[1,0,1]
	v_lshl_add_u64 v[92:93], v[92:93], 2, s[88:89]
	global_store_dwordx4 v[92:93], v[88:91], off
	s_nop 1
	v_sub_f32_e32 v89, v127, v134
	v_sub_f32_e32 v88, v126, v134
	v_sub_f32_e32 v91, v129, v134
	v_sub_f32_e32 v90, v128, v134
	v_pk_mul_f32 v[90:91], v[134:135], v[90:91] op_sel:[1,0]
	v_pk_mul_f32 v[88:89], v[134:135], v[88:89] op_sel:[1,0]
	v_pk_fma_f32 v[86:87], v[192:193], v[90:91], v[86:87]
	v_pk_fma_f32 v[84:85], v[194:195], v[88:89], v[84:85]
	v_add_u32_e32 v88, 0x48000, v148
	v_mov_b32_e32 v89, v159
	v_pk_fma_f32 v[86:87], v[102:103], s[78:79], v[86:87] op_sel_hi:[1,0,1]
	v_pk_fma_f32 v[84:85], v[100:101], s[78:79], v[84:85] op_sel_hi:[1,0,1]
	v_lshl_add_u64 v[88:89], v[88:89], 2, s[88:89]
	global_store_dwordx4 v[88:89], v[84:87], off
	s_nop 1
	v_sub_f32_e32 v85, v131, v134
	v_sub_f32_e32 v84, v130, v134
	v_sub_f32_e32 v87, v133, v134
	v_sub_f32_e32 v86, v132, v134
	v_pk_mul_f32 v[86:87], v[134:135], v[86:87] op_sel:[1,0]
	v_pk_mul_f32 v[84:85], v[134:135], v[84:85] op_sel:[1,0]
	v_pk_fma_f32 v[82:83], v[188:189], v[86:87], v[82:83]
	v_pk_fma_f32 v[80:81], v[190:191], v[84:85], v[80:81]
	v_add_u32_e32 v84, 0x48010, v148
	v_mov_b32_e32 v85, v159
	v_pk_fma_f32 v[82:83], v[98:99], s[78:79], v[82:83] op_sel_hi:[1,0,1]
	v_pk_fma_f32 v[80:81], v[96:97], s[78:79], v[80:81] op_sel_hi:[1,0,1]
	v_lshl_add_u64 v[84:85], v[84:85], 2, s[88:89]
	global_store_dwordx4 v[84:85], v[80:83], off
	s_nop 1
	v_add_u32_e32 v82, 0xa0, v203
	v_lshlrev_b32_e32 v80, 1, v82
	v_mov_b32_e32 v81, v159
	v_lshlrev_b32_e32 v116, 11, v82
	v_lshl_add_u64 v[108:109], v[80:81], 2, s[96:97]
	v_add_u32_e32 v80, v116, v158
	v_lshl_add_u64 v[80:81], v[80:81], 2, s[90:91]
	global_load_dwordx2 v[112:113], v[108:109], off
	v_add_u32_e32 v84, v116, v204
	global_load_dwordx4 v[80:83], v[80:81], off
	v_mov_b32_e32 v85, v159
	v_lshl_add_u64 v[84:85], v[84:85], 2, s[90:91]
	global_load_dwordx4 v[84:87], v[84:85], off
	v_add_u32_e32 v90, 0xb0, v203
	v_lshlrev_b32_e32 v88, 1, v90
	v_mov_b32_e32 v89, v159
	v_lshlrev_b32_e32 v117, 11, v90
	v_lshl_add_u64 v[110:111], v[88:89], 2, s[96:97]
	v_add_u32_e32 v88, v117, v158
	v_lshl_add_u64 v[88:89], v[88:89], 2, s[90:91]
	global_load_dwordx2 v[118:119], v[110:111], off
	v_add_u32_e32 v92, v117, v204
	global_load_dwordx4 v[88:91], v[88:89], off
	v_mov_b32_e32 v93, v159
	v_lshl_add_u64 v[92:93], v[92:93], 2, s[90:91]
	global_load_dwordx4 v[92:95], v[92:93], off
	s_waitcnt vmcnt(0)
	v_sub_f32_e32 v81, v81, v112
	v_sub_f32_e32 v80, v80, v112
	v_sub_f32_e32 v83, v83, v112
	v_sub_f32_e32 v82, v82, v112
	v_pk_mul_f32 v[82:83], v[112:113], v[82:83] op_sel:[1,0]
	v_pk_mul_f32 v[80:81], v[112:113], v[80:81] op_sel:[1,0]
	v_pk_fma_f32 v[78:79], v[192:193], v[82:83], v[78:79]
	v_pk_fma_f32 v[76:77], v[194:195], v[80:81], v[76:77]
	v_add_u32_e32 v80, 0x50000, v148
	v_mov_b32_e32 v81, v159
	v_pk_fma_f32 v[78:79], v[102:103], s[78:79], v[78:79] op_sel_hi:[1,0,1]
	v_pk_fma_f32 v[76:77], v[100:101], s[78:79], v[76:77] op_sel_hi:[1,0,1]
	v_lshl_add_u64 v[80:81], v[80:81], 2, s[88:89]
	global_store_dwordx4 v[80:81], v[76:79], off
	s_nop 1
	v_sub_f32_e32 v77, v85, v112
	v_sub_f32_e32 v76, v84, v112
	v_sub_f32_e32 v79, v87, v112
	v_sub_f32_e32 v78, v86, v112
	v_pk_mul_f32 v[78:79], v[112:113], v[78:79] op_sel:[1,0]
	v_pk_mul_f32 v[76:77], v[112:113], v[76:77] op_sel:[1,0]
	v_pk_fma_f32 v[74:75], v[188:189], v[78:79], v[74:75]
	v_pk_fma_f32 v[72:73], v[190:191], v[76:77], v[72:73]
	v_add_u32_e32 v76, 0x50010, v148
	v_mov_b32_e32 v77, v159
	v_pk_fma_f32 v[74:75], v[98:99], s[78:79], v[74:75] op_sel_hi:[1,0,1]
	v_pk_fma_f32 v[72:73], v[96:97], s[78:79], v[72:73] op_sel_hi:[1,0,1]
	v_lshl_add_u64 v[76:77], v[76:77], 2, s[88:89]
	global_store_dwordx4 v[76:77], v[72:75], off
	s_nop 1
	v_sub_f32_e32 v73, v89, v118
	v_sub_f32_e32 v72, v88, v118
	v_sub_f32_e32 v75, v91, v118
	v_sub_f32_e32 v74, v90, v118
	v_pk_mul_f32 v[74:75], v[118:119], v[74:75] op_sel:[1,0]
	v_pk_mul_f32 v[72:73], v[118:119], v[72:73] op_sel:[1,0]
	v_pk_fma_f32 v[70:71], v[192:193], v[74:75], v[70:71]
	v_pk_fma_f32 v[68:69], v[194:195], v[72:73], v[68:69]
	v_add_u32_e32 v72, 0x58000, v148
	v_mov_b32_e32 v73, v159
	v_pk_fma_f32 v[70:71], v[102:103], s[78:79], v[70:71] op_sel_hi:[1,0,1]
	v_pk_fma_f32 v[68:69], v[100:101], s[78:79], v[68:69] op_sel_hi:[1,0,1]
	v_lshl_add_u64 v[72:73], v[72:73], 2, s[88:89]
	global_store_dwordx4 v[72:73], v[68:71], off
	s_nop 1
	v_sub_f32_e32 v69, v93, v118
	v_sub_f32_e32 v68, v92, v118
	v_sub_f32_e32 v71, v95, v118
	v_sub_f32_e32 v70, v94, v118
	v_pk_mul_f32 v[70:71], v[118:119], v[70:71] op_sel:[1,0]
	v_pk_mul_f32 v[68:69], v[118:119], v[68:69] op_sel:[1,0]
	v_pk_fma_f32 v[66:67], v[188:189], v[70:71], v[66:67]
	v_pk_fma_f32 v[64:65], v[190:191], v[68:69], v[64:65]
	v_add_u32_e32 v68, 0x58010, v148
	v_mov_b32_e32 v69, v159
	v_pk_fma_f32 v[66:67], v[98:99], s[78:79], v[66:67] op_sel_hi:[1,0,1]
	v_pk_fma_f32 v[64:65], v[96:97], s[78:79], v[64:65] op_sel_hi:[1,0,1]
	v_lshl_add_u64 v[68:69], v[68:69], 2, s[88:89]
	global_store_dwordx4 v[68:69], v[64:67], off
	global_load_dwordx4 v[64:67], v[150:151], off offset:512
	v_or_b32_e32 v119, 0x80, v158
	v_add_u32_e32 v72, v202, v119
	v_mov_b32_e32 v73, v159
	v_lshl_add_u64 v[72:73], v[72:73], 2, s[90:91]
	v_or_b32_e32 v118, 0x90, v158
	v_add_u32_e32 v158, v202, v118
	s_waitcnt vmcnt(0)
;     template <bool LN, int BJ, int LO, int HI> DI void batch(const f32x4 (&acc)[2][2][4][2], unsigned row0, unsigned col0, const f32x4 (&gv)[2], const f32x4 (&bv)[2]) const {
;         f32x4 r[HI - LO]; float mean[(HI - LO) / 2], rstd[(HI - LO) / 2];
; #pragma unroll
;         for (int i = LO; i < HI; ++i) { const int ai = i >> 3, m = (i >> 1) & 3, n = i & 1; const unsigned row = row0 + ai * HALF + m * 16;
;             if (n == 0) { mean[(i - LO) >> 1] = 0.f; rstd[(i - LO) >> 1] = 1.f;
;                 if (LN) { const float2 st = *(const float2*)(stats + row * 2u); mean[(i - LO) >> 1] = st.x; rstd[(i - LO) >> 1] = st.y; } }
;             r[i - LO] = *(const f32x4*)(src + (row * (unsigned)DM + col0 + BJ * HALF + n * 16)); }
; #pragma unroll
;         for (int i = LO; i < HI; ++i) { const int ai = i >> 3, m = (i >> 1) & 3, n = i & 1; const unsigned row = row0 + ai * HALF + m * 16;
;             *(f32x4*)(Y + (row * (unsigned)DM + col0 + BJ * HALF + n * 16)) = acc[ai][BJ][m][n] + ((r[i - LO] - mean[(i - LO) >> 1]) * rstd[(i - LO) >> 1]) * gv[n] + bv[n]; }
;         __builtin_amdgcn_sched_barrier(0);
;     template <bool LN> DI void run(const f32x4 (&acc)[2][2][4][2], const Unit& u, int wr, int wc, int fr, int fq) const {
;     ...
;         load_gb<LN, 1>(col0, gv, bv);
;         batch<LN, 1, 0, 8>(acc, row0, col0, gv, bv);
;         batch<LN, 1, 8, 16>(acc, row0, col0, gv, bv);
	v_pk_mul_f32 v[96:97], v[66:67], s[78:79] op_sel_hi:[1,0]
	v_pk_mul_f32 v[98:99], v[64:65], s[78:79] op_sel_hi:[1,0]
	global_load_dwordx4 v[68:71], v[152:153], off offset:512
	global_load_dwordx4 v[64:67], v[150:151], off offset:576
	global_load_dwordx2 v[138:139], v[154:155], off
	global_load_dwordx4 v[126:129], v[72:73], off
	v_lshl_add_u64 v[72:73], v[158:159], 2, s[90:91]
	v_add_u32_e32 v158, v149, v119
	s_waitcnt vmcnt(0)
	v_pk_mul_f32 v[92:93], v[66:67], s[78:79] op_sel_hi:[1,0]
	v_pk_mul_f32 v[94:95], v[64:65], s[78:79] op_sel_hi:[1,0]
	global_load_dwordx4 v[64:67], v[152:153], off offset:576
	global_load_dwordx4 v[130:133], v[72:73], off
	global_load_dwordx2 v[112:113], v[186:187], off
	v_lshl_add_u64 v[72:73], v[158:159], 2, s[90:91]
	global_load_dwordx4 v[134:137], v[72:73], off
	v_add_u32_e32 v158, v149, v118
	v_lshl_add_u64 v[72:73], v[158:159], 2, s[90:91]
	global_load_dwordx4 v[88:91], v[72:73], off
	global_load_dwordx2 v[102:103], v[120:121], off
	v_add_u32_e32 v158, v124, v119
	v_lshl_add_u64 v[72:73], v[158:159], 2, s[90:91]
	global_load_dwordx4 v[84:87], v[72:73], off
	v_add_u32_e32 v158, v124, v118
	v_lshl_add_u64 v[72:73], v[158:159], 2, s[90:91]
	global_load_dwordx4 v[80:83], v[72:73], off
	global_load_dwordx2 v[100:101], v[122:123], off
	v_add_u32_e32 v158, v125, v119
	v_lshl_add_u64 v[72:73], v[158:159], 2, s[90:91]
	global_load_dwordx4 v[76:79], v[72:73], off
	v_add_u32_e32 v158, v125, v118
	v_lshl_add_u64 v[72:73], v[158:159], 2, s[90:91]
	global_load_dwordx4 v[72:75], v[72:73], off
	v_sub_f32_e32 v121, v127, v138
	v_sub_f32_e32 v120, v126, v138
	v_sub_f32_e32 v123, v129, v138
	v_sub_f32_e32 v122, v128, v138
	v_pk_mul_f32 v[122:123], v[138:139], v[122:123] op_sel:[1,0]
	v_pk_mul_f32 v[120:121], v[138:139], v[120:121] op_sel:[1,0]
	v_or_b32_e32 v158, 0x80, v148
	v_pk_fma_f32 v[60:61], v[98:99], v[120:121], v[60:61]
	v_pk_fma_f32 v[62:63], v[96:97], v[122:123], v[62:63]
	v_pk_fma_f32 v[60:61], v[68:69], s[78:79], v[60:61] op_sel_hi:[1,0,1]
	v_pk_fma_f32 v[62:63], v[70:71], s[78:79], v[62:63] op_sel_hi:[1,0,1]
	v_lshl_add_u64 v[120:121], v[158:159], 2, s[88:89]
	global_store_dwordx4 v[120:121], v[60:63], off
	v_or_b32_e32 v158, 0x90, v148
	s_waitcnt vmcnt(0)
	v_sub_f32_e32 v61, v131, v138
	v_sub_f32_e32 v60, v130, v138
	v_sub_f32_e32 v63, v133, v138
	v_sub_f32_e32 v62, v132, v138
	v_pk_mul_f32 v[62:63], v[138:139], v[62:63] op_sel:[1,0]
	v_pk_mul_f32 v[60:61], v[138:139], v[60:61] op_sel:[1,0]
	v_pk_fma_f32 v[58:59], v[92:93], v[62:63], v[58:59]
	v_pk_fma_f32 v[56:57], v[94:95], v[60:61], v[56:57]
	v_pk_fma_f32 v[58:59], v[66:67], s[78:79], v[58:59] op_sel_hi:[1,0,1]
	v_pk_fma_f32 v[56:57], v[64:65], s[78:79], v[56:57] op_sel_hi:[1,0,1]
	v_lshl_add_u64 v[60:61], v[158:159], 2, s[88:89]
	global_store_dwordx4 v[60:61], v[56:59], off
	v_add_u32_e32 v158, 0x8080, v148
	s_nop 0
	v_sub_f32_e32 v57, v135, v112
	v_sub_f32_e32 v56, v134, v112
	v_sub_f32_e32 v59, v137, v112
	v_sub_f32_e32 v58, v136, v112
	v_pk_mul_f32 v[58:59], v[112:113], v[58:59] op_sel:[1,0]
	v_pk_mul_f32 v[56:57], v[112:113], v[56:57] op_sel:[1,0]
	v_pk_fma_f32 v[54:55], v[96:97], v[58:59], v[54:55]
	v_pk_fma_f32 v[52:53], v[98:99], v[56:57], v[52:53]
	v_pk_fma_f32 v[54:55], v[70:71], s[78:79], v[54:55] op_sel_hi:[1,0,1]
	v_pk_fma_f32 v[52:53], v[68:69], s[78:79], v[52:53] op_sel_hi:[1,0,1]
	v_lshl_add_u64 v[56:57], v[158:159], 2, s[88:89]
	global_store_dwordx4 v[56:57], v[52:55], off
	v_add_u32_e32 v158, 0x8090, v148
	s_nop 0
	v_sub_f32_e32 v53, v89, v112
	v_sub_f32_e32 v52, v88, v112
	v_sub_f32_e32 v55, v91, v112
	v_sub_f32_e32 v54, v90, v112
	v_pk_mul_f32 v[54:55], v[112:113], v[54:55] op_sel:[1,0]
	v_pk_mul_f32 v[52:53], v[112:113], v[52:53] op_sel:[1,0]
	v_pk_fma_f32 v[50:51], v[92:93], v[54:55], v[50:51]
	v_pk_fma_f32 v[48:49], v[94:95], v[52:53], v[48:49]
	v_pk_fma_f32 v[50:51], v[66:67], s[78:79], v[50:51] op_sel_hi:[1,0,1]
	v_pk_fma_f32 v[48:49], v[64:65], s[78:79], v[48:49] op_sel_hi:[1,0,1]
	v_lshl_add_u64 v[52:53], v[158:159], 2, s[88:89]
	global_store_dwordx4 v[52:53], v[48:51], off
	v_add_u32_e32 v158, 0x10080, v148
	s_nop 0
	v_sub_f32_e32 v49, v85, v102
	v_sub_f32_e32 v48, v84, v102
	v_sub_f32_e32 v51, v87, v102
	v_sub_f32_e32 v50, v86, v102
	v_pk_mul_f32 v[50:51], v[102:103], v[50:51] op_sel:[1,0]
	v_pk_mul_f32 v[48:49], v[102:103], v[48:49] op_sel:[1,0]
	v_pk_fma_f32 v[46:47], v[96:97], v[50:51], v[46:47]
	v_pk_fma_f32 v[44:45], v[98:99], v[48:49], v[44:45]
	v_pk_fma_f32 v[46:47], v[70:71], s[78:79], v[46:47] op_sel_hi:[1,0,1]
	v_pk_fma_f32 v[44:45], v[68:69], s[78:79], v[44:45] op_sel_hi:[1,0,1]
	v_lshl_add_u64 v[48:49], v[158:159], 2, s[88:89]
	global_store_dwordx4 v[48:49], v[44:47], off
	v_add_u32_e32 v158, 0x10090, v148
	s_nop 0
	v_sub_f32_e32 v45, v81, v102
	v_sub_f32_e32 v44, v80, v102
	v_sub_f32_e32 v47, v83, v102
	v_sub_f32_e32 v46, v82, v102
	v_pk_mul_f32 v[46:47], v[102:103], v[46:47] op_sel:[1,0]
	v_pk_mul_f32 v[44:45], v[102:103], v[44:45] op_sel:[1,0]
	v_pk_fma_f32 v[42:43], v[92:93], v[46:47], v[42:43]
	v_pk_fma_f32 v[40:41], v[94:95], v[44:45], v[40:41]
	v_pk_fma_f32 v[42:43], v[66:67], s[78:79], v[42:43] op_sel_hi:[1,0,1]
	v_pk_fma_f32 v[40:41], v[64:65], s[78:79], v[40:41] op_sel_hi:[1,0,1]
	v_lshl_add_u64 v[44:45], v[158:159], 2, s[88:89]
	global_store_dwordx4 v[44:45], v[40:43], off
	v_add_u32_e32 v158, 0x18080, v148
	s_nop 0
	v_sub_f32_e32 v41, v77, v100
	v_sub_f32_e32 v40, v76, v100
	v_sub_f32_e32 v43, v79, v100
	v_sub_f32_e32 v42, v78, v100
	v_pk_mul_f32 v[42:43], v[100:101], v[42:43] op_sel:[1,0]
	v_pk_mul_f32 v[40:41], v[100:101], v[40:41] op_sel:[1,0]
	v_pk_fma_f32 v[38:39], v[96:97], v[42:43], v[38:39]
;     template <bool LN, int BJ, int LO, int HI> DI void batch(const f32x4 (&acc)[2][2][4][2], unsigned row0, unsigned col0, const f32x4 (&gv)[2], const f32x4 (&bv)[2]) const {
;         f32x4 r[HI - LO]; float mean[(HI - LO) / 2], rstd[(HI - LO) / 2];
; #pragma unroll
;         for (int i = LO; i < HI; ++i) { const int ai = i >> 3, m = (i >> 1) & 3, n = i & 1; const unsigned row = row0 + ai * HALF + m * 16;
;             if (n == 0) { mean[(i - LO) >> 1] = 0.f; rstd[(i - LO) >> 1] = 1.f;
;                 if (LN) { const float2 st = *(const float2*)(stats + row * 2u); mean[(i - LO) >> 1] = st.x; rstd[(i - LO) >> 1] = st.y; } }
;             r[i - LO] = *(const f32x4*)(src + (row * (unsigned)DM + col0 + BJ * HALF + n * 16)); }
; #pragma unroll
;         for (int i = LO; i < HI; ++i) { const int ai = i >> 3, m = (i >> 1) & 3, n = i & 1; const unsigned row = row0 + ai * HALF + m * 16;
;             *(f32x4*)(Y + (row * (unsigned)DM + col0 + BJ * HALF + n * 16)) = acc[ai][BJ][m][n] + ((r[i - LO] - mean[(i - LO) >> 1]) * rstd[(i - LO) >> 1]) * gv[n] + bv[n]; }
;         __builtin_amdgcn_sched_barrier(0);
	v_pk_fma_f32 v[36:37], v[98:99], v[40:41], v[36:37]
	v_pk_fma_f32 v[38:39], v[70:71], s[78:79], v[38:39] op_sel_hi:[1,0,1]
	v_pk_fma_f32 v[36:37], v[68:69], s[78:79], v[36:37] op_sel_hi:[1,0,1]
	v_lshl_add_u64 v[40:41], v[158:159], 2, s[88:89]
	global_store_dwordx4 v[40:41], v[36:39], off
	v_add_u32_e32 v158, 0x18090, v148
	s_nop 0
	v_sub_f32_e32 v37, v73, v100
	v_sub_f32_e32 v36, v72, v100
	v_sub_f32_e32 v39, v75, v100
	v_sub_f32_e32 v38, v74, v100
	v_pk_mul_f32 v[38:39], v[100:101], v[38:39] op_sel:[1,0]
	v_pk_mul_f32 v[36:37], v[100:101], v[36:37] op_sel:[1,0]
	v_pk_fma_f32 v[34:35], v[92:93], v[38:39], v[34:35]
	v_pk_fma_f32 v[32:33], v[94:95], v[36:37], v[32:33]
	v_pk_fma_f32 v[34:35], v[66:67], s[78:79], v[34:35] op_sel_hi:[1,0,1]
	v_pk_fma_f32 v[32:33], v[64:65], s[78:79], v[32:33] op_sel_hi:[1,0,1]
	v_lshl_add_u64 v[36:37], v[158:159], 2, s[88:89]
	global_store_dwordx4 v[36:37], v[32:35], off
	v_add_u32_e32 v158, v114, v119
	s_nop 0
	v_lshl_add_u64 v[32:33], v[158:159], 2, s[90:91]
	global_load_dwordx2 v[62:63], v[104:105], off
	global_load_dwordx4 v[54:57], v[32:33], off
	v_add_u32_e32 v158, v114, v118
	v_lshl_add_u64 v[32:33], v[158:159], 2, s[90:91]
	global_load_dwordx4 v[58:61], v[32:33], off
	global_load_dwordx2 v[52:53], v[106:107], off
	v_add_u32_e32 v158, v115, v119
	v_lshl_add_u64 v[32:33], v[158:159], 2, s[90:91]
	global_load_dwordx4 v[72:75], v[32:33], off
	v_add_u32_e32 v158, v115, v118
	v_lshl_add_u64 v[32:33], v[158:159], 2, s[90:91]
	global_load_dwordx4 v[76:79], v[32:33], off
	global_load_dwordx2 v[50:51], v[108:109], off
	v_add_u32_e32 v158, v116, v119
	v_lshl_add_u64 v[32:33], v[158:159], 2, s[90:91]
	global_load_dwordx4 v[44:47], v[32:33], off
	v_add_u32_e32 v158, v116, v118
	v_lshl_add_u64 v[32:33], v[158:159], 2, s[90:91]
	global_load_dwordx4 v[40:43], v[32:33], off
	global_load_dwordx2 v[48:49], v[110:111], off
	v_add_u32_e32 v158, v117, v119
	v_lshl_add_u64 v[32:33], v[158:159], 2, s[90:91]
	global_load_dwordx4 v[36:39], v[32:33], off
	v_add_u32_e32 v158, v117, v118
	v_lshl_add_u64 v[32:33], v[158:159], 2, s[90:91]
	global_load_dwordx4 v[32:35], v[32:33], off
	v_add_u32_e32 v158, 0x40080, v148
	s_waitcnt vmcnt(0)
; #define PG8_WAIT_V(n) asm volatile("s_waitcnt vmcnt(" #n ")" ::: "memory")
; #define PG8_BAR __builtin_amdgcn_s_barrier()
; template <class Epi>
; DI void gemm_phase(LAS unsigned char* lds, const Gemm g, const StaticOrder& S, const Epi& E) {
;     ...
;         E(acc, cur, wr, wc, fr, fq);
;         if (!has_next) break;
; #pragma unroll
;         for (int a = 0; a < 2; ++a)
; #pragma unroll
;             for (int b = 0; b < 2; ++b)
; #pragma unroll
;                 for (int m = 0; m < 4; ++m)
; #pragma unroll
;                     for (int n = 0; n < 2; ++n) acc[a][b][m][n] = (f32x4){0.f, 0.f, 0.f, 0.f};
;         cur = nxt; cA = nA; cB = nB; ++ui;
;     }
;     PG8_WAIT_V(0);
;     if (wr == 0) PG8_BAR;
;     PG8_BAR;
;     template <bool LN, int BJ, int LO, int HI> DI void batch(const f32x4 (&acc)[2][2][4][2], unsigned row0, unsigned col0, const f32x4 (&gv)[2], const f32x4 (&bv)[2]) const {
;         f32x4 r[HI - LO]; float mean[(HI - LO) / 2], rstd[(HI - LO) / 2];
; #pragma unroll
;         for (int i = LO; i < HI; ++i) { const int ai = i >> 3, m = (i >> 1) & 3, n = i & 1; const unsigned row = row0 + ai * HALF + m * 16;
;             if (n == 0) { mean[(i - LO) >> 1] = 0.f; rstd[(i - LO) >> 1] = 1.f;
;                 if (LN) { const float2 st = *(const float2*)(stats + row * 2u); mean[(i - LO) >> 1] = st.x; rstd[(i - LO) >> 1] = st.y; } }
;             r[i - LO] = *(const f32x4*)(src + (row * (unsigned)DM + col0 + BJ * HALF + n * 16)); }
; #pragma unroll
;         for (int i = LO; i < HI; ++i) { const int ai = i >> 3, m = (i >> 1) & 3, n = i & 1; const unsigned row = row0 + ai * HALF + m * 16;
;             *(f32x4*)(Y + (row * (unsigned)DM + col0 + BJ * HALF + n * 16)) = acc[ai][BJ][m][n] + ((r[i - LO] - mean[(i - LO) >> 1]) * rstd[(i - LO) >> 1]) * gv[n] + bv[n]; }
;         __builtin_amdgcn_sched_barrier(0);
	v_sub_f32_e32 v55, v55, v62
	v_sub_f32_e32 v54, v54, v62
	v_sub_f32_e32 v57, v57, v62
	v_sub_f32_e32 v56, v56, v62
	v_pk_mul_f32 v[56:57], v[62:63], v[56:57] op_sel:[1,0]
	v_pk_mul_f32 v[54:55], v[62:63], v[54:55] op_sel:[1,0]
	v_pk_fma_f32 v[30:31], v[96:97], v[56:57], v[30:31]
	v_pk_fma_f32 v[28:29], v[98:99], v[54:55], v[28:29]
	v_pk_fma_f32 v[30:31], v[70:71], s[78:79], v[30:31] op_sel_hi:[1,0,1]
	v_pk_fma_f32 v[28:29], v[68:69], s[78:79], v[28:29] op_sel_hi:[1,0,1]
	v_lshl_add_u64 v[54:55], v[158:159], 2, s[88:89]
	global_store_dwordx4 v[54:55], v[28:31], off
	v_add_u32_e32 v158, 0x40090, v148
	s_nop 0
	v_sub_f32_e32 v29, v59, v62
	v_sub_f32_e32 v28, v58, v62
	v_sub_f32_e32 v31, v61, v62
	v_sub_f32_e32 v30, v60, v62
	v_pk_mul_f32 v[30:31], v[62:63], v[30:31] op_sel:[1,0]
	v_pk_mul_f32 v[28:29], v[62:63], v[28:29] op_sel:[1,0]
	v_pk_fma_f32 v[26:27], v[92:93], v[30:31], v[26:27]
	v_pk_fma_f32 v[24:25], v[94:95], v[28:29], v[24:25]
	v_pk_fma_f32 v[26:27], v[66:67], s[78:79], v[26:27] op_sel_hi:[1,0,1]
	v_pk_fma_f32 v[24:25], v[64:65], s[78:79], v[24:25] op_sel_hi:[1,0,1]
	v_lshl_add_u64 v[28:29], v[158:159], 2, s[88:89]
	global_store_dwordx4 v[28:29], v[24:27], off
	v_add_u32_e32 v158, 0x48080, v148
	s_nop 0
	v_sub_f32_e32 v25, v73, v52
	v_sub_f32_e32 v24, v72, v52
	v_sub_f32_e32 v27, v75, v52
	v_sub_f32_e32 v26, v74, v52
	v_pk_mul_f32 v[26:27], v[52:53], v[26:27] op_sel:[1,0]
	v_pk_mul_f32 v[24:25], v[52:53], v[24:25] op_sel:[1,0]
	v_pk_fma_f32 v[22:23], v[96:97], v[26:27], v[22:23]
	v_pk_fma_f32 v[20:21], v[98:99], v[24:25], v[20:21]
	v_pk_fma_f32 v[22:23], v[70:71], s[78:79], v[22:23] op_sel_hi:[1,0,1]
	v_pk_fma_f32 v[20:21], v[68:69], s[78:79], v[20:21] op_sel_hi:[1,0,1]
	v_lshl_add_u64 v[24:25], v[158:159], 2, s[88:89]
	global_store_dwordx4 v[24:25], v[20:23], off
	v_add_u32_e32 v158, 0x48090, v148
	s_nop 0
	v_sub_f32_e32 v21, v77, v52
	v_sub_f32_e32 v20, v76, v52
	v_sub_f32_e32 v23, v79, v52
	v_sub_f32_e32 v22, v78, v52
	v_pk_mul_f32 v[22:23], v[52:53], v[22:23] op_sel:[1,0]
	v_pk_mul_f32 v[20:21], v[52:53], v[20:21] op_sel:[1,0]
	v_pk_fma_f32 v[18:19], v[92:93], v[22:23], v[18:19]
	v_pk_fma_f32 v[16:17], v[94:95], v[20:21], v[16:17]
	v_pk_fma_f32 v[18:19], v[66:67], s[78:79], v[18:19] op_sel_hi:[1,0,1]
	v_pk_fma_f32 v[16:17], v[64:65], s[78:79], v[16:17] op_sel_hi:[1,0,1]
	v_lshl_add_u64 v[20:21], v[158:159], 2, s[88:89]
	global_store_dwordx4 v[20:21], v[16:19], off
	v_add_u32_e32 v158, 0x50080, v148
	s_nop 0
	v_sub_f32_e32 v17, v45, v50
	v_sub_f32_e32 v16, v44, v50
	v_sub_f32_e32 v19, v47, v50
	v_sub_f32_e32 v18, v46, v50
	v_pk_mul_f32 v[18:19], v[50:51], v[18:19] op_sel:[1,0]
	v_pk_mul_f32 v[16:17], v[50:51], v[16:17] op_sel:[1,0]
	v_pk_fma_f32 v[14:15], v[96:97], v[18:19], v[14:15]
	v_pk_fma_f32 v[12:13], v[98:99], v[16:17], v[12:13]
	v_pk_fma_f32 v[14:15], v[70:71], s[78:79], v[14:15] op_sel_hi:[1,0,1]
	v_pk_fma_f32 v[12:13], v[68:69], s[78:79], v[12:13] op_sel_hi:[1,0,1]
	v_lshl_add_u64 v[16:17], v[158:159], 2, s[88:89]
	global_store_dwordx4 v[16:17], v[12:15], off
	v_add_u32_e32 v158, 0x50090, v148
	s_nop 0
	v_sub_f32_e32 v13, v41, v50
	v_sub_f32_e32 v12, v40, v50
	v_sub_f32_e32 v15, v43, v50
	v_sub_f32_e32 v14, v42, v50
	v_pk_mul_f32 v[14:15], v[50:51], v[14:15] op_sel:[1,0]
	v_pk_mul_f32 v[12:13], v[50:51], v[12:13] op_sel:[1,0]
	v_pk_fma_f32 v[10:11], v[92:93], v[14:15], v[10:11]
	v_pk_fma_f32 v[8:9], v[94:95], v[12:13], v[8:9]
	v_pk_fma_f32 v[10:11], v[66:67], s[78:79], v[10:11] op_sel_hi:[1,0,1]
	v_pk_fma_f32 v[8:9], v[64:65], s[78:79], v[8:9] op_sel_hi:[1,0,1]
	v_lshl_add_u64 v[12:13], v[158:159], 2, s[88:89]
	global_store_dwordx4 v[12:13], v[8:11], off
	v_add_u32_e32 v158, 0x58080, v148
	s_nop 0
	v_sub_f32_e32 v9, v37, v48
	v_sub_f32_e32 v8, v36, v48
	v_sub_f32_e32 v11, v39, v48
	v_sub_f32_e32 v10, v38, v48
	v_pk_mul_f32 v[10:11], v[48:49], v[10:11] op_sel:[1,0]
	v_pk_mul_f32 v[8:9], v[48:49], v[8:9] op_sel:[1,0]
	v_pk_fma_f32 v[6:7], v[96:97], v[10:11], v[6:7]
	v_pk_fma_f32 v[4:5], v[98:99], v[8:9], v[4:5]
	v_pk_fma_f32 v[6:7], v[70:71], s[78:79], v[6:7] op_sel_hi:[1,0,1]
	v_pk_fma_f32 v[4:5], v[68:69], s[78:79], v[4:5] op_sel_hi:[1,0,1]
	v_lshl_add_u64 v[8:9], v[158:159], 2, s[88:89]
	global_store_dwordx4 v[8:9], v[4:7], off
	v_add_u32_e32 v158, 0x58090, v148
	s_nop 0
	v_sub_f32_e32 v5, v33, v48
	v_sub_f32_e32 v4, v32, v48
	v_sub_f32_e32 v7, v35, v48
	v_sub_f32_e32 v6, v34, v48
	v_pk_mul_f32 v[6:7], v[48:49], v[6:7] op_sel:[1,0]
	v_pk_mul_f32 v[4:5], v[48:49], v[4:5] op_sel:[1,0]
	v_pk_fma_f32 v[2:3], v[92:93], v[6:7], v[2:3]
	v_pk_fma_f32 v[0:1], v[94:95], v[4:5], v[0:1]
	v_pk_fma_f32 v[2:3], v[66:67], s[78:79], v[2:3] op_sel_hi:[1,0,1]
	v_pk_fma_f32 v[0:1], v[64:65], s[78:79], v[0:1] op_sel_hi:[1,0,1]
	v_lshl_add_u64 v[4:5], v[158:159], 2, s[88:89]
	global_store_dwordx4 v[4:5], v[0:3], off
	s_and_b64 vcc, exec, s[6:7]
	s_mov_b32 s2, s37
	s_mov_b32 s3, s38
	s_mov_b64 s[18:19], s[10:11]
	s_mov_b64 s[16:17], s[8:9]
	v_readlane_b32 s33, v255, 39
	s_cbranch_vccz .LBB0_123
	s_waitcnt vmcnt(0)
	s_cmpk_gt_u32 s24, 0xff
	s_cbranch_scc1 .LBB0_138
	s_barrier

; #define PG8_STAGE(bufoff, gbase) do { _Pragma("unroll") for (int _i = 0; _i < 2; ++_i) \
;         __builtin_amdgcn_global_load_lds((const unsigned*)((const char*)(gbase) + voff[_i]), (LAS unsigned*)(lds + (bufoff) + ldsw + _i * 8192), 16, 0, 0); } while (0)
; #define PG8_LDA(dst, b, h) do { _Pragma("unroll") for (int m = 0; m < 4; ++m) _Pragma("unroll") for (int k = 0; k < 2; ++k) dst[m][k] = *(const LAS bf16x8*)(lds + PG8_SA(b, h) + aoff + m * 2048 + k * 1024); } while (0)
; #define PG8_LDB(dst, b, h) do { _Pragma("unroll") for (int n = 0; n < 2; ++n) _Pragma("unroll") for (int k = 0; k < 2; ++k) dst[n][k] = *(const LAS bf16x8*)(lds + PG8_SB(b, h) + boff + n * 2048 + k * 1024); } while (0)
; #define PG8_MMA(ai, bj, At, Bt) do { __builtin_amdgcn_s_setprio(1); _Pragma("unroll") for (int m = 0; m < 4; ++m) _Pragma("unroll") for (int n = 0; n < 2; ++n) _Pragma("unroll") for (int k = 0; k < 2; ++k) \
;         acc[ai][bj][m][n] = __builtin_amdgcn_mfma_f32_16x16x32_bf16(Bt[n][k], At[m][k], acc[ai][bj][m][n], 0, 0, 0); __builtin_amdgcn_s_setprio(0); } while (0)
; #define PG8_WAIT_V(n) asm volatile("s_waitcnt vmcnt(" #n ")" ::: "memory")
; #define PG8_WAIT_L(n) asm volatile("s_waitcnt lgkmcnt(" #n ")" ::: "memory")
; #define PG8_BAR __builtin_amdgcn_s_barrier()
; #define PG8_SCHED __builtin_amdgcn_sched_barrier(0)
; template <class Epi>
; DI void gemm_phase(LAS unsigned char* lds, const Gemm g, const StaticOrder& S, const Epi& E) {
;     ...
;         for (int t = 0; t < nt; t += 2) {
;             const bool last = (t == nt - 2);
;             const char* a1 = cA + (size_t)(t + 1) * kstep;
;             const char* a2 = last ? nA : cA + (size_t)(t + 2) * kstep; const char* b2 = last ? nB : cB + (size_t)(t + 2) * kstep;
;             const char* a3 = a2 + kstep; const char* b3 = b2 + kstep;
;             PG8_LDB(B0, 0, 0); PG8_SCHED; PG8_LDA(At, 0, 0); PG8_STAGE(PG8_SA(1, 1), a1 + hstep);
;             PG8_WAIT_L(8); PG8_BAR; PG8_WAIT_L(0); PG8_MMA(0, 0, At, B0); PG8_BAR; PG8_SCHED;
;             PG8_LDB(B1, 0, 1); PG8_STAGE(PG8_SB(0, 0), b2);
;             PG8_BAR; PG8_WAIT_L(0); PG8_MMA(0, 1, At, B1); PG8_BAR;
;             PG8_LDA(At, 0, 1); PG8_STAGE(PG8_SA(0, 0), a2);
;             PG8_BAR; PG8_WAIT_L(0); PG8_MMA(1, 0, At, B0); PG8_BAR; PG8_SCHED;
;             PG8_STAGE(PG8_SB(0, 1), b2 + hstep);
;             PG8_WAIT_V(6); PG8_BAR; PG8_MMA(1, 1, At, B1); PG8_BAR;
.LBB0_202:
	s_add_u32 s18, s8, 0xfff80080
	s_addc_u32 s19, s9, -1
	s_add_i32 s37, 0, 0x10000
	s_waitcnt lgkmcnt(0)
	ds_read_b128 v[128:131], v187
	ds_read_b128 v[132:135], v187 offset:1024
	ds_read_b128 v[136:139], v187 offset:2048
	ds_read_b128 v[190:193], v187 offset:3072
	s_cmp_eq_u32 s36, 28
	s_cselect_b32 s21, s4, s19
	s_cselect_b32 s20, s5, s18
	s_cselect_b32 s19, s11, s35
	s_cselect_b32 s18, s13, s33
	s_add_i32 m0, s26, 0xc000
	ds_read_b128 v[194:197], v189
	ds_read_b128 v[198:201], v189 offset:1024
	ds_read_b128 v[202:205], v189 offset:2048
	ds_read_b128 v[206:209], v189 offset:3072
	ds_read_b128 v[210:213], v189 offset:4096
	ds_read_b128 v[214:217], v189 offset:5120
	ds_read_b128 v[226:229], v189 offset:6144
	ds_read_b128 v[230:233], v189 offset:7168
	global_load_lds_dwordx4 v150, s[8:9]
	s_add_i32 m0, s26, 0xe000
	s_nop 0
	global_load_lds_dwordx4 v152, s[8:9]
	s_waitcnt lgkmcnt(8)
	s_barrier
	s_waitcnt lgkmcnt(0)
	v_mfma_f32_16x16x32_bf16 v[124:127], v[128:131], v[194:197], v[124:127]
	v_mfma_f32_16x16x32_bf16 v[120:123], v[136:139], v[194:197], v[120:123]
	v_mfma_f32_16x16x32_bf16 v[108:111], v[128:131], v[202:205], v[108:111]
	v_mfma_f32_16x16x32_bf16 v[104:107], v[136:139], v[202:205], v[104:107]
	v_mfma_f32_16x16x32_bf16 v[92:95], v[128:131], v[210:213], v[92:95]
	v_mfma_f32_16x16x32_bf16 v[88:91], v[136:139], v[210:213], v[88:91]
	v_mfma_f32_16x16x32_bf16 v[76:79], v[128:131], v[226:229], v[76:79]
	v_mfma_f32_16x16x32_bf16 v[72:75], v[136:139], v[226:229], v[72:75]
	v_mfma_f32_16x16x32_bf16 v[124:127], v[132:135], v[198:201], v[124:127]
	v_mfma_f32_16x16x32_bf16 v[120:123], v[190:193], v[198:201], v[120:123]
	v_mfma_f32_16x16x32_bf16 v[108:111], v[132:135], v[206:209], v[108:111]
	v_mfma_f32_16x16x32_bf16 v[104:107], v[190:193], v[206:209], v[104:107]
	v_mfma_f32_16x16x32_bf16 v[92:95], v[132:135], v[214:217], v[92:95]
	v_mfma_f32_16x16x32_bf16 v[88:91], v[190:193], v[214:217], v[88:91]
	v_mfma_f32_16x16x32_bf16 v[76:79], v[132:135], v[230:233], v[76:79]
	v_mfma_f32_16x16x32_bf16 v[72:75], v[190:193], v[230:233], v[72:75]
	s_barrier
	ds_read_b128 v[234:237], v187 offset:16384
	ds_read_b128 v[238:241], v187 offset:17408
	ds_read_b128 v[242:245], v187 offset:18432
	ds_read_b128 v[246:249], v187 offset:19456
	s_add_i32 s40, 0, 0x14000
	s_add_i32 s37, s37, s25
	s_mov_b32 m0, s37
	s_nop 0
	global_load_lds_dwordx4 v144, s[18:19]
	s_add_i32 m0, s37, 0x2000
	s_nop 0
	global_load_lds_dwordx4 v142, s[18:19]
	s_waitcnt lgkmcnt(0)
	s_barrier
	v_mfma_f32_16x16x32_bf16 v[116:119], v[234:237], v[194:197], v[116:119]
	v_mfma_f32_16x16x32_bf16 v[112:115], v[242:245], v[194:197], v[112:115]
	v_mfma_f32_16x16x32_bf16 v[100:103], v[234:237], v[202:205], v[100:103]
	v_mfma_f32_16x16x32_bf16 v[96:99], v[242:245], v[202:205], v[96:99]
	v_mfma_f32_16x16x32_bf16 v[84:87], v[234:237], v[210:213], v[84:87]
	v_mfma_f32_16x16x32_bf16 v[80:83], v[242:245], v[210:213], v[80:83]
	v_mfma_f32_16x16x32_bf16 v[68:71], v[234:237], v[226:229], v[68:71]
	v_mfma_f32_16x16x32_bf16 v[64:67], v[242:245], v[226:229], v[64:67]
	v_mfma_f32_16x16x32_bf16 v[116:119], v[238:241], v[198:201], v[116:119]
	s_mov_b32 m0, s26
	v_mfma_f32_16x16x32_bf16 v[112:115], v[246:249], v[198:201], v[112:115]
	s_mov_b64 s[100:101], s[20:21]
	v_mfma_f32_16x16x32_bf16 v[100:103], v[238:241], v[206:209], v[100:103]
	v_mfma_f32_16x16x32_bf16 v[96:99], v[246:249], v[206:209], v[96:99]
	v_mfma_f32_16x16x32_bf16 v[84:87], v[238:241], v[214:217], v[84:87]
	v_mfma_f32_16x16x32_bf16 v[80:83], v[246:249], v[214:217], v[80:83]
	v_mfma_f32_16x16x32_bf16 v[68:71], v[238:241], v[230:233], v[68:71]
	v_mfma_f32_16x16x32_bf16 v[64:67], v[246:249], v[230:233], v[64:67]
	s_barrier
	ds_read_b128 v[194:197], v189 offset:16384
	ds_read_b128 v[198:201], v189 offset:17408
	ds_read_b128 v[202:205], v189 offset:18432
	ds_read_b128 v[206:209], v189 offset:19456
	ds_read_b128 v[210:213], v189 offset:20480
	ds_read_b128 v[214:217], v189 offset:21504
	ds_read_b128 v[226:229], v189 offset:22528
	ds_read_b128 v[230:233], v189 offset:23552
	global_load_lds_dwordx4 v144, s[20:21]
	s_mov_b64 s[100:101], s[20:21]
	s_mov_b32 m0, s27
	s_nop 0
	global_load_lds_dwordx4 v142, s[20:21]
	s_waitcnt lgkmcnt(0)
	s_barrier
	v_mfma_f32_16x16x32_bf16 v[60:63], v[128:131], v[194:197], v[60:63]
	v_mfma_f32_16x16x32_bf16 v[56:59], v[136:139], v[194:197], v[56:59]
	v_mfma_f32_16x16x32_bf16 v[44:47], v[128:131], v[202:205], v[44:47]
	v_mfma_f32_16x16x32_bf16 v[40:43], v[136:139], v[202:205], v[40:43]
	v_mfma_f32_16x16x32_bf16 v[28:31], v[128:131], v[210:213], v[28:31]
	v_mfma_f32_16x16x32_bf16 v[24:27], v[136:139], v[210:213], v[24:27]
	v_mfma_f32_16x16x32_bf16 v[12:15], v[128:131], v[226:229], v[12:15]
	v_mfma_f32_16x16x32_bf16 v[8:11], v[136:139], v[226:229], v[8:11]
	v_mfma_f32_16x16x32_bf16 v[60:63], v[132:135], v[198:201], v[60:63]
	v_mfma_f32_16x16x32_bf16 v[56:59], v[190:193], v[198:201], v[56:59]
	v_mfma_f32_16x16x32_bf16 v[44:47], v[132:135], v[206:209], v[44:47]
	v_mfma_f32_16x16x32_bf16 v[40:43], v[190:193], v[206:209], v[40:43]
	v_mfma_f32_16x16x32_bf16 v[28:31], v[132:135], v[214:217], v[28:31]
	v_mfma_f32_16x16x32_bf16 v[24:27], v[190:193], v[214:217], v[24:27]
	v_mfma_f32_16x16x32_bf16 v[12:15], v[132:135], v[230:233], v[12:15]
	v_mfma_f32_16x16x32_bf16 v[8:11], v[190:193], v[230:233], v[8:11]
	s_barrier
	s_add_u32 s38, s18, 0x80000
	s_addc_u32 s39, s19, 0
	s_add_i32 s37, s40, s25
	s_mov_b32 m0, s37
	s_nop 0
	global_load_lds_dwordx4 v144, s[38:39]
	s_add_i32 m0, s37, 0x2000
	s_nop 0
	global_load_lds_dwordx4 v142, s[38:39]
	s_waitcnt vmcnt(6)
	s_barrier
; #define PG8_STAGE(bufoff, gbase) do { _Pragma("unroll") for (int _i = 0; _i < 2; ++_i) \
;         __builtin_amdgcn_global_load_lds((const unsigned*)((const char*)(gbase) + voff[_i]), (LAS unsigned*)(lds + (bufoff) + ldsw + _i * 8192), 16, 0, 0); } while (0)
; #define PG8_LDA(dst, b, h) do { _Pragma("unroll") for (int m = 0; m < 4; ++m) _Pragma("unroll") for (int k = 0; k < 2; ++k) dst[m][k] = *(const LAS bf16x8*)(lds + PG8_SA(b, h) + aoff + m * 2048 + k * 1024); } while (0)
; #define PG8_LDB(dst, b, h) do { _Pragma("unroll") for (int n = 0; n < 2; ++n) _Pragma("unroll") for (int k = 0; k < 2; ++k) dst[n][k] = *(const LAS bf16x8*)(lds + PG8_SB(b, h) + boff + n * 2048 + k * 1024); } while (0)
; #define PG8_MMA(ai, bj, At, Bt) do { __builtin_amdgcn_s_setprio(1); _Pragma("unroll") for (int m = 0; m < 4; ++m) _Pragma("unroll") for (int n = 0; n < 2; ++n) _Pragma("unroll") for (int k = 0; k < 2; ++k) \
;         acc[ai][bj][m][n] = __builtin_amdgcn_mfma_f32_16x16x32_bf16(Bt[n][k], At[m][k], acc[ai][bj][m][n], 0, 0, 0); __builtin_amdgcn_s_setprio(0); } while (0)
; #define PG8_WAIT_V(n) asm volatile("s_waitcnt vmcnt(" #n ")" ::: "memory")
; #define PG8_WAIT_L(n) asm volatile("s_waitcnt lgkmcnt(" #n ")" ::: "memory")
; #define PG8_BAR __builtin_amdgcn_s_barrier()
; #define PG8_SCHED __builtin_amdgcn_sched_barrier(0)
; template <class Epi>
; DI void gemm_phase(LAS unsigned char* lds, const Gemm g, const StaticOrder& S, const Epi& E) {
;     ...
;             PG8_WAIT_V(6); PG8_BAR; PG8_MMA(1, 1, At, B1); PG8_BAR;
;             PG8_LDB(B0, 1, 0); PG8_SCHED; PG8_LDA(At, 1, 0); PG8_STAGE(PG8_SA(0, 1), a2 + hstep);
;             PG8_WAIT_L(8); PG8_BAR; PG8_WAIT_L(0); PG8_MMA(0, 0, At, B0); PG8_BAR; PG8_SCHED;
;             PG8_LDB(B1, 1, 1); PG8_STAGE(PG8_SB(1, 0), b3);
;             PG8_BAR; PG8_WAIT_L(0); PG8_MMA(0, 1, At, B1); PG8_BAR;
;             PG8_LDA(At, 1, 1); PG8_STAGE(PG8_SA(1, 0), a3);
;             PG8_BAR; PG8_WAIT_L(0); PG8_MMA(1, 0, At, B0); PG8_BAR; PG8_SCHED;
	v_mfma_f32_16x16x32_bf16 v[52:55], v[234:237], v[194:197], v[52:55]
	v_mfma_f32_16x16x32_bf16 v[48:51], v[242:245], v[194:197], v[48:51]
	v_mfma_f32_16x16x32_bf16 v[36:39], v[234:237], v[202:205], v[36:39]
	v_mfma_f32_16x16x32_bf16 v[32:35], v[242:245], v[202:205], v[32:35]
	v_mfma_f32_16x16x32_bf16 v[20:23], v[234:237], v[210:213], v[20:23]
	v_mfma_f32_16x16x32_bf16 v[16:19], v[242:245], v[210:213], v[16:19]
	v_mfma_f32_16x16x32_bf16 v[4:7], v[234:237], v[226:229], v[4:7]
	v_mfma_f32_16x16x32_bf16 v[0:3], v[242:245], v[226:229], v[0:3]
	v_mfma_f32_16x16x32_bf16 v[52:55], v[238:241], v[198:201], v[52:55]
	s_add_i32 s37, 0, 0x18000
	v_mfma_f32_16x16x32_bf16 v[48:51], v[246:249], v[198:201], v[48:51]
	v_mfma_f32_16x16x32_bf16 v[36:39], v[238:241], v[206:209], v[36:39]
	v_mfma_f32_16x16x32_bf16 v[32:35], v[246:249], v[206:209], v[32:35]
	v_mfma_f32_16x16x32_bf16 v[20:23], v[238:241], v[214:217], v[20:23]
	v_mfma_f32_16x16x32_bf16 v[16:19], v[246:249], v[214:217], v[16:19]
	v_mfma_f32_16x16x32_bf16 v[4:7], v[238:241], v[230:233], v[4:7]
	v_mfma_f32_16x16x32_bf16 v[0:3], v[246:249], v[230:233], v[0:3]
	s_barrier
	ds_read_b128 v[128:131], v187 offset:32768
	ds_read_b128 v[132:135], v187 offset:33792
	ds_read_b128 v[136:139], v187 offset:34816
	ds_read_b128 v[190:193], v187 offset:35840
	ds_read_b128 v[194:197], v189 offset:32768
	ds_read_b128 v[198:201], v189 offset:33792
	ds_read_b128 v[202:205], v189 offset:34816
	ds_read_b128 v[206:209], v189 offset:35840
	ds_read_b128 v[210:213], v189 offset:36864
	ds_read_b128 v[214:217], v189 offset:37888
	ds_read_b128 v[226:229], v189 offset:38912
	ds_read_b128 v[230:233], v189 offset:39936
	s_add_u32 s20, s20, 0x80000
	s_addc_u32 s21, s21, 0
	s_mov_b32 m0, s28
	s_nop 0
	global_load_lds_dwordx4 v144, s[20:21]
	s_mov_b32 m0, s29
	s_nop 0
	global_load_lds_dwordx4 v142, s[20:21]
	s_waitcnt lgkmcnt(8)
	s_barrier
	s_waitcnt lgkmcnt(0)
	v_mfma_f32_16x16x32_bf16 v[124:127], v[128:131], v[194:197], v[124:127]
	v_mfma_f32_16x16x32_bf16 v[120:123], v[136:139], v[194:197], v[120:123]
	v_mfma_f32_16x16x32_bf16 v[108:111], v[128:131], v[202:205], v[108:111]
	v_mfma_f32_16x16x32_bf16 v[104:107], v[136:139], v[202:205], v[104:107]
	v_mfma_f32_16x16x32_bf16 v[92:95], v[128:131], v[210:213], v[92:95]
	v_mfma_f32_16x16x32_bf16 v[88:91], v[136:139], v[210:213], v[88:91]
	v_mfma_f32_16x16x32_bf16 v[76:79], v[128:131], v[226:229], v[76:79]
	v_mfma_f32_16x16x32_bf16 v[72:75], v[136:139], v[226:229], v[72:75]
	v_mfma_f32_16x16x32_bf16 v[124:127], v[132:135], v[198:201], v[124:127]
	v_mfma_f32_16x16x32_bf16 v[120:123], v[190:193], v[198:201], v[120:123]
	v_mfma_f32_16x16x32_bf16 v[108:111], v[132:135], v[206:209], v[108:111]
	v_mfma_f32_16x16x32_bf16 v[104:107], v[190:193], v[206:209], v[104:107]
	v_mfma_f32_16x16x32_bf16 v[92:95], v[132:135], v[214:217], v[92:95]
	v_mfma_f32_16x16x32_bf16 v[88:91], v[190:193], v[214:217], v[88:91]
	v_mfma_f32_16x16x32_bf16 v[76:79], v[132:135], v[230:233], v[76:79]
	v_mfma_f32_16x16x32_bf16 v[72:75], v[190:193], v[230:233], v[72:75]
	s_barrier
	ds_read_b128 v[234:237], v187 offset:49152
	ds_read_b128 v[238:241], v187 offset:50176
	ds_read_b128 v[242:245], v187 offset:51200
	ds_read_b128 v[246:249], v187 offset:52224
	s_add_i32 s20, 0, 0x1c000
	s_add_i32 s21, s37, s25
	s_add_i32 m0, s21, 0xffffff80
	s_nop 0
	global_load_lds_dwordx4 v144, s[18:19] offset:128
	s_add_i32 m0, s21, 0x1f80
	s_nop 0
	global_load_lds_dwordx4 v142, s[18:19] offset:128
	s_waitcnt lgkmcnt(0)
	s_barrier
	v_mfma_f32_16x16x32_bf16 v[116:119], v[234:237], v[194:197], v[116:119]
	v_mfma_f32_16x16x32_bf16 v[112:115], v[242:245], v[194:197], v[112:115]
	v_mfma_f32_16x16x32_bf16 v[100:103], v[234:237], v[202:205], v[100:103]
	v_mfma_f32_16x16x32_bf16 v[96:99], v[242:245], v[202:205], v[96:99]
	v_mfma_f32_16x16x32_bf16 v[84:87], v[234:237], v[210:213], v[84:87]
	v_mfma_f32_16x16x32_bf16 v[80:83], v[242:245], v[210:213], v[80:83]
	v_mfma_f32_16x16x32_bf16 v[68:71], v[234:237], v[226:229], v[68:71]
	v_mfma_f32_16x16x32_bf16 v[64:67], v[242:245], v[226:229], v[64:67]
	v_mfma_f32_16x16x32_bf16 v[116:119], v[238:241], v[198:201], v[116:119]
	s_add_i32 m0, s30, 0xffffff80
	v_mfma_f32_16x16x32_bf16 v[112:115], v[246:249], v[198:201], v[112:115]
	v_mfma_f32_16x16x32_bf16 v[100:103], v[238:241], v[206:209], v[100:103]
	v_mfma_f32_16x16x32_bf16 v[96:99], v[246:249], v[206:209], v[96:99]
	v_mfma_f32_16x16x32_bf16 v[84:87], v[238:241], v[214:217], v[84:87]
	v_mfma_f32_16x16x32_bf16 v[80:83], v[246:249], v[214:217], v[80:83]
	v_mfma_f32_16x16x32_bf16 v[68:71], v[238:241], v[230:233], v[68:71]
	v_mfma_f32_16x16x32_bf16 v[64:67], v[246:249], v[230:233], v[64:67]
	s_barrier
; #define PG8_STAGE(bufoff, gbase) do { _Pragma("unroll") for (int _i = 0; _i < 2; ++_i) \
;         __builtin_amdgcn_global_load_lds((const unsigned*)((const char*)(gbase) + voff[_i]), (LAS unsigned*)(lds + (bufoff) + ldsw + _i * 8192), 16, 0, 0); } while (0)
; #define PG8_MMA(ai, bj, At, Bt) do { __builtin_amdgcn_s_setprio(1); _Pragma("unroll") for (int m = 0; m < 4; ++m) _Pragma("unroll") for (int n = 0; n < 2; ++n) _Pragma("unroll") for (int k = 0; k < 2; ++k) \
;         acc[ai][bj][m][n] = __builtin_amdgcn_mfma_f32_16x16x32_bf16(Bt[n][k], At[m][k], acc[ai][bj][m][n], 0, 0, 0); __builtin_amdgcn_s_setprio(0); } while (0)
; #define PG8_WAIT_V(n) asm volatile("s_waitcnt vmcnt(" #n ")" ::: "memory")
; #define PG8_WAIT_L(n) asm volatile("s_waitcnt lgkmcnt(" #n ")" ::: "memory")
; #define PG8_BAR __builtin_amdgcn_s_barrier()
; #define PG8_SCHED __builtin_amdgcn_sched_barrier(0)
; template <class Epi>
; DI void gemm_phase(LAS unsigned char* lds, const Gemm g, const StaticOrder& S, const Epi& E) {
;     ...
;             PG8_BAR; PG8_WAIT_L(0); PG8_MMA(1, 0, At, B0); PG8_BAR; PG8_SCHED;
;             PG8_STAGE(PG8_SB(1, 1), b3 + hstep);
;             PG8_WAIT_V(6); PG8_BAR; PG8_MMA(1, 1, At, B1); PG8_BAR;
;     DI void operator()(const f32x4 (&acc)[2][2][4][2], const Unit& u, int wr, int wc, int fr, int fq) const {
;         const int row0 = u.pm * BM + wr * 64 + fr, col0 = u.pn * BM + wc * 16 + 4 * fq;
;         const bool rot = u.pn < 18;
; #pragma unroll
;         for (int ai = 0; ai < 2; ++ai)
; #pragma unroll
;             for (int m = 0; m < 4; ++m) { const int row = row0 + ai * HALF + m * 16; u16* rowp = O + (size_t)row * NQKV_DIL + col0;
;                 f32x4 c4 = (f32x4){1.f, 1.f, 1.f, 1.f}, s4 = (f32x4){0.f, 0.f, 0.f, 0.f};
;                 if (rot) { const int pos = row & (SEQ - 1); c4 = *(const f32x4*)(cs + pos * 64 + wc * 16 + 4 * fq); s4 = *(const f32x4*)(sn + pos * 64 + wc * 16 + 4 * fq); }
	ds_read_b128 v[194:197], v189 offset:49152
	ds_read_b128 v[198:201], v189 offset:50176
	ds_read_b128 v[202:205], v189 offset:51200
	ds_read_b128 v[206:209], v189 offset:52224
	ds_read_b128 v[210:213], v189 offset:53248
	ds_read_b128 v[214:217], v189 offset:54272
	ds_read_b128 v[226:229], v189 offset:55296
	ds_read_b128 v[230:233], v189 offset:56320
	global_load_lds_dwordx4 v144, s[100:101] offset:128
	s_add_i32 m0, s31, 0xffffff80
	s_nop 0
	global_load_lds_dwordx4 v142, s[100:101] offset:128
	s_waitcnt lgkmcnt(0)
	s_barrier
	v_mfma_f32_16x16x32_bf16 v[60:63], v[128:131], v[194:197], v[60:63]
	v_mfma_f32_16x16x32_bf16 v[56:59], v[136:139], v[194:197], v[56:59]
	v_mfma_f32_16x16x32_bf16 v[44:47], v[128:131], v[202:205], v[44:47]
	v_mfma_f32_16x16x32_bf16 v[40:43], v[136:139], v[202:205], v[40:43]
	v_mfma_f32_16x16x32_bf16 v[28:31], v[128:131], v[210:213], v[28:31]
	v_mfma_f32_16x16x32_bf16 v[24:27], v[136:139], v[210:213], v[24:27]
	v_mfma_f32_16x16x32_bf16 v[12:15], v[128:131], v[226:229], v[12:15]
	v_mfma_f32_16x16x32_bf16 v[8:11], v[136:139], v[226:229], v[8:11]
	v_mfma_f32_16x16x32_bf16 v[60:63], v[132:135], v[198:201], v[60:63]
	v_mfma_f32_16x16x32_bf16 v[56:59], v[190:193], v[198:201], v[56:59]
	v_mfma_f32_16x16x32_bf16 v[44:47], v[132:135], v[206:209], v[44:47]
	v_mfma_f32_16x16x32_bf16 v[40:43], v[190:193], v[206:209], v[40:43]
	v_mfma_f32_16x16x32_bf16 v[28:31], v[132:135], v[214:217], v[28:31]
	v_mfma_f32_16x16x32_bf16 v[24:27], v[190:193], v[214:217], v[24:27]
	v_mfma_f32_16x16x32_bf16 v[12:15], v[132:135], v[230:233], v[12:15]
	v_mfma_f32_16x16x32_bf16 v[8:11], v[190:193], v[230:233], v[8:11]
	s_barrier
	s_add_u32 s18, s18, 0x80080
	s_addc_u32 s19, s19, 0
	s_add_i32 s20, s20, s25
	s_mov_b32 m0, s20
	s_nop 0
	global_load_lds_dwordx4 v144, s[18:19]
	s_add_i32 m0, s20, 0x2000
	s_nop 0
	global_load_lds_dwordx4 v142, s[18:19]
	s_waitcnt vmcnt(6)
	s_barrier
	v_mfma_f32_16x16x32_bf16 v[52:55], v[234:237], v[194:197], v[52:55]
	v_mfma_f32_16x16x32_bf16 v[48:51], v[242:245], v[194:197], v[48:51]
	v_mfma_f32_16x16x32_bf16 v[36:39], v[234:237], v[202:205], v[36:39]
	v_mfma_f32_16x16x32_bf16 v[32:35], v[242:245], v[202:205], v[32:35]
	v_mfma_f32_16x16x32_bf16 v[20:23], v[234:237], v[210:213], v[20:23]
	v_mfma_f32_16x16x32_bf16 v[16:19], v[242:245], v[210:213], v[16:19]
	v_mfma_f32_16x16x32_bf16 v[4:7], v[234:237], v[226:229], v[4:7]
	v_mfma_f32_16x16x32_bf16 v[0:3], v[242:245], v[226:229], v[0:3]
	v_mfma_f32_16x16x32_bf16 v[52:55], v[238:241], v[198:201], v[52:55]
	s_add_i32 s36, s36, 2
	v_mfma_f32_16x16x32_bf16 v[48:51], v[246:249], v[198:201], v[48:51]
	s_add_u32 s8, s8, 0x100
	v_mfma_f32_16x16x32_bf16 v[36:39], v[238:241], v[206:209], v[36:39]
	s_addc_u32 s9, s9, 0
	v_mfma_f32_16x16x32_bf16 v[32:35], v[246:249], v[206:209], v[32:35]
	s_add_u32 s33, s33, 0x100
	v_mfma_f32_16x16x32_bf16 v[20:23], v[238:241], v[214:217], v[20:23]
	s_addc_u32 s35, s35, 0
	v_mfma_f32_16x16x32_bf16 v[16:19], v[246:249], v[214:217], v[16:19]
	s_cmp_gt_u32 s36, 29
	v_mfma_f32_16x16x32_bf16 v[4:7], v[238:241], v[230:233], v[4:7]
	v_mfma_f32_16x16x32_bf16 v[0:3], v[246:249], v[230:233], v[0:3]
	s_barrier
	s_cbranch_scc0 .LBB0_202
	s_cmp_lt_i32 s2, 18
	v_lshl_add_u32 v190, s3, 8, v186
	v_mov_b32_e32 v128, 1.0
	v_mov_b32_e32 v132, 0
	s_cselect_b64 s[18:19], -1, 0
	s_cmp_gt_i32 s2, 17
	v_mov_b32_e32 v134, 0
	v_mov_b32_e32 v135, 0
	v_mov_b32_e32 v136, 0
	v_mov_b32_e32 v137, 0
	v_mov_b32_e32 v138, 1.0
	v_mov_b32_e32 v139, 1.0
	v_mov_b32_e32 v140, 1.0
	v_mov_b32_e32 v141, 1.0
	s_cbranch_scc1 .LBB0_205
	v_lshlrev_b32_e32 v129, 8, v190
	v_and_b32_e32 v158, 0xfcf00, v129
	v_lshl_add_u64 v[130:131], v[146:147], 0, v[158:159]
	v_lshl_add_u64 v[134:135], v[148:149], 0, v[158:159]
	global_load_dwordx4 v[138:141], v[130:131], off
	s_nop 0
	global_load_dwordx4 v[134:137], v[134:135], off

; #define PG8_STAGE(bufoff, gbase) do { _Pragma("unroll") for (int _i = 0; _i < 2; ++_i) \
;         __builtin_amdgcn_global_load_lds((const unsigned*)((const char*)(gbase) + voff[_i]), (LAS unsigned*)(lds + (bufoff) + ldsw + _i * 8192), 16, 0, 0); } while (0)
; #define PG8_LDA(dst, b, h) do { _Pragma("unroll") for (int m = 0; m < 4; ++m) _Pragma("unroll") for (int k = 0; k < 2; ++k) dst[m][k] = *(const LAS bf16x8*)(lds + PG8_SA(b, h) + aoff + m * 2048 + k * 1024); } while (0)
; #define PG8_LDB(dst, b, h) do { _Pragma("unroll") for (int n = 0; n < 2; ++n) _Pragma("unroll") for (int k = 0; k < 2; ++k) dst[n][k] = *(const LAS bf16x8*)(lds + PG8_SB(b, h) + boff + n * 2048 + k * 1024); } while (0)
; #define PG8_MMA(ai, bj, At, Bt) do { __builtin_amdgcn_s_setprio(1); _Pragma("unroll") for (int m = 0; m < 4; ++m) _Pragma("unroll") for (int n = 0; n < 2; ++n) _Pragma("unroll") for (int k = 0; k < 2; ++k) \
;         acc[ai][bj][m][n] = __builtin_amdgcn_mfma_f32_16x16x32_bf16(Bt[n][k], At[m][k], acc[ai][bj][m][n], 0, 0, 0); __builtin_amdgcn_s_setprio(0); } while (0)
; #define PG8_WAIT_V(n) asm volatile("s_waitcnt vmcnt(" #n ")" ::: "memory")
; #define PG8_WAIT_L(n) asm volatile("s_waitcnt lgkmcnt(" #n ")" ::: "memory")
; #define PG8_BAR __builtin_amdgcn_s_barrier()
; #define PG8_SCHED __builtin_amdgcn_sched_barrier(0)
; template <class Epi>
; DI void gemm_phase(LAS unsigned char* lds, const Gemm g, const StaticOrder& S, const Epi& E) {
;     ...
;         for (int t = 0; t < nt; t += 2) {
;             const bool last = (t == nt - 2);
;             const char* a1 = cA + (size_t)(t + 1) * kstep;
;             const char* a2 = last ? nA : cA + (size_t)(t + 2) * kstep; const char* b2 = last ? nB : cB + (size_t)(t + 2) * kstep;
;             const char* a3 = a2 + kstep; const char* b3 = b2 + kstep;
;             PG8_LDB(B0, 0, 0); PG8_SCHED; PG8_LDA(At, 0, 0); PG8_STAGE(PG8_SA(1, 1), a1 + hstep);
;             PG8_WAIT_L(8); PG8_BAR; PG8_WAIT_L(0); PG8_MMA(0, 0, At, B0); PG8_BAR; PG8_SCHED;
;             PG8_LDB(B1, 0, 1); PG8_STAGE(PG8_SB(0, 0), b2);
;             PG8_BAR; PG8_WAIT_L(0); PG8_MMA(0, 1, At, B1); PG8_BAR;
;             PG8_LDA(At, 0, 1); PG8_STAGE(PG8_SA(0, 0), a2);
;             PG8_BAR; PG8_WAIT_L(0); PG8_MMA(1, 0, At, B0); PG8_BAR; PG8_SCHED;
;             PG8_STAGE(PG8_SB(0, 1), b2 + hstep);
;             PG8_WAIT_V(6); PG8_BAR; PG8_MMA(1, 1, At, B1); PG8_BAR;
.LBB0_231:
	ds_read_b128 v[138:141], v135
	ds_read_b128 v[142:145], v135 offset:1024
	ds_read_b128 v[146:149], v135 offset:2048
	ds_read_b128 v[150:153], v135 offset:3072
	ds_read_b128 v[186:189], v137
	ds_read_b128 v[190:193], v137 offset:1024
	ds_read_b128 v[194:197], v137 offset:2048
	ds_read_b128 v[198:201], v137 offset:3072
	ds_read_b128 v[202:205], v137 offset:4096
	ds_read_b128 v[206:209], v137 offset:5120
	ds_read_b128 v[210:213], v137 offset:6144
	ds_read_b128 v[214:217], v137 offset:7168
	s_add_u32 s18, s16, 0xfff80080
	s_addc_u32 s19, s17, -1
	s_add_i32 s37, 0, 0x10000
	s_cmp_eq_u32 s36, 28
	s_cselect_b32 s21, s4, s19
	s_cselect_b32 s20, s5, s18
	s_cselect_b32 s19, s9, s35
	s_cselect_b32 s18, s11, s34
	s_add_i32 m0, s24, 0xc000
	s_nop 0
	global_load_lds_dwordx4 v130, s[16:17]
	s_add_i32 m0, s24, 0xe000
	s_nop 0
	global_load_lds_dwordx4 v132, s[16:17]
	s_waitcnt lgkmcnt(8)
	s_barrier
	s_waitcnt lgkmcnt(0)
	v_mfma_f32_16x16x32_bf16 v[124:127], v[138:141], v[186:189], v[124:127]
	v_mfma_f32_16x16x32_bf16 v[120:123], v[146:149], v[186:189], v[120:123]
	v_mfma_f32_16x16x32_bf16 v[116:119], v[138:141], v[194:197], v[116:119]
	v_mfma_f32_16x16x32_bf16 v[112:115], v[146:149], v[194:197], v[112:115]
	v_mfma_f32_16x16x32_bf16 v[100:103], v[138:141], v[202:205], v[100:103]
	v_mfma_f32_16x16x32_bf16 v[96:99], v[146:149], v[202:205], v[96:99]
	v_mfma_f32_16x16x32_bf16 v[84:87], v[138:141], v[210:213], v[84:87]
	v_mfma_f32_16x16x32_bf16 v[80:83], v[146:149], v[210:213], v[80:83]
	v_mfma_f32_16x16x32_bf16 v[124:127], v[142:145], v[190:193], v[124:127]
	v_mfma_f32_16x16x32_bf16 v[120:123], v[150:153], v[190:193], v[120:123]
	v_mfma_f32_16x16x32_bf16 v[116:119], v[142:145], v[198:201], v[116:119]
	v_mfma_f32_16x16x32_bf16 v[112:115], v[150:153], v[198:201], v[112:115]
	v_mfma_f32_16x16x32_bf16 v[100:103], v[142:145], v[206:209], v[100:103]
	v_mfma_f32_16x16x32_bf16 v[96:99], v[150:153], v[206:209], v[96:99]
	v_mfma_f32_16x16x32_bf16 v[84:87], v[142:145], v[214:217], v[84:87]
	v_mfma_f32_16x16x32_bf16 v[80:83], v[150:153], v[214:217], v[80:83]
	s_barrier
	ds_read_b128 v[226:229], v135 offset:16384
	ds_read_b128 v[230:233], v135 offset:17408
	ds_read_b128 v[234:237], v135 offset:18432
	ds_read_b128 v[238:241], v135 offset:19456
	s_add_i32 s40, 0, 0x14000
	s_add_i32 s37, s37, s23
	s_mov_b32 m0, s37
	s_nop 0
	global_load_lds_dwordx4 v158, s[18:19]
	s_add_i32 m0, s37, 0x2000
	s_nop 0
	global_load_lds_dwordx4 v128, s[18:19]
	s_waitcnt lgkmcnt(0)
	s_barrier
	v_mfma_f32_16x16x32_bf16 v[108:111], v[226:229], v[186:189], v[108:111]
	v_mfma_f32_16x16x32_bf16 v[104:107], v[234:237], v[186:189], v[104:107]
	v_mfma_f32_16x16x32_bf16 v[92:95], v[226:229], v[194:197], v[92:95]
	v_mfma_f32_16x16x32_bf16 v[88:91], v[234:237], v[194:197], v[88:91]
	v_mfma_f32_16x16x32_bf16 v[76:79], v[226:229], v[202:205], v[76:79]
	v_mfma_f32_16x16x32_bf16 v[72:75], v[234:237], v[202:205], v[72:75]
	v_mfma_f32_16x16x32_bf16 v[68:71], v[226:229], v[210:213], v[68:71]
	v_mfma_f32_16x16x32_bf16 v[64:67], v[234:237], v[210:213], v[64:67]
	v_mfma_f32_16x16x32_bf16 v[108:111], v[230:233], v[190:193], v[108:111]
	s_mov_b32 m0, s24
	v_mfma_f32_16x16x32_bf16 v[104:107], v[238:241], v[190:193], v[104:107]
	s_mov_b64 s[100:101], s[20:21]
	v_mfma_f32_16x16x32_bf16 v[92:95], v[230:233], v[198:201], v[92:95]
	v_mfma_f32_16x16x32_bf16 v[88:91], v[238:241], v[198:201], v[88:91]
	v_mfma_f32_16x16x32_bf16 v[76:79], v[230:233], v[206:209], v[76:79]
	v_mfma_f32_16x16x32_bf16 v[72:75], v[238:241], v[206:209], v[72:75]
	v_mfma_f32_16x16x32_bf16 v[68:71], v[230:233], v[214:217], v[68:71]
	v_mfma_f32_16x16x32_bf16 v[64:67], v[238:241], v[214:217], v[64:67]
	s_barrier
	ds_read_b128 v[186:189], v137 offset:16384
	ds_read_b128 v[190:193], v137 offset:17408
	ds_read_b128 v[194:197], v137 offset:18432
	ds_read_b128 v[198:201], v137 offset:19456
	ds_read_b128 v[202:205], v137 offset:20480
	ds_read_b128 v[206:209], v137 offset:21504
	ds_read_b128 v[210:213], v137 offset:22528
	ds_read_b128 v[214:217], v137 offset:23552
	global_load_lds_dwordx4 v158, s[20:21]
	s_mov_b64 s[100:101], s[20:21]
	s_mov_b32 m0, s25
	s_nop 0
	global_load_lds_dwordx4 v128, s[20:21]
	s_waitcnt lgkmcnt(0)
	s_barrier
	v_mfma_f32_16x16x32_bf16 v[60:63], v[138:141], v[186:189], v[60:63]
	v_mfma_f32_16x16x32_bf16 v[56:59], v[146:149], v[186:189], v[56:59]
	v_mfma_f32_16x16x32_bf16 v[52:55], v[138:141], v[194:197], v[52:55]
	v_mfma_f32_16x16x32_bf16 v[48:51], v[146:149], v[194:197], v[48:51]
	v_mfma_f32_16x16x32_bf16 v[36:39], v[138:141], v[202:205], v[36:39]
	v_mfma_f32_16x16x32_bf16 v[32:35], v[146:149], v[202:205], v[32:35]
	v_mfma_f32_16x16x32_bf16 v[20:23], v[138:141], v[210:213], v[20:23]
	v_mfma_f32_16x16x32_bf16 v[16:19], v[146:149], v[210:213], v[16:19]
	v_mfma_f32_16x16x32_bf16 v[60:63], v[142:145], v[190:193], v[60:63]
	v_mfma_f32_16x16x32_bf16 v[56:59], v[150:153], v[190:193], v[56:59]
	v_mfma_f32_16x16x32_bf16 v[52:55], v[142:145], v[198:201], v[52:55]
	v_mfma_f32_16x16x32_bf16 v[48:51], v[150:153], v[198:201], v[48:51]
	v_mfma_f32_16x16x32_bf16 v[36:39], v[142:145], v[206:209], v[36:39]
	v_mfma_f32_16x16x32_bf16 v[32:35], v[150:153], v[206:209], v[32:35]
	v_mfma_f32_16x16x32_bf16 v[20:23], v[142:145], v[214:217], v[20:23]
	v_mfma_f32_16x16x32_bf16 v[16:19], v[150:153], v[214:217], v[16:19]
	s_barrier
	s_add_u32 s38, s18, 0x80000
	s_addc_u32 s39, s19, 0
	s_add_i32 s37, s40, s23
	s_mov_b32 m0, s37
	s_nop 0
	global_load_lds_dwordx4 v158, s[38:39]
	s_add_i32 m0, s37, 0x2000
	s_nop 0
	global_load_lds_dwordx4 v128, s[38:39]
	s_waitcnt vmcnt(6)
	s_barrier
; #define PG8_STAGE(bufoff, gbase) do { _Pragma("unroll") for (int _i = 0; _i < 2; ++_i) \
;         __builtin_amdgcn_global_load_lds((const unsigned*)((const char*)(gbase) + voff[_i]), (LAS unsigned*)(lds + (bufoff) + ldsw + _i * 8192), 16, 0, 0); } while (0)
; #define PG8_LDA(dst, b, h) do { _Pragma("unroll") for (int m = 0; m < 4; ++m) _Pragma("unroll") for (int k = 0; k < 2; ++k) dst[m][k] = *(const LAS bf16x8*)(lds + PG8_SA(b, h) + aoff + m * 2048 + k * 1024); } while (0)
; #define PG8_LDB(dst, b, h) do { _Pragma("unroll") for (int n = 0; n < 2; ++n) _Pragma("unroll") for (int k = 0; k < 2; ++k) dst[n][k] = *(const LAS bf16x8*)(lds + PG8_SB(b, h) + boff + n * 2048 + k * 1024); } while (0)
; #define PG8_MMA(ai, bj, At, Bt) do { __builtin_amdgcn_s_setprio(1); _Pragma("unroll") for (int m = 0; m < 4; ++m) _Pragma("unroll") for (int n = 0; n < 2; ++n) _Pragma("unroll") for (int k = 0; k < 2; ++k) \
;         acc[ai][bj][m][n] = __builtin_amdgcn_mfma_f32_16x16x32_bf16(Bt[n][k], At[m][k], acc[ai][bj][m][n], 0, 0, 0); __builtin_amdgcn_s_setprio(0); } while (0)
; #define PG8_WAIT_V(n) asm volatile("s_waitcnt vmcnt(" #n ")" ::: "memory")
; #define PG8_WAIT_L(n) asm volatile("s_waitcnt lgkmcnt(" #n ")" ::: "memory")
; #define PG8_BAR __builtin_amdgcn_s_barrier()
; #define PG8_SCHED __builtin_amdgcn_sched_barrier(0)
; template <class Epi>
; DI void gemm_phase(LAS unsigned char* lds, const Gemm g, const StaticOrder& S, const Epi& E) {
;     ...
;             PG8_WAIT_V(6); PG8_BAR; PG8_MMA(1, 1, At, B1); PG8_BAR;
;             PG8_LDB(B0, 1, 0); PG8_SCHED; PG8_LDA(At, 1, 0); PG8_STAGE(PG8_SA(0, 1), a2 + hstep);
;             PG8_WAIT_L(8); PG8_BAR; PG8_WAIT_L(0); PG8_MMA(0, 0, At, B0); PG8_BAR; PG8_SCHED;
;             PG8_LDB(B1, 1, 1); PG8_STAGE(PG8_SB(1, 0), b3);
;             PG8_BAR; PG8_WAIT_L(0); PG8_MMA(0, 1, At, B1); PG8_BAR;
;             PG8_LDA(At, 1, 1); PG8_STAGE(PG8_SA(1, 0), a3);
;             PG8_BAR; PG8_WAIT_L(0); PG8_MMA(1, 0, At, B0); PG8_BAR; PG8_SCHED;
	v_mfma_f32_16x16x32_bf16 v[44:47], v[226:229], v[186:189], v[44:47]
	v_mfma_f32_16x16x32_bf16 v[40:43], v[234:237], v[186:189], v[40:43]
	v_mfma_f32_16x16x32_bf16 v[28:31], v[226:229], v[194:197], v[28:31]
	v_mfma_f32_16x16x32_bf16 v[24:27], v[234:237], v[194:197], v[24:27]
	v_mfma_f32_16x16x32_bf16 v[12:15], v[226:229], v[202:205], v[12:15]
	v_mfma_f32_16x16x32_bf16 v[8:11], v[234:237], v[202:205], v[8:11]
	v_mfma_f32_16x16x32_bf16 v[4:7], v[226:229], v[210:213], v[4:7]
	v_mfma_f32_16x16x32_bf16 v[0:3], v[234:237], v[210:213], v[0:3]
	v_mfma_f32_16x16x32_bf16 v[44:47], v[230:233], v[190:193], v[44:47]
	s_add_i32 s37, 0, 0x18000
	v_mfma_f32_16x16x32_bf16 v[40:43], v[238:241], v[190:193], v[40:43]
	v_mfma_f32_16x16x32_bf16 v[28:31], v[230:233], v[198:201], v[28:31]
	v_mfma_f32_16x16x32_bf16 v[24:27], v[238:241], v[198:201], v[24:27]
	v_mfma_f32_16x16x32_bf16 v[12:15], v[230:233], v[206:209], v[12:15]
	v_mfma_f32_16x16x32_bf16 v[8:11], v[238:241], v[206:209], v[8:11]
	v_mfma_f32_16x16x32_bf16 v[4:7], v[230:233], v[214:217], v[4:7]
	v_mfma_f32_16x16x32_bf16 v[0:3], v[238:241], v[214:217], v[0:3]
	s_barrier
	ds_read_b128 v[138:141], v135 offset:32768
	ds_read_b128 v[142:145], v135 offset:33792
	ds_read_b128 v[146:149], v135 offset:34816
	ds_read_b128 v[150:153], v135 offset:35840
	ds_read_b128 v[186:189], v137 offset:32768
	ds_read_b128 v[190:193], v137 offset:33792
	ds_read_b128 v[194:197], v137 offset:34816
	ds_read_b128 v[198:201], v137 offset:35840
	ds_read_b128 v[202:205], v137 offset:36864
	ds_read_b128 v[206:209], v137 offset:37888
	ds_read_b128 v[210:213], v137 offset:38912
	ds_read_b128 v[214:217], v137 offset:39936
	s_add_u32 s20, s20, 0x80000
	s_addc_u32 s21, s21, 0
	s_mov_b32 m0, s26
	s_nop 0
	global_load_lds_dwordx4 v158, s[20:21]
	s_mov_b32 m0, s27
	s_nop 0
	global_load_lds_dwordx4 v128, s[20:21]
	s_waitcnt lgkmcnt(8)
	s_barrier
	s_waitcnt lgkmcnt(0)
	v_mfma_f32_16x16x32_bf16 v[124:127], v[138:141], v[186:189], v[124:127]
	v_mfma_f32_16x16x32_bf16 v[120:123], v[146:149], v[186:189], v[120:123]
	v_mfma_f32_16x16x32_bf16 v[116:119], v[138:141], v[194:197], v[116:119]
	v_mfma_f32_16x16x32_bf16 v[112:115], v[146:149], v[194:197], v[112:115]
	v_mfma_f32_16x16x32_bf16 v[100:103], v[138:141], v[202:205], v[100:103]
	v_mfma_f32_16x16x32_bf16 v[96:99], v[146:149], v[202:205], v[96:99]
	v_mfma_f32_16x16x32_bf16 v[84:87], v[138:141], v[210:213], v[84:87]
	v_mfma_f32_16x16x32_bf16 v[80:83], v[146:149], v[210:213], v[80:83]
	v_mfma_f32_16x16x32_bf16 v[124:127], v[142:145], v[190:193], v[124:127]
	v_mfma_f32_16x16x32_bf16 v[120:123], v[150:153], v[190:193], v[120:123]
	v_mfma_f32_16x16x32_bf16 v[116:119], v[142:145], v[198:201], v[116:119]
	v_mfma_f32_16x16x32_bf16 v[112:115], v[150:153], v[198:201], v[112:115]
	v_mfma_f32_16x16x32_bf16 v[100:103], v[142:145], v[206:209], v[100:103]
	v_mfma_f32_16x16x32_bf16 v[96:99], v[150:153], v[206:209], v[96:99]
	v_mfma_f32_16x16x32_bf16 v[84:87], v[142:145], v[214:217], v[84:87]
	v_mfma_f32_16x16x32_bf16 v[80:83], v[150:153], v[214:217], v[80:83]
	s_barrier
	ds_read_b128 v[226:229], v135 offset:49152
	ds_read_b128 v[230:233], v135 offset:50176
	ds_read_b128 v[234:237], v135 offset:51200
	ds_read_b128 v[238:241], v135 offset:52224
	s_add_i32 s20, 0, 0x1c000
	s_add_i32 s21, s37, s23
	s_add_i32 m0, s21, 0xffffff80
	s_nop 0
	global_load_lds_dwordx4 v158, s[18:19] offset:128
	s_add_i32 m0, s21, 0x1f80
	s_nop 0
	global_load_lds_dwordx4 v128, s[18:19] offset:128
	s_waitcnt lgkmcnt(0)
	s_barrier
	v_mfma_f32_16x16x32_bf16 v[108:111], v[226:229], v[186:189], v[108:111]
	v_mfma_f32_16x16x32_bf16 v[104:107], v[234:237], v[186:189], v[104:107]
	v_mfma_f32_16x16x32_bf16 v[92:95], v[226:229], v[194:197], v[92:95]
	v_mfma_f32_16x16x32_bf16 v[88:91], v[234:237], v[194:197], v[88:91]
	v_mfma_f32_16x16x32_bf16 v[76:79], v[226:229], v[202:205], v[76:79]
	v_mfma_f32_16x16x32_bf16 v[72:75], v[234:237], v[202:205], v[72:75]
	v_mfma_f32_16x16x32_bf16 v[68:71], v[226:229], v[210:213], v[68:71]
	v_mfma_f32_16x16x32_bf16 v[64:67], v[234:237], v[210:213], v[64:67]
	v_mfma_f32_16x16x32_bf16 v[108:111], v[230:233], v[190:193], v[108:111]
	s_add_i32 m0, s28, 0xffffff80
	v_mfma_f32_16x16x32_bf16 v[104:107], v[238:241], v[190:193], v[104:107]
	v_mfma_f32_16x16x32_bf16 v[92:95], v[230:233], v[198:201], v[92:95]
	v_mfma_f32_16x16x32_bf16 v[88:91], v[238:241], v[198:201], v[88:91]
	v_mfma_f32_16x16x32_bf16 v[76:79], v[230:233], v[206:209], v[76:79]
	v_mfma_f32_16x16x32_bf16 v[72:75], v[238:241], v[206:209], v[72:75]
	v_mfma_f32_16x16x32_bf16 v[68:71], v[230:233], v[214:217], v[68:71]
	v_mfma_f32_16x16x32_bf16 v[64:67], v[238:241], v[214:217], v[64:67]
	s_barrier
	ds_read_b128 v[186:189], v137 offset:49152
	ds_read_b128 v[190:193], v137 offset:50176
	ds_read_b128 v[194:197], v137 offset:51200
	ds_read_b128 v[198:201], v137 offset:52224
	ds_read_b128 v[202:205], v137 offset:53248
	ds_read_b128 v[206:209], v137 offset:54272
	ds_read_b128 v[210:213], v137 offset:55296
	ds_read_b128 v[214:217], v137 offset:56320
	global_load_lds_dwordx4 v158, s[100:101] offset:128
	s_add_i32 m0, s29, 0xffffff80
	s_nop 0
	global_load_lds_dwordx4 v128, s[100:101] offset:128
	s_waitcnt lgkmcnt(0)
	s_barrier
; #define PG8_STAGE(bufoff, gbase) do { _Pragma("unroll") for (int _i = 0; _i < 2; ++_i) \
;         __builtin_amdgcn_global_load_lds((const unsigned*)((const char*)(gbase) + voff[_i]), (LAS unsigned*)(lds + (bufoff) + ldsw + _i * 8192), 16, 0, 0); } while (0)
; #define PG8_MMA(ai, bj, At, Bt) do { __builtin_amdgcn_s_setprio(1); _Pragma("unroll") for (int m = 0; m < 4; ++m) _Pragma("unroll") for (int n = 0; n < 2; ++n) _Pragma("unroll") for (int k = 0; k < 2; ++k) \
;         acc[ai][bj][m][n] = __builtin_amdgcn_mfma_f32_16x16x32_bf16(Bt[n][k], At[m][k], acc[ai][bj][m][n], 0, 0, 0); __builtin_amdgcn_s_setprio(0); } while (0)
; #define PG8_WAIT_V(n) asm volatile("s_waitcnt vmcnt(" #n ")" ::: "memory")
; #define PG8_WAIT_L(n) asm volatile("s_waitcnt lgkmcnt(" #n ")" ::: "memory")
; #define PG8_BAR __builtin_amdgcn_s_barrier()
; #define PG8_SCHED __builtin_amdgcn_sched_barrier(0)
; template <class Epi>
; DI void gemm_phase(LAS unsigned char* lds, const Gemm g, const StaticOrder& S, const Epi& E) {
;     ...
;             PG8_BAR; PG8_WAIT_L(0); PG8_MMA(1, 0, At, B0); PG8_BAR; PG8_SCHED;
;             PG8_STAGE(PG8_SB(1, 1), b3 + hstep);
;             PG8_WAIT_V(6); PG8_BAR; PG8_MMA(1, 1, At, B1); PG8_BAR;
	v_mfma_f32_16x16x32_bf16 v[60:63], v[138:141], v[186:189], v[60:63]
	v_mfma_f32_16x16x32_bf16 v[56:59], v[146:149], v[186:189], v[56:59]
	v_mfma_f32_16x16x32_bf16 v[52:55], v[138:141], v[194:197], v[52:55]
	v_mfma_f32_16x16x32_bf16 v[48:51], v[146:149], v[194:197], v[48:51]
	v_mfma_f32_16x16x32_bf16 v[36:39], v[138:141], v[202:205], v[36:39]
	v_mfma_f32_16x16x32_bf16 v[32:35], v[146:149], v[202:205], v[32:35]
	v_mfma_f32_16x16x32_bf16 v[20:23], v[138:141], v[210:213], v[20:23]
	v_mfma_f32_16x16x32_bf16 v[16:19], v[146:149], v[210:213], v[16:19]
	v_mfma_f32_16x16x32_bf16 v[60:63], v[142:145], v[190:193], v[60:63]
	v_mfma_f32_16x16x32_bf16 v[56:59], v[150:153], v[190:193], v[56:59]
	v_mfma_f32_16x16x32_bf16 v[52:55], v[142:145], v[198:201], v[52:55]
	v_mfma_f32_16x16x32_bf16 v[48:51], v[150:153], v[198:201], v[48:51]
	v_mfma_f32_16x16x32_bf16 v[36:39], v[142:145], v[206:209], v[36:39]
	v_mfma_f32_16x16x32_bf16 v[32:35], v[150:153], v[206:209], v[32:35]
	v_mfma_f32_16x16x32_bf16 v[20:23], v[142:145], v[214:217], v[20:23]
	v_mfma_f32_16x16x32_bf16 v[16:19], v[150:153], v[214:217], v[16:19]
	s_barrier
	s_add_u32 s18, s18, 0x80080
	s_addc_u32 s19, s19, 0
	s_add_i32 s20, s20, s23
	s_mov_b32 m0, s20
	s_nop 0
	global_load_lds_dwordx4 v158, s[18:19]
	s_add_i32 m0, s20, 0x2000
	s_nop 0
	global_load_lds_dwordx4 v128, s[18:19]
	s_waitcnt vmcnt(6)
	s_barrier
	v_mfma_f32_16x16x32_bf16 v[44:47], v[226:229], v[186:189], v[44:47]
	v_mfma_f32_16x16x32_bf16 v[40:43], v[234:237], v[186:189], v[40:43]
	v_mfma_f32_16x16x32_bf16 v[28:31], v[226:229], v[194:197], v[28:31]
	v_mfma_f32_16x16x32_bf16 v[24:27], v[234:237], v[194:197], v[24:27]
	v_mfma_f32_16x16x32_bf16 v[12:15], v[226:229], v[202:205], v[12:15]
	v_mfma_f32_16x16x32_bf16 v[8:11], v[234:237], v[202:205], v[8:11]
	v_mfma_f32_16x16x32_bf16 v[4:7], v[226:229], v[210:213], v[4:7]
	v_mfma_f32_16x16x32_bf16 v[0:3], v[234:237], v[210:213], v[0:3]
	v_mfma_f32_16x16x32_bf16 v[44:47], v[230:233], v[190:193], v[44:47]
	s_add_i32 s36, s36, 2
	v_mfma_f32_16x16x32_bf16 v[40:43], v[238:241], v[190:193], v[40:43]
	s_add_u32 s16, s16, 0x100
	v_mfma_f32_16x16x32_bf16 v[28:31], v[230:233], v[198:201], v[28:31]
	s_addc_u32 s17, s17, 0
	v_mfma_f32_16x16x32_bf16 v[24:27], v[238:241], v[198:201], v[24:27]
	s_add_u32 s34, s34, 0x100
	v_mfma_f32_16x16x32_bf16 v[12:15], v[230:233], v[206:209], v[12:15]
	s_addc_u32 s35, s35, 0
	v_mfma_f32_16x16x32_bf16 v[8:11], v[238:241], v[206:209], v[8:11]
	s_cmp_gt_u32 s36, 29
	v_mfma_f32_16x16x32_bf16 v[4:7], v[230:233], v[214:217], v[4:7]
	v_mfma_f32_16x16x32_bf16 v[0:3], v[238:241], v[214:217], v[0:3]
	s_barrier
	s_cbranch_scc0 .LBB0_231
; #define PG8_WAIT_V(n) asm volatile("s_waitcnt vmcnt(" #n ")" ::: "memory")
; #define PG8_BAR __builtin_amdgcn_s_barrier()
; template <class Epi>
; DI void gemm_phase(LAS unsigned char* lds, const Gemm g, const StaticOrder& S, const Epi& E) {
;     ...
;         E(acc, cur, wr, wc, fr, fq);
;         if (!has_next) break;
; #pragma unroll
;         for (int a = 0; a < 2; ++a)
; #pragma unroll
;             for (int b = 0; b < 2; ++b)
; #pragma unroll
;                 for (int m = 0; m < 4; ++m)
; #pragma unroll
;                     for (int n = 0; n < 2; ++n) acc[a][b][m][n] = (f32x4){0.f, 0.f, 0.f, 0.f};
;         cur = nxt; cA = nA; cB = nB; ++ui;
;     }
;     PG8_WAIT_V(0);
;     if (wr == 0) PG8_BAR;
;     PG8_BAR;
;     DI void operator()(const f32x4 (&acc)[2][2][4][2], const Unit& u, int wr, int wc, int fr, int fq) const {
;         const int row0 = u.pm * BM + wr * 64 + fr, col0 = u.pn * BM + wc * 32 + 8 * fq;
; #pragma unroll
;         for (int ai = 0; ai < 2; ++ai)
; #pragma unroll
;             for (int m = 0; m < 4; ++m) { u16* rowp = O + (size_t)(row0 + ai * HALF + m * 16) * ldc + col0;
; #pragma unroll
;                 for (int bj = 0; bj < 2; ++bj) { const f32x4 v0 = acc[ai][bj][m][0], v1 = acc[ai][bj][m][1];
;                     *(u32x4*)(rowp + bj * HALF) = (u32x4){pk(v0[0], v0[1]), pk(v0[2], v0[3]), pk(v1[0], v1[1]), pk(v1[2], v1[3])}; } }
;     }
	v_lshl_add_u32 v144, s33, 8, v134
	v_lshl_or_b32 v138, s31, 8, v136
	v_ashrrev_i32_e32 v139, 31, v138
	v_mov_b64_e32 v[140:141], s[50:51]
	s_movk_i32 s9, 0x3000
	v_cvt_pk_bf16_f32 v68, v68, v69
	v_cvt_pk_bf16_f32 v69, v70, v71
	v_cvt_pk_bf16_f32 v70, v64, v65
	v_add_u32_e32 v64, 0x80, v144
	v_mad_i64_i32 v[142:143], s[4:5], v144, s9, v[140:141]
	v_lshlrev_b64 v[138:139], 1, v[138:139]
	v_cvt_pk_bf16_f32 v108, v108, v109
	v_cvt_pk_bf16_f32 v109, v110, v111
	v_cvt_pk_bf16_f32 v110, v104, v105
	v_or_b32_e32 v104, 16, v144
	v_mad_i64_i32 v[64:65], s[4:5], v64, s9, v[140:141]
	v_cvt_pk_bf16_f32 v44, v44, v45
	v_cvt_pk_bf16_f32 v45, v46, v47
	v_cvt_pk_bf16_f32 v46, v40, v41
	v_add_u32_e32 v40, 0x90, v144
	v_lshl_add_u64 v[142:143], v[142:143], 0, v[138:139]
	v_cvt_pk_bf16_f32 v111, v106, v107
	v_mad_i64_i32 v[104:105], s[4:5], v104, s9, v[140:141]
	v_cvt_pk_bf16_f32 v92, v92, v93
	v_cvt_pk_bf16_f32 v93, v94, v95
	v_cvt_pk_bf16_f32 v94, v88, v89
	v_or_b32_e32 v88, 32, v144
	v_lshl_add_u64 v[64:65], v[64:65], 0, v[138:139]
	v_cvt_pk_bf16_f32 v47, v42, v43
	v_mad_i64_i32 v[40:41], s[4:5], v40, s9, v[140:141]
	v_cvt_pk_bf16_f32 v28, v28, v29
	v_cvt_pk_bf16_f32 v29, v30, v31
	v_cvt_pk_bf16_f32 v30, v24, v25
	v_add_u32_e32 v24, 0xa0, v144
	global_store_dwordx4 v[142:143], v[108:111], off offset:256
	v_cvt_pk_bf16_f32 v95, v90, v91
	v_mad_i64_i32 v[88:89], s[4:5], v88, s9, v[140:141]
	v_lshl_add_u64 v[108:109], v[104:105], 0, v[138:139]
	v_cvt_pk_bf16_f32 v76, v76, v77
	v_cvt_pk_bf16_f32 v77, v78, v79
	v_cvt_pk_bf16_f32 v78, v72, v73
	v_or_b32_e32 v72, 48, v144
	global_store_dwordx4 v[64:65], v[44:47], off offset:256
	v_cvt_pk_bf16_f32 v31, v26, v27
	v_mad_i64_i32 v[24:25], s[4:5], v24, s9, v[140:141]
	v_lshl_add_u64 v[44:45], v[40:41], 0, v[138:139]
	v_cvt_pk_bf16_f32 v12, v12, v13
	v_cvt_pk_bf16_f32 v13, v14, v15
	v_cvt_pk_bf16_f32 v14, v8, v9
	v_add_u32_e32 v8, 0xb0, v144
	global_store_dwordx4 v[108:109], v[92:95], off offset:256
	v_cvt_pk_bf16_f32 v79, v74, v75
	v_mad_i64_i32 v[72:73], s[4:5], v72, s9, v[140:141]
	v_lshl_add_u64 v[92:93], v[88:89], 0, v[138:139]
	global_store_dwordx4 v[44:45], v[28:31], off offset:256
	v_cvt_pk_bf16_f32 v15, v10, v11
	v_mad_i64_i32 v[8:9], s[4:5], v8, s9, v[140:141]
	v_lshl_add_u64 v[28:29], v[24:25], 0, v[138:139]
	v_cvt_pk_bf16_f32 v124, v124, v125
	v_cvt_pk_bf16_f32 v125, v126, v127
	v_cvt_pk_bf16_f32 v126, v120, v121
	v_cvt_pk_bf16_f32 v127, v122, v123
	v_cvt_pk_bf16_f32 v104, v116, v117
	v_cvt_pk_bf16_f32 v105, v118, v119
	v_cvt_pk_bf16_f32 v106, v112, v113
	v_cvt_pk_bf16_f32 v107, v114, v115
	v_cvt_pk_bf16_f32 v88, v100, v101
	v_cvt_pk_bf16_f32 v89, v102, v103
	v_cvt_pk_bf16_f32 v90, v96, v97
	v_cvt_pk_bf16_f32 v91, v98, v99
	global_store_dwordx4 v[92:93], v[76:79], off offset:256
	v_cvt_pk_bf16_f32 v74, v80, v81
	v_cvt_pk_bf16_f32 v75, v82, v83
	v_lshl_add_u64 v[76:77], v[72:73], 0, v[138:139]
	v_cvt_pk_bf16_f32 v72, v84, v85
	v_cvt_pk_bf16_f32 v73, v86, v87
	v_cvt_pk_bf16_f32 v71, v66, v67
	v_cvt_pk_bf16_f32 v60, v60, v61
	v_cvt_pk_bf16_f32 v61, v62, v63
	v_cvt_pk_bf16_f32 v62, v56, v57
	v_cvt_pk_bf16_f32 v63, v58, v59
	v_cvt_pk_bf16_f32 v40, v52, v53
	v_cvt_pk_bf16_f32 v41, v54, v55
	v_cvt_pk_bf16_f32 v42, v48, v49
	v_cvt_pk_bf16_f32 v43, v50, v51
	v_cvt_pk_bf16_f32 v24, v36, v37
	v_cvt_pk_bf16_f32 v25, v38, v39
	v_cvt_pk_bf16_f32 v26, v32, v33
	v_cvt_pk_bf16_f32 v27, v34, v35
	global_store_dwordx4 v[28:29], v[12:15], off offset:256
	v_cvt_pk_bf16_f32 v10, v16, v17
	v_cvt_pk_bf16_f32 v11, v18, v19
	v_lshl_add_u64 v[12:13], v[8:9], 0, v[138:139]
	v_cvt_pk_bf16_f32 v8, v20, v21
	v_cvt_pk_bf16_f32 v9, v22, v23
	v_cvt_pk_bf16_f32 v4, v4, v5
	v_cvt_pk_bf16_f32 v5, v6, v7
	v_cvt_pk_bf16_f32 v6, v0, v1
	v_cvt_pk_bf16_f32 v7, v2, v3
	s_and_b64 vcc, exec, s[6:7]
	s_mov_b32 s31, s8
	s_mov_b32 s33, s10
	s_mov_b64 s[18:19], s[14:15]
	s_mov_b64 s[16:17], s[12:13]
	global_store_dwordx4 v[142:143], v[124:127], off
	global_store_dwordx4 v[108:109], v[104:107], off
	global_store_dwordx4 v[92:93], v[88:91], off
	global_store_dwordx4 v[76:77], v[72:75], off
	global_store_dwordx4 v[76:77], v[68:71], off offset:256
	global_store_dwordx4 v[64:65], v[60:63], off
	global_store_dwordx4 v[44:45], v[40:43], off
	global_store_dwordx4 v[28:29], v[24:27], off
	global_store_dwordx4 v[12:13], v[8:11], off
	global_store_dwordx4 v[12:13], v[4:7], off offset:256
	s_cbranch_vccz .LBB0_228
	s_waitcnt vmcnt(0)
	s_cmpk_gt_u32 s2, 0xff
	s_cbranch_scc1 .LBB0_235
	s_barrier

; #define PG8_STAGE(bufoff, gbase) do { _Pragma("unroll") for (int _i = 0; _i < 2; ++_i) \
;         __builtin_amdgcn_global_load_lds((const unsigned*)((const char*)(gbase) + voff[_i]), (LAS unsigned*)(lds + (bufoff) + ldsw + _i * 8192), 16, 0, 0); } while (0)
; #define PG8_LDA(dst, b, h) do { _Pragma("unroll") for (int m = 0; m < 4; ++m) _Pragma("unroll") for (int k = 0; k < 2; ++k) dst[m][k] = *(const LAS bf16x8*)(lds + PG8_SA(b, h) + aoff + m * 2048 + k * 1024); } while (0)
; #define PG8_LDB(dst, b, h) do { _Pragma("unroll") for (int n = 0; n < 2; ++n) _Pragma("unroll") for (int k = 0; k < 2; ++k) dst[n][k] = *(const LAS bf16x8*)(lds + PG8_SB(b, h) + boff + n * 2048 + k * 1024); } while (0)
; #define PG8_MMA(ai, bj, At, Bt) do { __builtin_amdgcn_s_setprio(1); _Pragma("unroll") for (int m = 0; m < 4; ++m) _Pragma("unroll") for (int n = 0; n < 2; ++n) _Pragma("unroll") for (int k = 0; k < 2; ++k) \
;         acc[ai][bj][m][n] = __builtin_amdgcn_mfma_f32_16x16x32_bf16(Bt[n][k], At[m][k], acc[ai][bj][m][n], 0, 0, 0); __builtin_amdgcn_s_setprio(0); } while (0)
; #define PG8_WAIT_V(n) asm volatile("s_waitcnt vmcnt(" #n ")" ::: "memory")
; #define PG8_WAIT_L(n) asm volatile("s_waitcnt lgkmcnt(" #n ")" ::: "memory")
; #define PG8_BAR __builtin_amdgcn_s_barrier()
; #define PG8_SCHED __builtin_amdgcn_sched_barrier(0)
; template <class Epi>
; DI void gemm_phase(LAS unsigned char* lds, const Gemm g, const StaticOrder& S, const Epi& E) {
;     ...
;         for (int t = 0; t < nt; t += 2) {
;             const bool last = (t == nt - 2);
;             const char* a1 = cA + (size_t)(t + 1) * kstep;
;             const char* a2 = last ? nA : cA + (size_t)(t + 2) * kstep; const char* b2 = last ? nB : cB + (size_t)(t + 2) * kstep;
;             const char* a3 = a2 + kstep; const char* b3 = b2 + kstep;
;             PG8_LDB(B0, 0, 0); PG8_SCHED; PG8_LDA(At, 0, 0); PG8_STAGE(PG8_SA(1, 1), a1 + hstep);
;             PG8_WAIT_L(8); PG8_BAR; PG8_WAIT_L(0); PG8_MMA(0, 0, At, B0); PG8_BAR; PG8_SCHED;
;             PG8_LDB(B1, 0, 1); PG8_STAGE(PG8_SB(0, 0), b2);
;             PG8_BAR; PG8_WAIT_L(0); PG8_MMA(0, 1, At, B1); PG8_BAR;
;             PG8_LDA(At, 0, 1); PG8_STAGE(PG8_SA(0, 0), a2);
;             PG8_BAR; PG8_WAIT_L(0); PG8_MMA(1, 0, At, B0); PG8_BAR; PG8_SCHED;
;             PG8_STAGE(PG8_SB(0, 1), b2 + hstep);
;             PG8_WAIT_V(6); PG8_BAR; PG8_MMA(1, 1, At, B1); PG8_BAR;
.LBB0_320:
	s_add_u32 s26, s24, 0x100
	s_addc_u32 s27, s25, 0
	s_add_i32 s47, 0, 0x10000
	ds_read_b128 v[128:131], v226
	ds_read_b128 v[132:135], v226 offset:1024
	ds_read_b128 v[136:139], v226 offset:2048
	ds_read_b128 v[140:143], v226 offset:3072
	s_cmp_eq_u32 s46, 28
	s_cselect_b32 s31, s4, s27
	s_cselect_b32 s30, s5, s26
	s_cselect_b32 s29, s9, s45
	s_cselect_b32 s28, s11, s33
	v_lshl_add_u64 v[214:215], s[24:25], 0, v[190:191]
	s_add_i32 m0, s38, 0xc000
	ds_read_b128 v[144:147], v228
	ds_read_b128 v[148:151], v228 offset:1024
	ds_read_b128 v[152:155], v228 offset:2048
	ds_read_b128 v[194:197], v228 offset:3072
	ds_read_b128 v[198:201], v228 offset:4096
	ds_read_b128 v[202:205], v228 offset:5120
	ds_read_b128 v[206:209], v228 offset:6144
	ds_read_b128 v[210:213], v228 offset:7168
	global_load_lds_dwordx4 v[214:215], off
	v_lshl_add_u64 v[214:215], s[24:25], 0, v[192:193]
	s_add_i32 m0, s38, 0xe000
	s_nop 0
	global_load_lds_dwordx4 v[214:215], off
	s_waitcnt lgkmcnt(8)
	s_barrier
	s_waitcnt lgkmcnt(0)
	v_mfma_f32_16x16x32_bf16 v[124:127], v[128:131], v[144:147], v[124:127]
	v_mfma_f32_16x16x32_bf16 v[120:123], v[136:139], v[144:147], v[120:123]
	v_mfma_f32_16x16x32_bf16 v[116:119], v[128:131], v[152:155], v[116:119]
	v_mfma_f32_16x16x32_bf16 v[112:115], v[136:139], v[152:155], v[112:115]
	v_mfma_f32_16x16x32_bf16 v[108:111], v[128:131], v[198:201], v[108:111]
	v_mfma_f32_16x16x32_bf16 v[104:107], v[136:139], v[198:201], v[104:107]
	v_mfma_f32_16x16x32_bf16 v[100:103], v[128:131], v[206:209], v[100:103]
	v_mfma_f32_16x16x32_bf16 v[96:99], v[136:139], v[206:209], v[96:99]
	v_mfma_f32_16x16x32_bf16 v[124:127], v[132:135], v[148:151], v[124:127]
	v_mfma_f32_16x16x32_bf16 v[120:123], v[140:143], v[148:151], v[120:123]
	v_mfma_f32_16x16x32_bf16 v[116:119], v[132:135], v[194:197], v[116:119]
	v_mfma_f32_16x16x32_bf16 v[112:115], v[140:143], v[194:197], v[112:115]
	v_mfma_f32_16x16x32_bf16 v[108:111], v[132:135], v[202:205], v[108:111]
	v_mfma_f32_16x16x32_bf16 v[104:107], v[140:143], v[202:205], v[104:107]
	v_mfma_f32_16x16x32_bf16 v[100:103], v[132:135], v[210:213], v[100:103]
	v_mfma_f32_16x16x32_bf16 v[96:99], v[140:143], v[210:213], v[96:99]
	s_barrier
	ds_read_b128 v[214:217], v226 offset:16384
	ds_read_b128 v[230:233], v226 offset:17408
	ds_read_b128 v[234:237], v226 offset:18432
	ds_read_b128 v[238:241], v226 offset:19456
	s_add_i32 s48, 0, 0x14000
	s_add_i32 s24, s47, s37
	s_mov_b32 m0, s24
	s_nop 0
	global_load_lds_dwordx4 v188, s[28:29]
	s_add_i32 m0, s24, 0x2000
	s_nop 0
	global_load_lds_dwordx4 v186, s[28:29]
	s_waitcnt lgkmcnt(0)
	s_barrier
	v_mfma_f32_16x16x32_bf16 v[60:63], v[214:217], v[144:147], v[60:63]
	v_mfma_f32_16x16x32_bf16 v[56:59], v[234:237], v[144:147], v[56:59]
	v_mfma_f32_16x16x32_bf16 v[52:55], v[214:217], v[152:155], v[52:55]
	v_mfma_f32_16x16x32_bf16 v[48:51], v[234:237], v[152:155], v[48:51]
	v_mfma_f32_16x16x32_bf16 v[44:47], v[214:217], v[198:201], v[44:47]
	v_mfma_f32_16x16x32_bf16 v[40:43], v[234:237], v[198:201], v[40:43]
	v_mfma_f32_16x16x32_bf16 v[36:39], v[214:217], v[206:209], v[36:39]
	v_mfma_f32_16x16x32_bf16 v[32:35], v[234:237], v[206:209], v[32:35]
	v_mfma_f32_16x16x32_bf16 v[60:63], v[230:233], v[148:151], v[60:63]
	s_mov_b32 m0, s38
	v_mfma_f32_16x16x32_bf16 v[56:59], v[238:241], v[148:151], v[56:59]
	s_mov_b64 s[100:101], s[30:31]
	v_mfma_f32_16x16x32_bf16 v[52:55], v[230:233], v[194:197], v[52:55]
	v_mfma_f32_16x16x32_bf16 v[48:51], v[238:241], v[194:197], v[48:51]
	v_mfma_f32_16x16x32_bf16 v[44:47], v[230:233], v[202:205], v[44:47]
	v_mfma_f32_16x16x32_bf16 v[40:43], v[238:241], v[202:205], v[40:43]
	v_mfma_f32_16x16x32_bf16 v[36:39], v[230:233], v[210:213], v[36:39]
	v_mfma_f32_16x16x32_bf16 v[32:35], v[238:241], v[210:213], v[32:35]
	s_barrier
	ds_read_b128 v[144:147], v228 offset:16384
	ds_read_b128 v[148:151], v228 offset:17408
	ds_read_b128 v[152:155], v228 offset:18432
	ds_read_b128 v[194:197], v228 offset:19456
	ds_read_b128 v[198:201], v228 offset:20480
	ds_read_b128 v[202:205], v228 offset:21504
	ds_read_b128 v[206:209], v228 offset:22528
	ds_read_b128 v[210:213], v228 offset:23552
	global_load_lds_dwordx4 v188, s[30:31]
	s_mov_b64 s[100:101], s[30:31]
	s_mov_b32 m0, s39
	s_nop 0
	global_load_lds_dwordx4 v186, s[30:31]
	s_waitcnt lgkmcnt(0)
	s_barrier
	v_mfma_f32_16x16x32_bf16 v[92:95], v[128:131], v[144:147], v[92:95]
	v_mfma_f32_16x16x32_bf16 v[88:91], v[136:139], v[144:147], v[88:91]
	v_mfma_f32_16x16x32_bf16 v[84:87], v[128:131], v[152:155], v[84:87]
	v_mfma_f32_16x16x32_bf16 v[80:83], v[136:139], v[152:155], v[80:83]
	v_mfma_f32_16x16x32_bf16 v[76:79], v[128:131], v[198:201], v[76:79]
	v_mfma_f32_16x16x32_bf16 v[72:75], v[136:139], v[198:201], v[72:75]
	v_mfma_f32_16x16x32_bf16 v[68:71], v[128:131], v[206:209], v[68:71]
	v_mfma_f32_16x16x32_bf16 v[64:67], v[136:139], v[206:209], v[64:67]
	v_mfma_f32_16x16x32_bf16 v[92:95], v[132:135], v[148:151], v[92:95]
	v_mfma_f32_16x16x32_bf16 v[88:91], v[140:143], v[148:151], v[88:91]
	v_mfma_f32_16x16x32_bf16 v[84:87], v[132:135], v[194:197], v[84:87]
	v_mfma_f32_16x16x32_bf16 v[80:83], v[140:143], v[194:197], v[80:83]
	v_mfma_f32_16x16x32_bf16 v[76:79], v[132:135], v[202:205], v[76:79]
	v_mfma_f32_16x16x32_bf16 v[72:75], v[140:143], v[202:205], v[72:75]
	v_mfma_f32_16x16x32_bf16 v[68:71], v[132:135], v[210:213], v[68:71]
	v_mfma_f32_16x16x32_bf16 v[64:67], v[140:143], v[210:213], v[64:67]
	s_barrier
	s_add_u32 s24, s28, 0x80000
	s_addc_u32 s25, s29, 0
	s_add_i32 s47, s48, s37
	s_mov_b32 m0, s47
	s_nop 0
	global_load_lds_dwordx4 v188, s[24:25]
	s_add_i32 m0, s47, 0x2000
	s_nop 0
	global_load_lds_dwordx4 v186, s[24:25]
	s_waitcnt vmcnt(6)
	s_barrier
; #define PG8_STAGE(bufoff, gbase) do { _Pragma("unroll") for (int _i = 0; _i < 2; ++_i) \
;         __builtin_amdgcn_global_load_lds((const unsigned*)((const char*)(gbase) + voff[_i]), (LAS unsigned*)(lds + (bufoff) + ldsw + _i * 8192), 16, 0, 0); } while (0)
; #define PG8_LDA(dst, b, h) do { _Pragma("unroll") for (int m = 0; m < 4; ++m) _Pragma("unroll") for (int k = 0; k < 2; ++k) dst[m][k] = *(const LAS bf16x8*)(lds + PG8_SA(b, h) + aoff + m * 2048 + k * 1024); } while (0)
; #define PG8_LDB(dst, b, h) do { _Pragma("unroll") for (int n = 0; n < 2; ++n) _Pragma("unroll") for (int k = 0; k < 2; ++k) dst[n][k] = *(const LAS bf16x8*)(lds + PG8_SB(b, h) + boff + n * 2048 + k * 1024); } while (0)
; #define PG8_MMA(ai, bj, At, Bt) do { __builtin_amdgcn_s_setprio(1); _Pragma("unroll") for (int m = 0; m < 4; ++m) _Pragma("unroll") for (int n = 0; n < 2; ++n) _Pragma("unroll") for (int k = 0; k < 2; ++k) \
;         acc[ai][bj][m][n] = __builtin_amdgcn_mfma_f32_16x16x32_bf16(Bt[n][k], At[m][k], acc[ai][bj][m][n], 0, 0, 0); __builtin_amdgcn_s_setprio(0); } while (0)
; #define PG8_WAIT_V(n) asm volatile("s_waitcnt vmcnt(" #n ")" ::: "memory")
; #define PG8_WAIT_L(n) asm volatile("s_waitcnt lgkmcnt(" #n ")" ::: "memory")
; #define PG8_BAR __builtin_amdgcn_s_barrier()
; #define PG8_SCHED __builtin_amdgcn_sched_barrier(0)
; template <class Epi>
; DI void gemm_phase(LAS unsigned char* lds, const Gemm g, const StaticOrder& S, const Epi& E) {
;     ...
;             PG8_WAIT_V(6); PG8_BAR; PG8_MMA(1, 1, At, B1); PG8_BAR;
;             PG8_LDB(B0, 1, 0); PG8_SCHED; PG8_LDA(At, 1, 0); PG8_STAGE(PG8_SA(0, 1), a2 + hstep);
;             PG8_WAIT_L(8); PG8_BAR; PG8_WAIT_L(0); PG8_MMA(0, 0, At, B0); PG8_BAR; PG8_SCHED;
;             PG8_LDB(B1, 1, 1); PG8_STAGE(PG8_SB(1, 0), b3);
;             PG8_BAR; PG8_WAIT_L(0); PG8_MMA(0, 1, At, B1); PG8_BAR;
;             PG8_LDA(At, 1, 1); PG8_STAGE(PG8_SA(1, 0), a3);
;             PG8_BAR; PG8_WAIT_L(0); PG8_MMA(1, 0, At, B0); PG8_BAR; PG8_SCHED;
	v_mfma_f32_16x16x32_bf16 v[28:31], v[214:217], v[144:147], v[28:31]
	v_mfma_f32_16x16x32_bf16 v[24:27], v[234:237], v[144:147], v[24:27]
	v_mfma_f32_16x16x32_bf16 v[20:23], v[214:217], v[152:155], v[20:23]
	v_mfma_f32_16x16x32_bf16 v[16:19], v[234:237], v[152:155], v[16:19]
	v_mfma_f32_16x16x32_bf16 v[12:15], v[214:217], v[198:201], v[12:15]
	v_mfma_f32_16x16x32_bf16 v[8:11], v[234:237], v[198:201], v[8:11]
	v_mfma_f32_16x16x32_bf16 v[4:7], v[214:217], v[206:209], v[4:7]
	v_mfma_f32_16x16x32_bf16 v[0:3], v[234:237], v[206:209], v[0:3]
	v_mfma_f32_16x16x32_bf16 v[28:31], v[230:233], v[148:151], v[28:31]
	s_add_i32 s47, 0, 0x18000
	v_mfma_f32_16x16x32_bf16 v[24:27], v[238:241], v[148:151], v[24:27]
	v_mfma_f32_16x16x32_bf16 v[20:23], v[230:233], v[194:197], v[20:23]
	v_mfma_f32_16x16x32_bf16 v[16:19], v[238:241], v[194:197], v[16:19]
	v_mfma_f32_16x16x32_bf16 v[12:15], v[230:233], v[202:205], v[12:15]
	v_mfma_f32_16x16x32_bf16 v[8:11], v[238:241], v[202:205], v[8:11]
	v_mfma_f32_16x16x32_bf16 v[4:7], v[230:233], v[210:213], v[4:7]
	v_mfma_f32_16x16x32_bf16 v[0:3], v[238:241], v[210:213], v[0:3]
	s_barrier
	ds_read_b128 v[128:131], v226 offset:32768
	ds_read_b128 v[132:135], v226 offset:33792
	ds_read_b128 v[136:139], v226 offset:34816
	ds_read_b128 v[140:143], v226 offset:35840
	ds_read_b128 v[144:147], v228 offset:32768
	ds_read_b128 v[148:151], v228 offset:33792
	ds_read_b128 v[152:155], v228 offset:34816
	ds_read_b128 v[194:197], v228 offset:35840
	ds_read_b128 v[198:201], v228 offset:36864
	ds_read_b128 v[202:205], v228 offset:37888
	ds_read_b128 v[206:209], v228 offset:38912
	ds_read_b128 v[210:213], v228 offset:39936
	s_add_u32 s24, s30, 0x80000
	s_addc_u32 s25, s31, 0
	s_mov_b32 m0, s40
	s_nop 0
	global_load_lds_dwordx4 v188, s[24:25]
	s_mov_b32 m0, s41
	s_nop 0
	global_load_lds_dwordx4 v186, s[24:25]
	s_waitcnt lgkmcnt(8)
	s_barrier
	s_waitcnt lgkmcnt(0)
	v_mfma_f32_16x16x32_bf16 v[124:127], v[128:131], v[144:147], v[124:127]
	v_mfma_f32_16x16x32_bf16 v[120:123], v[136:139], v[144:147], v[120:123]
	v_mfma_f32_16x16x32_bf16 v[116:119], v[128:131], v[152:155], v[116:119]
	v_mfma_f32_16x16x32_bf16 v[112:115], v[136:139], v[152:155], v[112:115]
	v_mfma_f32_16x16x32_bf16 v[108:111], v[128:131], v[198:201], v[108:111]
	v_mfma_f32_16x16x32_bf16 v[104:107], v[136:139], v[198:201], v[104:107]
	v_mfma_f32_16x16x32_bf16 v[100:103], v[128:131], v[206:209], v[100:103]
	v_mfma_f32_16x16x32_bf16 v[96:99], v[136:139], v[206:209], v[96:99]
	v_mfma_f32_16x16x32_bf16 v[124:127], v[132:135], v[148:151], v[124:127]
	v_mfma_f32_16x16x32_bf16 v[120:123], v[140:143], v[148:151], v[120:123]
	v_mfma_f32_16x16x32_bf16 v[116:119], v[132:135], v[194:197], v[116:119]
	v_mfma_f32_16x16x32_bf16 v[112:115], v[140:143], v[194:197], v[112:115]
	v_mfma_f32_16x16x32_bf16 v[108:111], v[132:135], v[202:205], v[108:111]
	v_mfma_f32_16x16x32_bf16 v[104:107], v[140:143], v[202:205], v[104:107]
	v_mfma_f32_16x16x32_bf16 v[100:103], v[132:135], v[210:213], v[100:103]
	v_mfma_f32_16x16x32_bf16 v[96:99], v[140:143], v[210:213], v[96:99]
	s_barrier
	ds_read_b128 v[214:217], v226 offset:49152
	ds_read_b128 v[230:233], v226 offset:50176
	ds_read_b128 v[234:237], v226 offset:51200
	ds_read_b128 v[238:241], v226 offset:52224
	s_add_i32 s30, 0, 0x1c000
	s_add_i32 s24, s47, s37
	s_add_i32 m0, s24, 0xffffff80
	s_nop 0
	global_load_lds_dwordx4 v188, s[28:29] offset:128
	s_add_i32 m0, s24, 0x1f80
	s_nop 0
	global_load_lds_dwordx4 v186, s[28:29] offset:128
	s_waitcnt lgkmcnt(0)
	s_barrier
	v_mfma_f32_16x16x32_bf16 v[60:63], v[214:217], v[144:147], v[60:63]
	v_mfma_f32_16x16x32_bf16 v[56:59], v[234:237], v[144:147], v[56:59]
	v_mfma_f32_16x16x32_bf16 v[52:55], v[214:217], v[152:155], v[52:55]
	v_mfma_f32_16x16x32_bf16 v[48:51], v[234:237], v[152:155], v[48:51]
	v_mfma_f32_16x16x32_bf16 v[44:47], v[214:217], v[198:201], v[44:47]
	v_mfma_f32_16x16x32_bf16 v[40:43], v[234:237], v[198:201], v[40:43]
	v_mfma_f32_16x16x32_bf16 v[36:39], v[214:217], v[206:209], v[36:39]
	v_mfma_f32_16x16x32_bf16 v[32:35], v[234:237], v[206:209], v[32:35]
	v_mfma_f32_16x16x32_bf16 v[60:63], v[230:233], v[148:151], v[60:63]
	s_add_i32 m0, s42, 0xffffff80
	v_mfma_f32_16x16x32_bf16 v[56:59], v[238:241], v[148:151], v[56:59]
	v_mfma_f32_16x16x32_bf16 v[52:55], v[230:233], v[194:197], v[52:55]
	v_mfma_f32_16x16x32_bf16 v[48:51], v[238:241], v[194:197], v[48:51]
	v_mfma_f32_16x16x32_bf16 v[44:47], v[230:233], v[202:205], v[44:47]
	v_mfma_f32_16x16x32_bf16 v[40:43], v[238:241], v[202:205], v[40:43]
	v_mfma_f32_16x16x32_bf16 v[36:39], v[230:233], v[210:213], v[36:39]
	v_mfma_f32_16x16x32_bf16 v[32:35], v[238:241], v[210:213], v[32:35]
	s_barrier
	ds_read_b128 v[144:147], v228 offset:49152
	ds_read_b128 v[148:151], v228 offset:50176
	ds_read_b128 v[152:155], v228 offset:51200
	ds_read_b128 v[194:197], v228 offset:52224
	ds_read_b128 v[198:201], v228 offset:53248
	ds_read_b128 v[202:205], v228 offset:54272
	ds_read_b128 v[206:209], v228 offset:55296
	ds_read_b128 v[210:213], v228 offset:56320
	global_load_lds_dwordx4 v188, s[100:101] offset:128
	s_add_i32 m0, s43, 0xffffff80
	s_nop 0
	global_load_lds_dwordx4 v186, s[100:101] offset:128
	s_waitcnt lgkmcnt(0)
	s_barrier
; #define PG8_STAGE(bufoff, gbase) do { _Pragma("unroll") for (int _i = 0; _i < 2; ++_i) \
;         __builtin_amdgcn_global_load_lds((const unsigned*)((const char*)(gbase) + voff[_i]), (LAS unsigned*)(lds + (bufoff) + ldsw + _i * 8192), 16, 0, 0); } while (0)
; #define PG8_MMA(ai, bj, At, Bt) do { __builtin_amdgcn_s_setprio(1); _Pragma("unroll") for (int m = 0; m < 4; ++m) _Pragma("unroll") for (int n = 0; n < 2; ++n) _Pragma("unroll") for (int k = 0; k < 2; ++k) \
;         acc[ai][bj][m][n] = __builtin_amdgcn_mfma_f32_16x16x32_bf16(Bt[n][k], At[m][k], acc[ai][bj][m][n], 0, 0, 0); __builtin_amdgcn_s_setprio(0); } while (0)
; #define PG8_WAIT_V(n) asm volatile("s_waitcnt vmcnt(" #n ")" ::: "memory")
; #define PG8_WAIT_L(n) asm volatile("s_waitcnt lgkmcnt(" #n ")" ::: "memory")
; #define PG8_BAR __builtin_amdgcn_s_barrier()
; #define PG8_SCHED __builtin_amdgcn_sched_barrier(0)
; template <class Epi>
; DI void gemm_phase(LAS unsigned char* lds, const Gemm g, const StaticOrder& S, const Epi& E) {
;     ...
;             PG8_BAR; PG8_WAIT_L(0); PG8_MMA(1, 0, At, B0); PG8_BAR; PG8_SCHED;
;             PG8_STAGE(PG8_SB(1, 1), b3 + hstep);
;             PG8_WAIT_V(6); PG8_BAR; PG8_MMA(1, 1, At, B1); PG8_BAR;
;     template <bool LN, int BJ> DI void load_gb(unsigned col0, f32x4 (&gv)[2], f32x4 (&bv)[2]) const {
; #pragma unroll
;         for (int n = 0; n < 2; ++n) {
;             if (LN) { gv[n] = *(const f32x4*)(gam + col0 + BJ * HALF + n * 16) * ALPHA; bv[n] = *(const f32x4*)(bet + col0 + BJ * HALF + n * 16) * ALPHA; }
;             else { gv[n] = (f32x4){ALPHA, ALPHA, ALPHA, ALPHA}; bv[n] = (f32x4){0.f, 0.f, 0.f, 0.f}; }
;         }
;     }
;     template <bool LN> DI void run(const f32x4 (&acc)[2][2][4][2], const Unit& u, int wr, int wc, int fr, int fq) const {
;         const unsigned row0 = u.pm * BM + wr * 64 + fr, col0 = u.pn * BM + wc * 32 + 4 * fq;
;         f32x4 gv[2], bv[2];
;         load_gb<LN, 0>(col0, gv, bv);
;         batch<LN, 0, 0, 4>(acc, row0, col0, gv, bv);
;         batch<LN, 0, 4, 8>(acc, row0, col0, gv, bv);
;         batch<LN, 0, 8, 12>(acc, row0, col0, gv, bv);
	v_mfma_f32_16x16x32_bf16 v[92:95], v[128:131], v[144:147], v[92:95]
	v_mfma_f32_16x16x32_bf16 v[88:91], v[136:139], v[144:147], v[88:91]
	v_mfma_f32_16x16x32_bf16 v[84:87], v[128:131], v[152:155], v[84:87]
	v_mfma_f32_16x16x32_bf16 v[80:83], v[136:139], v[152:155], v[80:83]
	v_mfma_f32_16x16x32_bf16 v[76:79], v[128:131], v[198:201], v[76:79]
	v_mfma_f32_16x16x32_bf16 v[72:75], v[136:139], v[198:201], v[72:75]
	v_mfma_f32_16x16x32_bf16 v[68:71], v[128:131], v[206:209], v[68:71]
	v_mfma_f32_16x16x32_bf16 v[64:67], v[136:139], v[206:209], v[64:67]
	v_mfma_f32_16x16x32_bf16 v[92:95], v[132:135], v[148:151], v[92:95]
	v_mfma_f32_16x16x32_bf16 v[88:91], v[140:143], v[148:151], v[88:91]
	v_mfma_f32_16x16x32_bf16 v[84:87], v[132:135], v[194:197], v[84:87]
	v_mfma_f32_16x16x32_bf16 v[80:83], v[140:143], v[194:197], v[80:83]
	v_mfma_f32_16x16x32_bf16 v[76:79], v[132:135], v[202:205], v[76:79]
	v_mfma_f32_16x16x32_bf16 v[72:75], v[140:143], v[202:205], v[72:75]
	v_mfma_f32_16x16x32_bf16 v[68:71], v[132:135], v[210:213], v[68:71]
	v_mfma_f32_16x16x32_bf16 v[64:67], v[140:143], v[210:213], v[64:67]
	s_barrier
	s_add_u32 s24, s28, 0x80080
	s_addc_u32 s25, s29, 0
	s_add_i32 s28, s30, s37
	s_mov_b32 m0, s28
	s_nop 0
	global_load_lds_dwordx4 v188, s[24:25]
	s_add_i32 m0, s28, 0x2000
	s_nop 0
	global_load_lds_dwordx4 v186, s[24:25]
	s_waitcnt vmcnt(6)
	s_barrier
	v_mfma_f32_16x16x32_bf16 v[28:31], v[214:217], v[144:147], v[28:31]
	v_mfma_f32_16x16x32_bf16 v[24:27], v[234:237], v[144:147], v[24:27]
	v_mfma_f32_16x16x32_bf16 v[20:23], v[214:217], v[152:155], v[20:23]
	v_mfma_f32_16x16x32_bf16 v[16:19], v[234:237], v[152:155], v[16:19]
	v_mfma_f32_16x16x32_bf16 v[12:15], v[214:217], v[198:201], v[12:15]
	v_mfma_f32_16x16x32_bf16 v[8:11], v[234:237], v[198:201], v[8:11]
	v_mfma_f32_16x16x32_bf16 v[4:7], v[214:217], v[206:209], v[4:7]
	v_mfma_f32_16x16x32_bf16 v[0:3], v[234:237], v[206:209], v[0:3]
	v_mfma_f32_16x16x32_bf16 v[28:31], v[230:233], v[148:151], v[28:31]
	s_add_i32 s46, s46, 2
	v_mfma_f32_16x16x32_bf16 v[24:27], v[238:241], v[148:151], v[24:27]
	s_add_u32 s33, s33, 0x100
	v_mfma_f32_16x16x32_bf16 v[20:23], v[230:233], v[194:197], v[20:23]
	s_addc_u32 s45, s45, 0
	v_mfma_f32_16x16x32_bf16 v[16:19], v[238:241], v[194:197], v[16:19]
	s_cmp_gt_u32 s46, 29
	v_mfma_f32_16x16x32_bf16 v[12:15], v[230:233], v[202:205], v[12:15]
	s_mov_b64 s[24:25], s[26:27]
	v_mfma_f32_16x16x32_bf16 v[8:11], v[238:241], v[202:205], v[8:11]
	v_mfma_f32_16x16x32_bf16 v[4:7], v[230:233], v[210:213], v[4:7]
	v_mfma_f32_16x16x32_bf16 v[0:3], v[238:241], v[210:213], v[0:3]
	s_barrier
	s_cbranch_scc0 .LBB0_320
	v_lshl_add_u32 v206, s3, 8, v225
	v_lshl_or_b32 v158, s2, 8, v227
	v_lshlrev_b32_e32 v232, 11, v206
	s_andn2_b64 vcc, exec, s[14:15]
	v_or_b32_e32 v231, 16, v158
	v_add_u32_e32 v194, v232, v158
	v_or_b32_e32 v230, 0x80, v158
	v_or_b32_e32 v229, 0x90, v158
	s_cbranch_vccnz .LBB0_323
	v_lshlrev_b64 v[132:133], 2, v[158:159]
	v_lshl_add_u64 v[140:141], s[16:17], 0, v[132:133]
	global_load_dwordx4 v[128:131], v[140:141], off
	v_lshl_add_u64 v[142:143], s[18:19], 0, v[132:133]
	v_readlane_b32 s2, v253, 8
	v_mov_b32_e32 v195, v159
	v_lshlrev_b32_e32 v136, 1, v206
	v_mov_b32_e32 v137, v159
	v_readlane_b32 s3, v253, 9
	v_lshlrev_b64 v[212:213], 2, v[194:195]
	v_add_u32_e32 v146, v232, v231
	v_lshl_add_u64 v[144:145], v[136:137], 2, s[2:3]
	v_lshl_add_u64 v[136:137], s[88:89], 0, v[212:213]
	v_mov_b32_e32 v147, v159
	v_lshl_add_u64 v[146:147], v[146:147], 2, s[88:89]
	v_or_b32_e32 v195, 16, v206
	v_mov_b32_e32 v201, v159
	v_mov_b32_e32 v209, v159
	v_lshl_add_u64 v[212:213], s[90:91], 0, v[212:213]
	s_waitcnt vmcnt(0)
	v_pk_mul_f32 v[152:153], v[130:131], s[78:79] op_sel_hi:[1,0]
	v_pk_mul_f32 v[154:155], v[128:129], s[78:79] op_sel_hi:[1,0]
	global_load_dwordx4 v[132:135], v[142:143], off
	global_load_dwordx4 v[128:131], v[140:141], off offset:64
	global_load_dwordx2 v[204:205], v[144:145], off
	global_load_dwordx4 v[196:199], v[146:147], off
	v_lshlrev_b32_e32 v146, 1, v195
	global_load_dwordx4 v[136:139], v[136:137], off
	v_lshlrev_b32_e32 v195, 11, v195
	v_mov_b32_e32 v147, v159
	v_add_u32_e32 v200, v195, v158
	v_lshl_add_u64 v[146:147], v[146:147], 2, s[2:3]
	v_lshl_add_u64 v[200:201], v[200:201], 2, s[88:89]
	global_load_dwordx2 v[214:215], v[146:147], off
	v_add_u32_e32 v208, v195, v231
	global_load_dwordx4 v[200:203], v[200:201], off
	v_lshl_add_u64 v[208:209], v[208:209], 2, s[88:89]
	global_load_dwordx4 v[208:211], v[208:209], off
	s_waitcnt vmcnt(0)
	v_pk_mul_f32 v[148:149], v[130:131], s[78:79] op_sel_hi:[1,0]
	v_pk_mul_f32 v[150:151], v[128:129], s[78:79] op_sel_hi:[1,0]
	global_load_dwordx4 v[128:131], v[142:143], off offset:64
	v_sub_f32_e32 v137, v137, v204
	v_sub_f32_e32 v136, v136, v204
	v_sub_f32_e32 v139, v139, v204
	v_sub_f32_e32 v138, v138, v204
	v_pk_mul_f32 v[138:139], v[204:205], v[138:139] op_sel:[1,0]
	v_pk_mul_f32 v[136:137], v[204:205], v[136:137] op_sel:[1,0]
	v_pk_fma_f32 v[138:139], v[152:153], v[138:139], v[126:127]
	v_pk_fma_f32 v[136:137], v[154:155], v[136:137], v[124:125]
	v_pk_fma_f32 v[138:139], v[134:135], s[78:79], v[138:139] op_sel_hi:[1,0,1]
	v_pk_fma_f32 v[136:137], v[132:133], s[78:79], v[136:137] op_sel_hi:[1,0,1]
	global_store_dwordx4 v[212:213], v[136:139], off
	s_nop 1
	v_sub_f32_e32 v137, v197, v204
	v_sub_f32_e32 v136, v196, v204
	v_sub_f32_e32 v139, v199, v204
	v_sub_f32_e32 v138, v198, v204
	v_pk_mul_f32 v[138:139], v[204:205], v[138:139] op_sel:[1,0]
	v_pk_mul_f32 v[136:137], v[204:205], v[136:137] op_sel:[1,0]
	v_pk_fma_f32 v[138:139], v[148:149], v[138:139], v[122:123]
	v_pk_fma_f32 v[136:137], v[150:151], v[136:137], v[120:121]
	v_or_b32_e32 v196, 16, v194
	v_mov_b32_e32 v197, v159
	v_lshl_add_u64 v[196:197], v[196:197], 2, s[90:91]
	s_waitcnt vmcnt(0)
;     template <bool LN, int BJ, int LO, int HI> DI void batch(const f32x4 (&acc)[2][2][4][2], unsigned row0, unsigned col0, const f32x4 (&gv)[2], const f32x4 (&bv)[2]) const {
;         f32x4 r[HI - LO]; float mean[(HI - LO) / 2], rstd[(HI - LO) / 2];
; #pragma unroll
;         for (int i = LO; i < HI; ++i) { const int ai = i >> 3, m = (i >> 1) & 3, n = i & 1; const unsigned row = row0 + ai * HALF + m * 16;
;             if (n == 0) { mean[(i - LO) >> 1] = 0.f; rstd[(i - LO) >> 1] = 1.f;
;                 if (LN) { const float2 st = *(const float2*)(stats + row * 2u); mean[(i - LO) >> 1] = st.x; rstd[(i - LO) >> 1] = st.y; } }
;             r[i - LO] = *(const f32x4*)(src + (row * (unsigned)DM + col0 + BJ * HALF + n * 16)); }
; #pragma unroll
;         for (int i = LO; i < HI; ++i) { const int ai = i >> 3, m = (i >> 1) & 3, n = i & 1; const unsigned row = row0 + ai * HALF + m * 16;
;             *(f32x4*)(Y + (row * (unsigned)DM + col0 + BJ * HALF + n * 16)) = acc[ai][BJ][m][n] + ((r[i - LO] - mean[(i - LO) >> 1]) * rstd[(i - LO) >> 1]) * gv[n] + bv[n]; }
;         __builtin_amdgcn_sched_barrier(0);
;     }
;     template <bool LN, int BJ> DI void load_gb(unsigned col0, f32x4 (&gv)[2], f32x4 (&bv)[2]) const {
; #pragma unroll
;         for (int n = 0; n < 2; ++n) {
;             if (LN) { gv[n] = *(const f32x4*)(gam + col0 + BJ * HALF + n * 16) * ALPHA; bv[n] = *(const f32x4*)(bet + col0 + BJ * HALF + n * 16) * ALPHA; }
;             else { gv[n] = (f32x4){ALPHA, ALPHA, ALPHA, ALPHA}; bv[n] = (f32x4){0.f, 0.f, 0.f, 0.f}; }
;         }
;     }
;     template <bool LN> DI void run(const f32x4 (&acc)[2][2][4][2], const Unit& u, int wr, int wc, int fr, int fq) const {
;         const unsigned row0 = u.pm * BM + wr * 64 + fr, col0 = u.pn * BM + wc * 32 + 4 * fq;
;         f32x4 gv[2], bv[2];
;         load_gb<LN, 0>(col0, gv, bv);
;         batch<LN, 0, 0, 4>(acc, row0, col0, gv, bv);
;         batch<LN, 0, 4, 8>(acc, row0, col0, gv, bv);
;         batch<LN, 0, 8, 12>(acc, row0, col0, gv, bv);
;         batch<LN, 0, 12, 16>(acc, row0, col0, gv, bv);
	v_pk_fma_f32 v[138:139], v[130:131], s[78:79], v[138:139] op_sel_hi:[1,0,1]
	v_pk_fma_f32 v[136:137], v[128:129], s[78:79], v[136:137] op_sel_hi:[1,0,1]
	global_store_dwordx4 v[196:197], v[136:139], off
	v_add_u32_e32 v196, 0x8000, v194
	v_mov_b32_e32 v197, v159
	v_sub_f32_e32 v137, v201, v214
	v_sub_f32_e32 v136, v200, v214
	v_sub_f32_e32 v139, v203, v214
	v_sub_f32_e32 v138, v202, v214
	v_pk_mul_f32 v[138:139], v[214:215], v[138:139] op_sel:[1,0]
	v_pk_mul_f32 v[136:137], v[214:215], v[136:137] op_sel:[1,0]
	v_pk_fma_f32 v[138:139], v[152:153], v[138:139], v[118:119]
	v_pk_fma_f32 v[136:137], v[154:155], v[136:137], v[116:117]
	v_pk_fma_f32 v[138:139], v[134:135], s[78:79], v[138:139] op_sel_hi:[1,0,1]
	v_pk_fma_f32 v[136:137], v[132:133], s[78:79], v[136:137] op_sel_hi:[1,0,1]
	v_lshl_add_u64 v[196:197], v[196:197], 2, s[90:91]
	global_store_dwordx4 v[196:197], v[136:139], off
	v_add_u32_e32 v196, 0x8010, v194
	v_mov_b32_e32 v197, v159
	v_sub_f32_e32 v137, v209, v214
	v_sub_f32_e32 v136, v208, v214
	v_sub_f32_e32 v139, v211, v214
	v_sub_f32_e32 v138, v210, v214
	v_pk_mul_f32 v[138:139], v[214:215], v[138:139] op_sel:[1,0]
	v_pk_mul_f32 v[136:137], v[214:215], v[136:137] op_sel:[1,0]
	v_pk_fma_f32 v[138:139], v[148:149], v[138:139], v[114:115]
	v_pk_fma_f32 v[136:137], v[150:151], v[136:137], v[112:113]
	v_pk_fma_f32 v[138:139], v[130:131], s[78:79], v[138:139] op_sel_hi:[1,0,1]
	v_pk_fma_f32 v[136:137], v[128:129], s[78:79], v[136:137] op_sel_hi:[1,0,1]
	v_lshl_add_u64 v[196:197], v[196:197], 2, s[90:91]
	global_store_dwordx4 v[196:197], v[136:139], off
	s_nop 1
	v_or_b32_e32 v138, 32, v206
	v_lshlrev_b32_e32 v136, 1, v138
	v_mov_b32_e32 v137, v159
	v_lshlrev_b32_e32 v236, 11, v138
	v_lshl_add_u64 v[200:201], v[136:137], 2, s[2:3]
	v_add_u32_e32 v136, v236, v158
	v_lshl_add_u64 v[136:137], v[136:137], 2, s[88:89]
	global_load_dwordx2 v[204:205], v[200:201], off
	v_add_u32_e32 v196, v236, v231
	global_load_dwordx4 v[136:139], v[136:137], off
	v_mov_b32_e32 v197, v159
	v_lshl_add_u64 v[196:197], v[196:197], 2, s[88:89]
	global_load_dwordx4 v[196:199], v[196:197], off
	v_or_b32_e32 v207, 48, v206
	v_lshlrev_b32_e32 v235, 11, v207
	v_lshlrev_b32_e32 v202, 1, v207
	v_mov_b32_e32 v203, v159
	v_add_u32_e32 v208, v235, v158
	v_mov_b32_e32 v209, v159
	v_lshl_add_u64 v[202:203], v[202:203], 2, s[2:3]
	v_lshl_add_u64 v[208:209], v[208:209], 2, s[88:89]
	global_load_dwordx2 v[216:217], v[202:203], off
	v_add_u32_e32 v212, v235, v231
	global_load_dwordx4 v[208:211], v[208:209], off
	v_mov_b32_e32 v213, v159
	v_lshl_add_u64 v[212:213], v[212:213], 2, s[88:89]
	global_load_dwordx4 v[212:215], v[212:213], off
	v_add_u32_e32 v218, 0x10000, v194
	v_mov_b32_e32 v219, v159
	v_lshl_add_u64 v[218:219], v[218:219], 2, s[90:91]
	s_waitcnt vmcnt(0)
	v_sub_f32_e32 v137, v137, v204
	v_sub_f32_e32 v136, v136, v204
	v_sub_f32_e32 v139, v139, v204
	v_sub_f32_e32 v138, v138, v204
	v_pk_mul_f32 v[138:139], v[204:205], v[138:139] op_sel:[1,0]
	v_pk_mul_f32 v[136:137], v[204:205], v[136:137] op_sel:[1,0]
	v_pk_fma_f32 v[138:139], v[152:153], v[138:139], v[110:111]
	v_pk_fma_f32 v[136:137], v[154:155], v[136:137], v[108:109]
	v_pk_fma_f32 v[138:139], v[134:135], s[78:79], v[138:139] op_sel_hi:[1,0,1]
	v_pk_fma_f32 v[136:137], v[132:133], s[78:79], v[136:137] op_sel_hi:[1,0,1]
	global_store_dwordx4 v[218:219], v[136:139], off
	s_nop 1
	v_sub_f32_e32 v137, v197, v204
	v_sub_f32_e32 v136, v196, v204
	v_sub_f32_e32 v139, v199, v204
	v_sub_f32_e32 v138, v198, v204
	v_pk_mul_f32 v[138:139], v[204:205], v[138:139] op_sel:[1,0]
	v_pk_mul_f32 v[136:137], v[204:205], v[136:137] op_sel:[1,0]
	v_pk_fma_f32 v[138:139], v[148:149], v[138:139], v[106:107]
	v_pk_fma_f32 v[136:137], v[150:151], v[136:137], v[104:105]
	v_add_u32_e32 v196, 0x10010, v194
	v_mov_b32_e32 v197, v159
	v_pk_fma_f32 v[138:139], v[130:131], s[78:79], v[138:139] op_sel_hi:[1,0,1]
	v_pk_fma_f32 v[136:137], v[128:129], s[78:79], v[136:137] op_sel_hi:[1,0,1]
	v_lshl_add_u64 v[196:197], v[196:197], 2, s[90:91]
	global_store_dwordx4 v[196:197], v[136:139], off
	v_add_u32_e32 v196, 0x18000, v194
	v_mov_b32_e32 v197, v159
	v_sub_f32_e32 v137, v209, v216
	v_sub_f32_e32 v136, v208, v216
	v_sub_f32_e32 v139, v211, v216
	v_sub_f32_e32 v138, v210, v216
	v_pk_mul_f32 v[138:139], v[216:217], v[138:139] op_sel:[1,0]
	v_pk_mul_f32 v[136:137], v[216:217], v[136:137] op_sel:[1,0]
	v_pk_fma_f32 v[138:139], v[152:153], v[138:139], v[102:103]
	v_pk_fma_f32 v[136:137], v[154:155], v[136:137], v[100:101]
	v_pk_fma_f32 v[138:139], v[134:135], s[78:79], v[138:139] op_sel_hi:[1,0,1]
	v_pk_fma_f32 v[136:137], v[132:133], s[78:79], v[136:137] op_sel_hi:[1,0,1]
	v_lshl_add_u64 v[196:197], v[196:197], 2, s[90:91]
	global_store_dwordx4 v[196:197], v[136:139], off
	v_add_u32_e32 v196, 0x18010, v194
	v_mov_b32_e32 v197, v159
	v_sub_f32_e32 v137, v213, v216
	v_sub_f32_e32 v136, v212, v216
	v_sub_f32_e32 v139, v215, v216
	v_sub_f32_e32 v138, v214, v216
	v_pk_mul_f32 v[138:139], v[216:217], v[138:139] op_sel:[1,0]
	v_pk_mul_f32 v[136:137], v[216:217], v[136:137] op_sel:[1,0]
	v_pk_fma_f32 v[138:139], v[148:149], v[138:139], v[98:99]
	v_pk_fma_f32 v[136:137], v[150:151], v[136:137], v[96:97]
	v_pk_fma_f32 v[138:139], v[130:131], s[78:79], v[138:139] op_sel_hi:[1,0,1]
	v_pk_fma_f32 v[136:137], v[128:129], s[78:79], v[136:137] op_sel_hi:[1,0,1]
	v_lshl_add_u64 v[196:197], v[196:197], 2, s[90:91]
	global_store_dwordx4 v[196:197], v[136:139], off
	s_nop 1
	v_add_u32_e32 v138, 0x80, v206
	v_lshlrev_b32_e32 v136, 1, v138
	v_mov_b32_e32 v137, v159
	v_lshlrev_b32_e32 v233, 11, v138
	v_lshl_add_u64 v[196:197], v[136:137], 2, s[2:3]
	v_add_u32_e32 v136, v233, v158
	v_lshl_add_u64 v[136:137], v[136:137], 2, s[88:89]
	global_load_dwordx2 v[204:205], v[196:197], off
	v_add_u32_e32 v198, v233, v231
	global_load_dwordx4 v[136:139], v[136:137], off
	v_mov_b32_e32 v199, v159
	v_add_u32_e32 v207, 0x90, v206
	v_lshl_add_u64 v[198:199], v[198:199], 2, s[88:89]
	v_lshlrev_b32_e32 v234, 11, v207
	global_load_dwordx4 v[208:211], v[198:199], off
	v_add_u32_e32 v212, v234, v158
	v_mov_b32_e32 v213, v159
	v_lshl_add_u64 v[212:213], v[212:213], 2, s[88:89]
	global_load_dwordx4 v[212:215], v[212:213], off
	v_lshlrev_b32_e32 v198, 1, v207
	v_mov_b32_e32 v199, v159
	v_lshl_add_u64 v[198:199], v[198:199], 2, s[2:3]
	global_load_dwordx2 v[238:239], v[198:199], off
	v_add_u32_e32 v216, v234, v231
	v_mov_b32_e32 v217, v159
	v_lshl_add_u64 v[216:217], v[216:217], 2, s[88:89]
	global_load_dwordx4 v[216:219], v[216:217], off
	v_add_u32_e32 v240, 0x40000, v194
	v_mov_b32_e32 v241, v159
	v_lshl_add_u64 v[240:241], v[240:241], 2, s[90:91]
	s_waitcnt vmcnt(0)
;     template <bool LN, int BJ, int LO, int HI> DI void batch(const f32x4 (&acc)[2][2][4][2], unsigned row0, unsigned col0, const f32x4 (&gv)[2], const f32x4 (&bv)[2]) const {
;         f32x4 r[HI - LO]; float mean[(HI - LO) / 2], rstd[(HI - LO) / 2];
; #pragma unroll
;         for (int i = LO; i < HI; ++i) { const int ai = i >> 3, m = (i >> 1) & 3, n = i & 1; const unsigned row = row0 + ai * HALF + m * 16;
;             if (n == 0) { mean[(i - LO) >> 1] = 0.f; rstd[(i - LO) >> 1] = 1.f;
;                 if (LN) { const float2 st = *(const float2*)(stats + row * 2u); mean[(i - LO) >> 1] = st.x; rstd[(i - LO) >> 1] = st.y; } }
;             r[i - LO] = *(const f32x4*)(src + (row * (unsigned)DM + col0 + BJ * HALF + n * 16)); }
; #pragma unroll
;         for (int i = LO; i < HI; ++i) { const int ai = i >> 3, m = (i >> 1) & 3, n = i & 1; const unsigned row = row0 + ai * HALF + m * 16;
;             *(f32x4*)(Y + (row * (unsigned)DM + col0 + BJ * HALF + n * 16)) = acc[ai][BJ][m][n] + ((r[i - LO] - mean[(i - LO) >> 1]) * rstd[(i - LO) >> 1]) * gv[n] + bv[n]; }
;         __builtin_amdgcn_sched_barrier(0);
;     }
;     template <bool LN> DI void run(const f32x4 (&acc)[2][2][4][2], const Unit& u, int wr, int wc, int fr, int fq) const {
;     ...
;         load_gb<LN, 0>(col0, gv, bv);
;         batch<LN, 0, 0, 4>(acc, row0, col0, gv, bv);
;         batch<LN, 0, 4, 8>(acc, row0, col0, gv, bv);
;         batch<LN, 0, 8, 12>(acc, row0, col0, gv, bv);
;         batch<LN, 0, 12, 16>(acc, row0, col0, gv, bv);
;         load_gb<LN, 1>(col0, gv, bv);
;         batch<LN, 1, 0, 8>(acc, row0, col0, gv, bv);
	v_sub_f32_e32 v137, v137, v204
	v_sub_f32_e32 v136, v136, v204
	v_sub_f32_e32 v139, v139, v204
	v_sub_f32_e32 v138, v138, v204
	v_pk_mul_f32 v[138:139], v[204:205], v[138:139] op_sel:[1,0]
	v_pk_mul_f32 v[136:137], v[204:205], v[136:137] op_sel:[1,0]
	v_pk_fma_f32 v[138:139], v[152:153], v[138:139], v[94:95]
	v_pk_fma_f32 v[136:137], v[154:155], v[136:137], v[92:93]
	v_pk_fma_f32 v[138:139], v[134:135], s[78:79], v[138:139] op_sel_hi:[1,0,1]
	v_pk_fma_f32 v[136:137], v[132:133], s[78:79], v[136:137] op_sel_hi:[1,0,1]
	global_store_dwordx4 v[240:241], v[136:139], off
	s_nop 1
	v_sub_f32_e32 v137, v209, v204
	v_sub_f32_e32 v136, v208, v204
	v_sub_f32_e32 v139, v211, v204
	v_sub_f32_e32 v138, v210, v204
	v_pk_mul_f32 v[138:139], v[204:205], v[138:139] op_sel:[1,0]
	v_pk_mul_f32 v[136:137], v[204:205], v[136:137] op_sel:[1,0]
	v_pk_fma_f32 v[138:139], v[148:149], v[138:139], v[90:91]
	v_pk_fma_f32 v[136:137], v[150:151], v[136:137], v[88:89]
	v_add_u32_e32 v204, 0x40010, v194
	v_mov_b32_e32 v205, v159
	v_pk_fma_f32 v[138:139], v[130:131], s[78:79], v[138:139] op_sel_hi:[1,0,1]
	v_pk_fma_f32 v[136:137], v[128:129], s[78:79], v[136:137] op_sel_hi:[1,0,1]
	v_lshl_add_u64 v[204:205], v[204:205], 2, s[90:91]
	global_store_dwordx4 v[204:205], v[136:139], off
	v_add_u32_e32 v204, 0x48000, v194
	v_mov_b32_e32 v205, v159
	v_sub_f32_e32 v137, v213, v238
	v_sub_f32_e32 v136, v212, v238
	v_sub_f32_e32 v139, v215, v238
	v_sub_f32_e32 v138, v214, v238
	v_pk_mul_f32 v[138:139], v[238:239], v[138:139] op_sel:[1,0]
	v_pk_mul_f32 v[136:137], v[238:239], v[136:137] op_sel:[1,0]
	v_pk_fma_f32 v[138:139], v[152:153], v[138:139], v[86:87]
	v_pk_fma_f32 v[136:137], v[154:155], v[136:137], v[84:85]
	v_pk_fma_f32 v[138:139], v[134:135], s[78:79], v[138:139] op_sel_hi:[1,0,1]
	v_pk_fma_f32 v[136:137], v[132:133], s[78:79], v[136:137] op_sel_hi:[1,0,1]
	v_lshl_add_u64 v[204:205], v[204:205], 2, s[90:91]
	global_store_dwordx4 v[204:205], v[136:139], off
	v_add_u32_e32 v204, 0x48010, v194
	v_mov_b32_e32 v205, v159
	v_sub_f32_e32 v137, v217, v238
	v_sub_f32_e32 v136, v216, v238
	v_sub_f32_e32 v139, v219, v238
	v_sub_f32_e32 v138, v218, v238
	v_pk_mul_f32 v[138:139], v[238:239], v[138:139] op_sel:[1,0]
	v_pk_mul_f32 v[136:137], v[238:239], v[136:137] op_sel:[1,0]
	v_pk_fma_f32 v[138:139], v[148:149], v[138:139], v[82:83]
	v_pk_fma_f32 v[136:137], v[150:151], v[136:137], v[80:81]
	v_pk_fma_f32 v[138:139], v[130:131], s[78:79], v[138:139] op_sel_hi:[1,0,1]
	v_pk_fma_f32 v[136:137], v[128:129], s[78:79], v[136:137] op_sel_hi:[1,0,1]
	v_lshl_add_u64 v[204:205], v[204:205], 2, s[90:91]
	global_store_dwordx4 v[204:205], v[136:139], off
	s_nop 1
	v_add_u32_e32 v138, 0xa0, v206
	v_lshlrev_b32_e32 v136, 1, v138
	v_mov_b32_e32 v137, v159
	v_lshlrev_b32_e32 v237, 11, v138
	v_lshl_add_u64 v[204:205], v[136:137], 2, s[2:3]
	v_add_u32_e32 v136, v237, v158
	v_lshl_add_u64 v[136:137], v[136:137], 2, s[88:89]
	global_load_dwordx2 v[240:241], v[204:205], off
	v_add_u32_e32 v208, v237, v231
	global_load_dwordx4 v[136:139], v[136:137], off
	v_mov_b32_e32 v209, v159
	v_lshl_add_u64 v[208:209], v[208:209], 2, s[88:89]
	global_load_dwordx4 v[212:215], v[208:209], off
	v_add_u32_e32 v208, 0xb0, v206
	v_lshlrev_b32_e32 v206, 1, v208
	v_mov_b32_e32 v207, v159
	v_lshlrev_b32_e32 v238, 11, v208
	v_lshl_add_u64 v[210:211], v[206:207], 2, s[2:3]
	v_add_u32_e32 v206, v238, v158
	v_lshl_add_u64 v[206:207], v[206:207], 2, s[88:89]
	global_load_dwordx2 v[242:243], v[210:211], off
	v_add_u32_e32 v216, v238, v231
	global_load_dwordx4 v[206:209], v[206:207], off
	v_mov_b32_e32 v217, v159
	v_lshl_add_u64 v[216:217], v[216:217], 2, s[88:89]
	global_load_dwordx4 v[216:219], v[216:217], off
	v_add_u32_e32 v244, 0x50000, v194
	v_mov_b32_e32 v245, v159
	v_lshl_add_u64 v[244:245], v[244:245], 2, s[90:91]
	s_waitcnt vmcnt(0)
	v_sub_f32_e32 v137, v137, v240
	v_sub_f32_e32 v136, v136, v240
	v_sub_f32_e32 v139, v139, v240
	v_sub_f32_e32 v138, v138, v240
	v_pk_mul_f32 v[138:139], v[240:241], v[138:139] op_sel:[1,0]
	v_pk_mul_f32 v[136:137], v[240:241], v[136:137] op_sel:[1,0]
	v_pk_fma_f32 v[138:139], v[152:153], v[138:139], v[78:79]
	v_pk_fma_f32 v[136:137], v[154:155], v[136:137], v[76:77]
	v_pk_fma_f32 v[138:139], v[134:135], s[78:79], v[138:139] op_sel_hi:[1,0,1]
	v_pk_fma_f32 v[136:137], v[132:133], s[78:79], v[136:137] op_sel_hi:[1,0,1]
	global_store_dwordx4 v[244:245], v[136:139], off
	s_nop 1
	v_sub_f32_e32 v137, v213, v240
	v_sub_f32_e32 v136, v212, v240
	v_sub_f32_e32 v139, v215, v240
	v_sub_f32_e32 v138, v214, v240
	v_pk_mul_f32 v[138:139], v[240:241], v[138:139] op_sel:[1,0]
	v_pk_mul_f32 v[136:137], v[240:241], v[136:137] op_sel:[1,0]
	v_pk_fma_f32 v[138:139], v[148:149], v[138:139], v[74:75]
	v_pk_fma_f32 v[136:137], v[150:151], v[136:137], v[72:73]
	v_add_u32_e32 v212, 0x50010, v194
	v_mov_b32_e32 v213, v159
	v_pk_fma_f32 v[138:139], v[130:131], s[78:79], v[138:139] op_sel_hi:[1,0,1]
	v_pk_fma_f32 v[136:137], v[128:129], s[78:79], v[136:137] op_sel_hi:[1,0,1]
	v_lshl_add_u64 v[212:213], v[212:213], 2, s[90:91]
	global_store_dwordx4 v[212:213], v[136:139], off
	s_nop 1
	v_sub_f32_e32 v137, v207, v242
	v_sub_f32_e32 v136, v206, v242
	v_sub_f32_e32 v139, v209, v242
	v_sub_f32_e32 v138, v208, v242
	v_pk_mul_f32 v[136:137], v[242:243], v[136:137] op_sel:[1,0]
	v_pk_mul_f32 v[138:139], v[242:243], v[138:139] op_sel:[1,0]
	v_pk_fma_f32 v[136:137], v[154:155], v[136:137], v[68:69]
	v_pk_fma_f32 v[138:139], v[152:153], v[138:139], v[70:71]
	v_pk_fma_f32 v[132:133], v[132:133], s[78:79], v[136:137] op_sel_hi:[1,0,1]
	v_add_u32_e32 v136, 0x58000, v194
	v_mov_b32_e32 v137, v159
	v_pk_fma_f32 v[134:135], v[134:135], s[78:79], v[138:139] op_sel_hi:[1,0,1]
	v_lshl_add_u64 v[136:137], v[136:137], 2, s[90:91]
	global_store_dwordx4 v[136:137], v[132:135], off
	s_nop 1
	v_sub_f32_e32 v133, v217, v242
	v_sub_f32_e32 v132, v216, v242
	v_sub_f32_e32 v135, v219, v242
	v_sub_f32_e32 v134, v218, v242
	v_pk_mul_f32 v[132:133], v[242:243], v[132:133] op_sel:[1,0]
	v_pk_mul_f32 v[134:135], v[242:243], v[134:135] op_sel:[1,0]
	v_pk_fma_f32 v[132:133], v[150:151], v[132:133], v[64:65]
	v_pk_fma_f32 v[134:135], v[148:149], v[134:135], v[66:67]
	v_pk_fma_f32 v[128:129], v[128:129], s[78:79], v[132:133] op_sel_hi:[1,0,1]
	v_add_u32_e32 v132, 0x58010, v194
	v_mov_b32_e32 v133, v159
	v_pk_fma_f32 v[130:131], v[130:131], s[78:79], v[134:135] op_sel_hi:[1,0,1]
	v_lshl_add_u64 v[132:133], v[132:133], 2, s[90:91]
	global_store_dwordx4 v[132:133], v[128:131], off
	global_load_dwordx4 v[128:131], v[140:141], off offset:512
	v_add_u32_e32 v136, v232, v230
	v_mov_b32_e32 v137, v159
	v_lshl_add_u64 v[136:137], v[136:137], 2, s[88:89]
	s_waitcnt vmcnt(0)
;     template <bool LN, int BJ, int LO, int HI> DI void batch(const f32x4 (&acc)[2][2][4][2], unsigned row0, unsigned col0, const f32x4 (&gv)[2], const f32x4 (&bv)[2]) const {
;         f32x4 r[HI - LO]; float mean[(HI - LO) / 2], rstd[(HI - LO) / 2];
; #pragma unroll
;         for (int i = LO; i < HI; ++i) { const int ai = i >> 3, m = (i >> 1) & 3, n = i & 1; const unsigned row = row0 + ai * HALF + m * 16;
;             if (n == 0) { mean[(i - LO) >> 1] = 0.f; rstd[(i - LO) >> 1] = 1.f;
;                 if (LN) { const float2 st = *(const float2*)(stats + row * 2u); mean[(i - LO) >> 1] = st.x; rstd[(i - LO) >> 1] = st.y; } }
;             r[i - LO] = *(const f32x4*)(src + (row * (unsigned)DM + col0 + BJ * HALF + n * 16)); }
; #pragma unroll
;         for (int i = LO; i < HI; ++i) { const int ai = i >> 3, m = (i >> 1) & 3, n = i & 1; const unsigned row = row0 + ai * HALF + m * 16;
;             *(f32x4*)(Y + (row * (unsigned)DM + col0 + BJ * HALF + n * 16)) = acc[ai][BJ][m][n] + ((r[i - LO] - mean[(i - LO) >> 1]) * rstd[(i - LO) >> 1]) * gv[n] + bv[n]; }
;         __builtin_amdgcn_sched_barrier(0);
;     }
;     template <bool LN, int BJ> DI void load_gb(unsigned col0, f32x4 (&gv)[2], f32x4 (&bv)[2]) const {
; #pragma unroll
;         for (int n = 0; n < 2; ++n) {
;             if (LN) { gv[n] = *(const f32x4*)(gam + col0 + BJ * HALF + n * 16) * ALPHA; bv[n] = *(const f32x4*)(bet + col0 + BJ * HALF + n * 16) * ALPHA; }
;             else { gv[n] = (f32x4){ALPHA, ALPHA, ALPHA, ALPHA}; bv[n] = (f32x4){0.f, 0.f, 0.f, 0.f}; }
;         }
;     }
	v_pk_mul_f32 v[212:213], v[130:131], s[78:79] op_sel_hi:[1,0]
	v_pk_mul_f32 v[214:215], v[128:129], s[78:79] op_sel_hi:[1,0]
	global_load_dwordx4 v[132:135], v[142:143], off offset:512
	global_load_dwordx4 v[128:131], v[140:141], off offset:576
	s_waitcnt vmcnt(0)
	v_pk_mul_f32 v[206:207], v[130:131], s[78:79] op_sel_hi:[1,0]
	v_pk_mul_f32 v[208:209], v[128:129], s[78:79] op_sel_hi:[1,0]
	global_load_dwordx4 v[128:131], v[142:143], off offset:576
	global_load_dwordx2 v[220:221], v[144:145], off
	global_load_dwordx4 v[240:243], v[136:137], off
	v_add_u32_e32 v136, v232, v229
	v_mov_b32_e32 v137, v159
	v_lshl_add_u64 v[136:137], v[136:137], 2, s[88:89]
	global_load_dwordx4 v[244:247], v[136:137], off
	global_load_dwordx2 v[218:219], v[146:147], off
	v_add_u32_e32 v136, v195, v230
	v_mov_b32_e32 v137, v159
	v_lshl_add_u64 v[136:137], v[136:137], 2, s[88:89]
	global_load_dwordx4 v[248:251], v[136:137], off
	v_add_u32_e32 v136, v195, v229
	v_mov_b32_e32 v137, v159
	v_lshl_add_u64 v[136:137], v[136:137], 2, s[88:89]
	global_load_dwordx4 v[152:155], v[136:137], off
	global_load_dwordx2 v[216:217], v[200:201], off
	v_add_u32_e32 v136, v236, v230
	v_mov_b32_e32 v137, v159
	v_lshl_add_u64 v[136:137], v[136:137], 2, s[88:89]
	global_load_dwordx4 v[148:151], v[136:137], off
	v_add_u32_e32 v136, v236, v229
	v_mov_b32_e32 v137, v159
	v_lshl_add_u64 v[136:137], v[136:137], 2, s[88:89]
	global_load_dwordx4 v[144:147], v[136:137], off
	global_load_dwordx2 v[200:201], v[202:203], off
	v_add_u32_e32 v136, v235, v230
	v_mov_b32_e32 v137, v159
	v_lshl_add_u64 v[136:137], v[136:137], 2, s[88:89]
	global_load_dwordx4 v[140:143], v[136:137], off
	v_add_u32_e32 v136, v235, v229
	v_mov_b32_e32 v137, v159
	v_lshl_add_u64 v[136:137], v[136:137], 2, s[88:89]
	global_load_dwordx4 v[136:139], v[136:137], off
	v_add_u32_e32 v202, 0x80, v194
	v_mov_b32_e32 v203, v159
	v_lshl_add_u64 v[202:203], v[202:203], 2, s[90:91]
	s_waitcnt vmcnt(0)
	v_sub_f32_e32 v241, v241, v220
	v_sub_f32_e32 v240, v240, v220
	v_sub_f32_e32 v243, v243, v220
	v_sub_f32_e32 v242, v242, v220
	v_pk_mul_f32 v[242:243], v[220:221], v[242:243] op_sel:[1,0]
	v_pk_mul_f32 v[240:241], v[220:221], v[240:241] op_sel:[1,0]
	v_pk_fma_f32 v[242:243], v[212:213], v[242:243], v[62:63]
	v_pk_fma_f32 v[240:241], v[214:215], v[240:241], v[60:61]
	v_pk_fma_f32 v[242:243], v[134:135], s[78:79], v[242:243] op_sel_hi:[1,0,1]
	v_pk_fma_f32 v[240:241], v[132:133], s[78:79], v[240:241] op_sel_hi:[1,0,1]
	global_store_dwordx4 v[202:203], v[240:243], off
	v_sub_f32_e32 v203, v245, v220
	v_sub_f32_e32 v202, v244, v220
	v_sub_f32_e32 v241, v247, v220
	v_sub_f32_e32 v240, v246, v220
	v_pk_mul_f32 v[202:203], v[220:221], v[202:203] op_sel:[1,0]
	v_pk_mul_f32 v[240:241], v[220:221], v[240:241] op_sel:[1,0]
	v_pk_fma_f32 v[202:203], v[208:209], v[202:203], v[56:57]
	v_pk_fma_f32 v[220:221], v[206:207], v[240:241], v[58:59]
	v_pk_fma_f32 v[240:241], v[128:129], s[78:79], v[202:203] op_sel_hi:[1,0,1]
	v_add_u32_e32 v202, 0x90, v194
	v_mov_b32_e32 v203, v159
	v_pk_fma_f32 v[242:243], v[130:131], s[78:79], v[220:221] op_sel_hi:[1,0,1]
	v_lshl_add_u64 v[202:203], v[202:203], 2, s[90:91]
	global_store_dwordx4 v[202:203], v[240:243], off
	v_sub_f32_e32 v203, v249, v218
	v_sub_f32_e32 v202, v248, v218
	v_sub_f32_e32 v221, v251, v218
	v_sub_f32_e32 v220, v250, v218
	v_pk_mul_f32 v[202:203], v[218:219], v[202:203] op_sel:[1,0]
	v_pk_mul_f32 v[220:221], v[218:219], v[220:221] op_sel:[1,0]
	v_pk_fma_f32 v[202:203], v[214:215], v[202:203], v[52:53]
	v_pk_fma_f32 v[220:221], v[212:213], v[220:221], v[54:55]
	v_pk_fma_f32 v[240:241], v[132:133], s[78:79], v[202:203] op_sel_hi:[1,0,1]
	v_add_u32_e32 v202, 0x8080, v194
	v_mov_b32_e32 v203, v159
	v_sub_f32_e32 v153, v153, v218
	v_sub_f32_e32 v152, v152, v218
	v_sub_f32_e32 v155, v155, v218
	v_sub_f32_e32 v154, v154, v218
	v_pk_fma_f32 v[242:243], v[134:135], s[78:79], v[220:221] op_sel_hi:[1,0,1]
	v_lshl_add_u64 v[202:203], v[202:203], 2, s[90:91]
	v_pk_mul_f32 v[154:155], v[218:219], v[154:155] op_sel:[1,0]
	v_pk_mul_f32 v[152:153], v[218:219], v[152:153] op_sel:[1,0]
	global_store_dwordx4 v[202:203], v[240:243], off
	v_pk_fma_f32 v[152:153], v[208:209], v[152:153], v[48:49]
	v_pk_fma_f32 v[154:155], v[206:207], v[154:155], v[50:51]
	v_add_u32_e32 v202, 0x8090, v194
	v_mov_b32_e32 v203, v159
	v_sub_f32_e32 v149, v149, v216
	v_sub_f32_e32 v148, v148, v216
	v_sub_f32_e32 v151, v151, v216
	v_sub_f32_e32 v150, v150, v216
	v_pk_fma_f32 v[154:155], v[130:131], s[78:79], v[154:155] op_sel_hi:[1,0,1]
	v_pk_fma_f32 v[152:153], v[128:129], s[78:79], v[152:153] op_sel_hi:[1,0,1]
	v_lshl_add_u64 v[202:203], v[202:203], 2, s[90:91]
	v_pk_mul_f32 v[150:151], v[216:217], v[150:151] op_sel:[1,0]
	v_pk_mul_f32 v[148:149], v[216:217], v[148:149] op_sel:[1,0]
	global_store_dwordx4 v[202:203], v[152:155], off
	v_pk_fma_f32 v[148:149], v[214:215], v[148:149], v[44:45]
	v_pk_fma_f32 v[150:151], v[212:213], v[150:151], v[46:47]
	v_add_u32_e32 v152, 0x10080, v194
	v_mov_b32_e32 v153, v159
	v_sub_f32_e32 v145, v145, v216
	v_sub_f32_e32 v144, v144, v216
	v_sub_f32_e32 v147, v147, v216
	v_sub_f32_e32 v146, v146, v216
	v_pk_fma_f32 v[150:151], v[134:135], s[78:79], v[150:151] op_sel_hi:[1,0,1]
	v_pk_fma_f32 v[148:149], v[132:133], s[78:79], v[148:149] op_sel_hi:[1,0,1]
	v_lshl_add_u64 v[152:153], v[152:153], 2, s[90:91]
	v_pk_mul_f32 v[146:147], v[216:217], v[146:147] op_sel:[1,0]
	v_pk_mul_f32 v[144:145], v[216:217], v[144:145] op_sel:[1,0]
	global_store_dwordx4 v[152:153], v[148:151], off
	v_pk_fma_f32 v[144:145], v[208:209], v[144:145], v[40:41]
	v_pk_fma_f32 v[146:147], v[206:207], v[146:147], v[42:43]
;     template <bool LN, int BJ, int LO, int HI> DI void batch(const f32x4 (&acc)[2][2][4][2], unsigned row0, unsigned col0, const f32x4 (&gv)[2], const f32x4 (&bv)[2]) const {
;         f32x4 r[HI - LO]; float mean[(HI - LO) / 2], rstd[(HI - LO) / 2];
; #pragma unroll
;         for (int i = LO; i < HI; ++i) { const int ai = i >> 3, m = (i >> 1) & 3, n = i & 1; const unsigned row = row0 + ai * HALF + m * 16;
;             if (n == 0) { mean[(i - LO) >> 1] = 0.f; rstd[(i - LO) >> 1] = 1.f;
;                 if (LN) { const float2 st = *(const float2*)(stats + row * 2u); mean[(i - LO) >> 1] = st.x; rstd[(i - LO) >> 1] = st.y; } }
;             r[i - LO] = *(const f32x4*)(src + (row * (unsigned)DM + col0 + BJ * HALF + n * 16)); }
; #pragma unroll
;         for (int i = LO; i < HI; ++i) { const int ai = i >> 3, m = (i >> 1) & 3, n = i & 1; const unsigned row = row0 + ai * HALF + m * 16;
;             *(f32x4*)(Y + (row * (unsigned)DM + col0 + BJ * HALF + n * 16)) = acc[ai][BJ][m][n] + ((r[i - LO] - mean[(i - LO) >> 1]) * rstd[(i - LO) >> 1]) * gv[n] + bv[n]; }
;         __builtin_amdgcn_sched_barrier(0);
;     }
	v_add_u32_e32 v148, 0x10090, v194
	v_mov_b32_e32 v149, v159
	v_sub_f32_e32 v141, v141, v200
	v_sub_f32_e32 v140, v140, v200
	v_sub_f32_e32 v143, v143, v200
	v_sub_f32_e32 v142, v142, v200
	v_pk_fma_f32 v[146:147], v[130:131], s[78:79], v[146:147] op_sel_hi:[1,0,1]
	v_pk_fma_f32 v[144:145], v[128:129], s[78:79], v[144:145] op_sel_hi:[1,0,1]
	v_lshl_add_u64 v[148:149], v[148:149], 2, s[90:91]
	v_pk_mul_f32 v[142:143], v[200:201], v[142:143] op_sel:[1,0]
	v_pk_mul_f32 v[140:141], v[200:201], v[140:141] op_sel:[1,0]
	global_store_dwordx4 v[148:149], v[144:147], off
	v_pk_fma_f32 v[140:141], v[214:215], v[140:141], v[36:37]
	v_pk_fma_f32 v[142:143], v[212:213], v[142:143], v[38:39]
	v_add_u32_e32 v144, 0x18080, v194
	v_mov_b32_e32 v145, v159
	v_sub_f32_e32 v137, v137, v200
	v_sub_f32_e32 v136, v136, v200
	v_sub_f32_e32 v139, v139, v200
	v_sub_f32_e32 v138, v138, v200
	v_pk_fma_f32 v[142:143], v[134:135], s[78:79], v[142:143] op_sel_hi:[1,0,1]
	v_pk_fma_f32 v[140:141], v[132:133], s[78:79], v[140:141] op_sel_hi:[1,0,1]
	v_lshl_add_u64 v[144:145], v[144:145], 2, s[90:91]
	v_pk_mul_f32 v[138:139], v[200:201], v[138:139] op_sel:[1,0]
	v_pk_mul_f32 v[136:137], v[200:201], v[136:137] op_sel:[1,0]
	global_store_dwordx4 v[144:145], v[140:143], off
	v_pk_fma_f32 v[136:137], v[208:209], v[136:137], v[32:33]
	v_pk_fma_f32 v[138:139], v[206:207], v[138:139], v[34:35]
	v_add_u32_e32 v140, 0x18090, v194
	v_mov_b32_e32 v141, v159
	v_pk_fma_f32 v[138:139], v[130:131], s[78:79], v[138:139] op_sel_hi:[1,0,1]
	v_pk_fma_f32 v[136:137], v[128:129], s[78:79], v[136:137] op_sel_hi:[1,0,1]
	v_lshl_add_u64 v[140:141], v[140:141], 2, s[90:91]
	global_store_dwordx4 v[140:141], v[136:139], off
	s_nop 1
	v_add_u32_e32 v136, v233, v230
	v_mov_b32_e32 v137, v159
	v_lshl_add_u64 v[136:137], v[136:137], 2, s[88:89]
	global_load_dwordx2 v[220:221], v[196:197], off
	global_load_dwordx4 v[216:219], v[136:137], off
	v_add_u32_e32 v136, v233, v229
	v_mov_b32_e32 v137, v159
	v_lshl_add_u64 v[136:137], v[136:137], 2, s[88:89]
	global_load_dwordx4 v[240:243], v[136:137], off
	global_load_dwordx2 v[200:201], v[198:199], off
	v_add_u32_e32 v136, v234, v230
	v_mov_b32_e32 v137, v159
	v_lshl_add_u64 v[136:137], v[136:137], 2, s[88:89]
	global_load_dwordx4 v[244:247], v[136:137], off
	v_add_u32_e32 v136, v234, v229
	v_mov_b32_e32 v137, v159
	v_lshl_add_u64 v[136:137], v[136:137], 2, s[88:89]
	global_load_dwordx4 v[152:155], v[136:137], off
	global_load_dwordx2 v[198:199], v[204:205], off
	v_add_u32_e32 v136, v237, v230
	v_mov_b32_e32 v137, v159
	v_lshl_add_u64 v[136:137], v[136:137], 2, s[88:89]
	global_load_dwordx4 v[148:151], v[136:137], off
	v_add_u32_e32 v136, v237, v229
	v_mov_b32_e32 v137, v159
	v_lshl_add_u64 v[136:137], v[136:137], 2, s[88:89]
	global_load_dwordx4 v[144:147], v[136:137], off
	global_load_dwordx2 v[196:197], v[210:211], off
	v_add_u32_e32 v136, v238, v230
	v_mov_b32_e32 v137, v159
	v_lshl_add_u64 v[136:137], v[136:137], 2, s[88:89]
	global_load_dwordx4 v[140:143], v[136:137], off
	v_add_u32_e32 v136, v238, v229
	v_mov_b32_e32 v137, v159
	v_lshl_add_u64 v[136:137], v[136:137], 2, s[88:89]
	global_load_dwordx4 v[136:139], v[136:137], off
	v_add_u32_e32 v210, 0x40080, v194
	v_mov_b32_e32 v211, v159
	v_lshl_add_u64 v[210:211], v[210:211], 2, s[90:91]
	s_waitcnt vmcnt(0)
;     template <bool LN, int BJ, int LO, int HI> DI void batch(const f32x4 (&acc)[2][2][4][2], unsigned row0, unsigned col0, const f32x4 (&gv)[2], const f32x4 (&bv)[2]) const {
;         f32x4 r[HI - LO]; float mean[(HI - LO) / 2], rstd[(HI - LO) / 2];
; #pragma unroll
;         for (int i = LO; i < HI; ++i) { const int ai = i >> 3, m = (i >> 1) & 3, n = i & 1; const unsigned row = row0 + ai * HALF + m * 16;
;             if (n == 0) { mean[(i - LO) >> 1] = 0.f; rstd[(i - LO) >> 1] = 1.f;
;                 if (LN) { const float2 st = *(const float2*)(stats + row * 2u); mean[(i - LO) >> 1] = st.x; rstd[(i - LO) >> 1] = st.y; } }
;             r[i - LO] = *(const f32x4*)(src + (row * (unsigned)DM + col0 + BJ * HALF + n * 16)); }
; #pragma unroll
;         for (int i = LO; i < HI; ++i) { const int ai = i >> 3, m = (i >> 1) & 3, n = i & 1; const unsigned row = row0 + ai * HALF + m * 16;
;             *(f32x4*)(Y + (row * (unsigned)DM + col0 + BJ * HALF + n * 16)) = acc[ai][BJ][m][n] + ((r[i - LO] - mean[(i - LO) >> 1]) * rstd[(i - LO) >> 1]) * gv[n] + bv[n]; }
;         __builtin_amdgcn_sched_barrier(0);
;     }
	v_sub_f32_e32 v203, v217, v220
	v_sub_f32_e32 v202, v216, v220
	v_sub_f32_e32 v205, v219, v220
	v_sub_f32_e32 v204, v218, v220
	v_pk_mul_f32 v[204:205], v[220:221], v[204:205] op_sel:[1,0]
	v_pk_mul_f32 v[202:203], v[220:221], v[202:203] op_sel:[1,0]
	v_pk_fma_f32 v[204:205], v[212:213], v[204:205], v[30:31]
	v_pk_fma_f32 v[202:203], v[214:215], v[202:203], v[28:29]
	v_pk_fma_f32 v[204:205], v[134:135], s[78:79], v[204:205] op_sel_hi:[1,0,1]
	v_pk_fma_f32 v[202:203], v[132:133], s[78:79], v[202:203] op_sel_hi:[1,0,1]
	global_store_dwordx4 v[210:211], v[202:205], off
	v_add_u32_e32 v210, 0x40090, v194
	v_mov_b32_e32 v211, v159
	v_sub_f32_e32 v203, v241, v220
	v_sub_f32_e32 v202, v240, v220
	v_sub_f32_e32 v205, v243, v220
	v_sub_f32_e32 v204, v242, v220
	v_pk_mul_f32 v[204:205], v[220:221], v[204:205] op_sel:[1,0]
	v_pk_mul_f32 v[202:203], v[220:221], v[202:203] op_sel:[1,0]
	v_pk_fma_f32 v[204:205], v[206:207], v[204:205], v[26:27]
	v_pk_fma_f32 v[202:203], v[208:209], v[202:203], v[24:25]
	v_pk_fma_f32 v[204:205], v[130:131], s[78:79], v[204:205] op_sel_hi:[1,0,1]
	v_pk_fma_f32 v[202:203], v[128:129], s[78:79], v[202:203] op_sel_hi:[1,0,1]
	v_lshl_add_u64 v[210:211], v[210:211], 2, s[90:91]
	global_store_dwordx4 v[210:211], v[202:205], off
	v_sub_f32_e32 v149, v149, v198
	v_sub_f32_e32 v148, v148, v198
	v_sub_f32_e32 v203, v245, v200
	v_sub_f32_e32 v202, v244, v200
	v_sub_f32_e32 v141, v141, v196
	v_sub_f32_e32 v140, v140, v196
	v_sub_f32_e32 v205, v247, v200
	v_sub_f32_e32 v204, v246, v200
	v_pk_mul_f32 v[202:203], v[200:201], v[202:203] op_sel:[1,0]
	v_sub_f32_e32 v151, v151, v198
	v_sub_f32_e32 v150, v150, v198
	v_pk_mul_f32 v[148:149], v[198:199], v[148:149] op_sel:[1,0]
	v_sub_f32_e32 v143, v143, v196
	v_sub_f32_e32 v142, v142, v196
	v_pk_mul_f32 v[140:141], v[196:197], v[140:141] op_sel:[1,0]
	v_pk_mul_f32 v[204:205], v[200:201], v[204:205] op_sel:[1,0]
	v_pk_fma_f32 v[202:203], v[214:215], v[202:203], v[20:21]
	v_sub_f32_e32 v153, v153, v200
	v_sub_f32_e32 v152, v152, v200
	v_sub_f32_e32 v155, v155, v200
	v_sub_f32_e32 v154, v154, v200
	v_pk_mul_f32 v[150:151], v[198:199], v[150:151] op_sel:[1,0]
	v_pk_fma_f32 v[148:149], v[214:215], v[148:149], v[12:13]
	v_pk_mul_f32 v[142:143], v[196:197], v[142:143] op_sel:[1,0]
	v_pk_fma_f32 v[140:141], v[214:215], v[140:141], v[4:5]
	v_pk_fma_f32 v[204:205], v[212:213], v[204:205], v[22:23]
	v_pk_fma_f32 v[202:203], v[132:133], s[78:79], v[202:203] op_sel_hi:[1,0,1]
	v_pk_mul_f32 v[154:155], v[200:201], v[154:155] op_sel:[1,0]
	v_pk_mul_f32 v[152:153], v[200:201], v[152:153] op_sel:[1,0]
	v_pk_fma_f32 v[150:151], v[212:213], v[150:151], v[14:15]
	v_pk_fma_f32 v[148:149], v[132:133], s[78:79], v[148:149] op_sel_hi:[1,0,1]
	v_pk_fma_f32 v[142:143], v[212:213], v[142:143], v[6:7]
	v_pk_fma_f32 v[132:133], v[132:133], s[78:79], v[140:141] op_sel_hi:[1,0,1]
	v_add_u32_e32 v140, 0x58080, v194
	v_mov_b32_e32 v141, v159
	v_pk_fma_f32 v[204:205], v[134:135], s[78:79], v[204:205] op_sel_hi:[1,0,1]
	v_pk_fma_f32 v[152:153], v[208:209], v[152:153], v[16:17]
	v_pk_fma_f32 v[154:155], v[206:207], v[154:155], v[18:19]
	v_add_u32_e32 v200, 0x48090, v194
	v_mov_b32_e32 v201, v159
	v_pk_fma_f32 v[150:151], v[134:135], s[78:79], v[150:151] op_sel_hi:[1,0,1]
	v_pk_fma_f32 v[134:135], v[134:135], s[78:79], v[142:143] op_sel_hi:[1,0,1]
	v_lshl_add_u64 v[140:141], v[140:141], 2, s[90:91]
	v_pk_fma_f32 v[154:155], v[130:131], s[78:79], v[154:155] op_sel_hi:[1,0,1]
	v_pk_fma_f32 v[152:153], v[128:129], s[78:79], v[152:153] op_sel_hi:[1,0,1]
	v_lshl_add_u64 v[200:201], v[200:201], 2, s[90:91]
	v_sub_f32_e32 v145, v145, v198
	v_sub_f32_e32 v144, v144, v198
	global_store_dwordx4 v[140:141], v[132:135], off
	global_store_dwordx4 v[200:201], v[152:155], off
	v_sub_f32_e32 v147, v147, v198
	v_sub_f32_e32 v133, v137, v196
	v_sub_f32_e32 v132, v136, v196
	v_add_u32_e32 v152, 0x50080, v194
	v_mov_b32_e32 v153, v159
	v_sub_f32_e32 v146, v146, v198
	v_pk_mul_f32 v[144:145], v[198:199], v[144:145] op_sel:[1,0]
	v_sub_f32_e32 v135, v139, v196
	v_sub_f32_e32 v134, v138, v196
	v_pk_mul_f32 v[132:133], v[196:197], v[132:133] op_sel:[1,0]
	v_lshl_add_u64 v[152:153], v[152:153], 2, s[90:91]
	v_pk_mul_f32 v[146:147], v[198:199], v[146:147] op_sel:[1,0]
	v_pk_fma_f32 v[144:145], v[208:209], v[144:145], v[8:9]
	v_pk_mul_f32 v[134:135], v[196:197], v[134:135] op_sel:[1,0]
	v_pk_fma_f32 v[132:133], v[208:209], v[132:133], v[0:1]
	v_add_u32_e32 v210, 0x48080, v194
	v_mov_b32_e32 v211, v159
	global_store_dwordx4 v[152:153], v[148:151], off
	v_pk_fma_f32 v[146:147], v[206:207], v[146:147], v[10:11]
	v_pk_fma_f32 v[144:145], v[128:129], s[78:79], v[144:145] op_sel_hi:[1,0,1]
	v_add_u32_e32 v148, 0x50090, v194
	v_mov_b32_e32 v149, v159
	v_pk_fma_f32 v[134:135], v[206:207], v[134:135], v[2:3]
	v_pk_fma_f32 v[128:129], v[128:129], s[78:79], v[132:133] op_sel_hi:[1,0,1]
	v_add_u32_e32 v132, 0x58090, v194
	v_mov_b32_e32 v133, v159
	v_lshl_add_u64 v[210:211], v[210:211], 2, s[90:91]
	v_pk_fma_f32 v[146:147], v[130:131], s[78:79], v[146:147] op_sel_hi:[1,0,1]
	v_lshl_add_u64 v[148:149], v[148:149], 2, s[90:91]
	v_pk_fma_f32 v[130:131], v[130:131], s[78:79], v[134:135] op_sel_hi:[1,0,1]
	v_lshl_add_u64 v[132:133], v[132:133], 2, s[90:91]
	global_store_dwordx4 v[210:211], v[202:205], off
	global_store_dwordx4 v[148:149], v[144:147], off
	global_store_dwordx4 v[132:133], v[128:131], off
	s_mov_b64 s[24:25], 0
	s_branch .LBB0_324
